# v66 + HGRN pass-C blocks repartitioned per 32 workgroups as 4x0 / 4x6 / 24x5 wave-tasks so the 32 workgroups that also run a ctx attention unit carry no pass-C block
# baseline (speedup 1.0000x reference)
.LBB0_372:
	s_andn2_b64 vcc, exec, s[2:3]
	s_cbranch_vccnz .LBB0_339
	s_and_b32 s2, s4, 31
	s_lshr_b32 s3, s4, 5
	s_mulk_i32 s3, 0x90
	s_cmp_lt_u32 s2, 8
	s_cbranch_scc0 .Lpc_hi
	s_lshr_b32 s101, s2, 1
	s_mul_i32 s101, s101, 6
	s_add_i32 s101, s101, s3
	s_and_b32 s3, s2, 1
	s_mul_i32 s3, s3, 6
	s_mov_b32 s2, s101
	s_branch .Lpc_done
.Lpc_hi:
	s_mul_i32 s2, s2, 5
	s_add_i32 s2, s2, s3
	s_sub_i32 s2, s2, 16
	s_mov_b32 s3, 5
.Lpc_done:
	v_ashrrev_i32_e32 v0, 6, v205
	v_cmp_gt_i32_e32 vcc, s3, v0
	s_and_saveexec_b64 s[38:39], vcc
	s_cbranch_execz .LBB0_338
	v_add_u32_e32 v0, s2, v0
	s_mov_b32 s2, 0x38e38e39
	v_mul_hi_i32 v2, v0, s2
	v_lshrrev_b32_e32 v3, 31, v2
	v_ashrrev_i32_e32 v2, 3, v2
	v_add_u32_e32 v2, v2, v3
	v_mul_lo_u32 v3, v2, 36
	v_sub_u32_e32 v96, v0, v3
	v_cmp_gt_i32_e64 s[40:41], 4, v96
	s_and_b64 s[2:3], s[18:19], s[40:41]
	v_mov_b32_e32 v1, v236
	s_xor_b64 s[2:3], s[2:3], -1
	s_and_b64 exec, exec, s[2:3]
	s_cbranch_execz .LBB0_338
	v_lshrrev_b32_e32 v0, 6, v1
	s_movk_i32 s2, 0x4d00
	v_mul_lo_u32 v0, v0, s2
	v_add_u32_e32 v92, 16, v0
	v_lshlrev_b32_e32 v0, 6, v2
	v_and_b32_e32 v94, 63, v1
	v_and_b32_e32 v0, 0xc0, v0
	v_or_b32_e32 v3, v94, v0
	v_readlane_b32 s0, v255, 20
	v_lshlrev_b32_e32 v160, 2, v3
	v_readlane_b32 s1, v255, 21
	s_nop 4
	global_load_dword v3, v160, s[0:1]
	global_load_dword v6, v160, s[0:1] offset:2048
	v_lshl_add_u64 v[4:5], s[0:1], 0, v[160:161]
	v_add_co_u32_e32 v4, vcc, 0x1000, v4
	s_mov_b32 s0, 0xf149f2ca
	s_nop 0
	v_addc_co_u32_e32 v5, vcc, 0, v5, vcc
	global_load_dword v8, v[4:5], off
	s_nop 0
	global_load_dword v4, v[4:5], off offset:2048
	v_lshlrev_b32_e32 v148, 1, v2
	v_ashrrev_i32_e32 v97, 31, v96
	v_mov_b32_e32 v99, v161
	v_mov_b32_e32 v101, v161
	v_readlane_b32 s44, v254, 28
	v_readlane_b32 s45, v254, 29
	v_mov_b32_e32 v16, v94
	s_waitcnt vmcnt(2)
	v_max3_f32 v7, v3, s0, v6
	v_readlane_b32 s0, v255, 1
	v_readlane_b32 s1, v255, 2
	s_waitcnt vmcnt(0)
	v_max3_f32 v5, v7, v8, v4
	v_sub_f32_e32 v6, v6, v5
	v_mul_f32_e32 v6, 0x3fb8aa3b, v6
	v_sub_f32_e32 v3, v3, v5
	v_exp_f32_e32 v6, v6
	v_sub_f32_e32 v7, v8, v5
	v_mul_f32_e32 v3, 0x3fb8aa3b, v3
	v_mul_f32_e32 v7, 0x3fb8aa3b, v7
	v_exp_f32_e32 v3, v3
	v_exp_f32_e32 v7, v7
	v_sub_f32_e32 v4, v4, v5
	v_mul_f32_e32 v4, 0x3fb8aa3b, v4
	v_exp_f32_e32 v4, v4
	v_add_f32_e32 v5, 0, v6
	v_cndmask_b32_e64 v5, v5, 0, s[0:1]
	v_readlane_b32 s0, v255, 3
	v_add_f32_e32 v8, v7, v5
	v_readlane_b32 s1, v255, 4
	v_add_f32_e32 v3, 0, v3
	v_add_f32_e32 v3, v6, v3
	v_cndmask_b32_e64 v5, v8, v5, s[0:1]
	v_readlane_b32 s0, v255, 5
	v_add_f32_e32 v8, v4, v5
	v_readlane_b32 s1, v255, 6
	v_add_f32_e32 v3, v7, v3
	v_add_f32_e32 v3, v4, v3
	v_cndmask_b32_e64 v5, v8, v5, s[0:1]
	v_div_scale_f32 v4, s[2:3], v3, v3, v5
	v_rcp_f32_e32 v6, v4
	v_readlane_b32 s0, v255, 22
	v_readlane_b32 s1, v255, 23
	v_fma_f32 v7, -v4, v6, 1.0
	v_fmac_f32_e32 v6, v7, v6
	v_div_scale_f32 v7, vcc, v5, v3, v5
	v_mul_f32_e32 v8, v7, v6
	v_fma_f32 v9, -v4, v8, v7
	v_fmac_f32_e32 v8, v9, v6
	v_fma_f32 v4, -v4, v8, v7
	v_div_fmas_f32 v4, v4, v6, v8
	v_div_fixup_f32 v149, v4, v3, v5
	v_ashrrev_i32_e32 v6, 2, v2
	v_mad_i64_i32 v[2:3], s[2:3], v148, 36, v[96:97]
	v_lshlrev_b64 v[2:3], 13, v[2:3]
	v_lshlrev_b32_e32 v4, 7, v1
	v_lshl_add_u64 v[2:3], s[0:1], 0, v[2:3]
	v_and_b32_e32 v98, 0xf80, v4
	v_lshrrev_b32_e32 v1, 2, v1
	v_lshl_add_u64 v[2:3], v[2:3], 0, v[98:99]
	v_and_b32_e32 v100, 8, v1
	v_lshl_add_u64 v[2:3], v[2:3], 0, v[100:101]
	global_load_dwordx2 v[42:43], v[2:3], off
	global_load_dwordx2 v[36:37], v[2:3], off offset:16
	global_load_dwordx2 v[34:35], v[2:3], off offset:32
	global_load_dwordx2 v[4:5], v[2:3], off offset:48
	s_movk_i32 s0, 0x1000
	v_mov_b32_e32 v1, 0xffffff00
	v_lshl_add_u32 v1, v6, 11, v1
	s_mov_b64 s[2:3], s[44:45]
	v_sub_f32_e32 v80, 1.0, v149
	s_waitcnt vmcnt(1)
	v_lshlrev_b32_e32 v40, 16, v35
	s_waitcnt vmcnt(0)
	v_lshlrev_b32_e32 v44, 16, v4
	v_and_b32_e32 v45, 0xffff0000, v4
	v_add_co_u32_e32 v4, vcc, s0, v2
	v_lshlrev_b32_e32 v46, 16, v5
	v_and_b32_e32 v47, 0xffff0000, v5
	v_addc_co_u32_e32 v5, vcc, 0, v3, vcc
	global_load_dwordx2 v[52:53], v[4:5], off
	global_load_dwordx2 v[50:51], v[4:5], off offset:16
	global_load_dwordx2 v[48:49], v[4:5], off offset:32
	global_load_dwordx2 v[38:39], v[4:5], off offset:48
	global_load_dwordx2 v[60:61], v[2:3], off offset:64
	global_load_dwordx2 v[58:59], v[2:3], off offset:80
	global_load_dwordx2 v[56:57], v[2:3], off offset:96
	global_load_dwordx2 v[54:55], v[2:3], off offset:112
	global_load_dwordx2 v[26:27], v[4:5], off offset:64
	global_load_dwordx2 v[28:29], v[4:5], off offset:80
	global_load_dwordx2 v[30:31], v[4:5], off offset:96
	global_load_dwordx2 v[32:33], v[4:5], off offset:112
	v_mov_b32_e32 v2, 0x4000
	v_lshl_add_u32 v2, v6, 8, v2
	v_cndmask_b32_e64 v1, v1, v2, s[40:41]
	v_lshl_add_u32 v93, v96, 6, v1
	v_and_b32_e32 v41, 0xffff0000, v35
	v_ashrrev_i32_e32 v89, 31, v93
	v_and_b32_e32 v35, 31, v16
	v_ashrrev_i32_e32 v81, 5, v16
	v_mov_b64_e32 v[2:3], s[2:3]
	s_movk_i32 s0, 0x1200
	v_mad_i64_i32 v[2:3], s[4:5], v93, s0, v[2:3]
	v_lshlrev_b32_e32 v90, 1, v0
	v_mov_b32_e32 v91, v161
	v_ashrrev_i32_e32 v17, 31, v16
	v_lshl_add_u64 v[0:1], v[2:3], 0, v[90:91]
	v_lshl_add_u64 v[18:19], v[16:17], 1, v[0:1]
	s_mov_b64 s[0:1], 0xb200000
	v_lshl_add_u64 v[0:1], v[18:19], 0, s[0:1]
	global_load_ushort v15, v[0:1], off offset:3072
	global_load_ushort v66, v[0:1], off offset:2048
	s_mov_b32 s7, 0xb202000
	v_add_co_u32_e32 v2, vcc, s7, v18
	s_mov_b32 s11, 0xb205000
	s_nop 0
	v_addc_co_u32_e32 v3, vcc, 0, v19, vcc
	v_add_co_u32_e32 v4, vcc, s11, v18
	s_mov_b32 s12, 0xb207000
	s_nop 0
	v_addc_co_u32_e32 v5, vcc, 0, v19, vcc
	v_add_co_u32_e32 v6, vcc, s12, v18
	s_mov_b32 s13, 0xb209000
	s_nop 0
	v_addc_co_u32_e32 v7, vcc, 0, v19, vcc
	v_add_co_u32_e32 v8, vcc, s13, v18
	s_mov_b32 s14, 0xb20b000
	s_nop 0
	v_addc_co_u32_e32 v9, vcc, 0, v19, vcc
	v_add_co_u32_e32 v10, vcc, s14, v18
	s_mov_b32 s15, 0xb20e000
	s_nop 0
	v_addc_co_u32_e32 v11, vcc, 0, v19, vcc
	v_add_co_u32_e32 v62, vcc, s15, v18
	s_mov_b32 s18, 0xb210000
	s_nop 0
	v_addc_co_u32_e32 v63, vcc, 0, v19, vcc
	v_add_co_u32_e32 v64, vcc, s18, v18
	s_mov_b32 s19, 0xb212000
	s_nop 0
	v_addc_co_u32_e32 v65, vcc, 0, v19, vcc
	v_add_co_u32_e32 v76, vcc, s19, v18
	s_mov_b32 s21, 0xb214000
	s_nop 0
	v_addc_co_u32_e32 v77, vcc, 0, v19, vcc
	v_add_co_u32_e32 v102, vcc, s21, v18
	s_mov_b32 s30, 0xb217000
	s_nop 0
	v_addc_co_u32_e32 v103, vcc, 0, v19, vcc
	global_load_ushort v88, v[4:5], off offset:1024
	global_load_ushort v95, v[4:5], off
	global_load_ushort v104, v[2:3], off offset:3072
	global_load_ushort v14, v[4:5], off offset:512
	global_load_ushort v13, v[2:3], off offset:3584
	global_load_ushort v12, v[0:1], off offset:2560
	v_add_co_u32_e32 v78, vcc, s30, v18
	s_mov_b32 s9, 0xc1f00000
	s_nop 0
	v_addc_co_u32_e32 v79, vcc, 0, v19, vcc
	s_mov_b32 s31, 0xb219000
	v_add_co_u32_e32 v82, vcc, s31, v18
	s_mov_b32 s34, 0xb21b000
	s_nop 0
	v_addc_co_u32_e32 v83, vcc, 0, v19, vcc
	v_add_co_u32_e32 v20, vcc, s34, v18
	s_mov_b32 s35, 0xb21d000
	s_nop 0
	v_addc_co_u32_e32 v21, vcc, 0, v19, vcc
	v_add_co_u32_e32 v68, vcc, s35, v18
	s_mov_b32 s36, 0xb220000
	s_nop 0
	v_addc_co_u32_e32 v69, vcc, 0, v19, vcc
	v_add_co_u32_e32 v22, vcc, s36, v18
	s_mov_b32 s37, 0xb222000
	s_nop 0
	v_addc_co_u32_e32 v23, vcc, 0, v19, vcc
	v_add_co_u32_e32 v24, vcc, s37, v18
	s_mov_b32 s40, 0xb201000
	s_nop 0
	v_addc_co_u32_e32 v25, vcc, 0, v19, vcc
	s_waitcnt vmcnt(7)
	v_lshlrev_b32_e32 v0, 16, v15
	v_max_f32_e32 v0, v0, v0
	v_med3_f32 v0, v0, s9, v244
	v_mul_f32_e32 v0, 0xbfb8aa3b, v0
	v_exp_f32_e32 v86, v0
	v_add_co_u32_e32 v0, vcc, s40, v18
	s_mov_b32 s41, 0xb203000
	v_add_f32_e32 v2, 1.0, v86
	v_rcp_f32_e32 v118, v2
	v_addc_co_u32_e32 v1, vcc, 0, v19, vcc
	s_waitcnt vmcnt(6)
	v_lshlrev_b32_e32 v4, 16, v66
	v_fma_f32 v5, v80, v118, v149
	v_max_f32_e32 v15, 0xda24260, v5
	v_add_co_u32_e32 v2, vcc, s41, v18
	v_mul_f32_e32 v4, v15, v4
	s_nop 0
	v_addc_co_u32_e32 v3, vcc, 0, v19, vcc
	v_bfe_u32 v5, v4, 16, 1
	s_movk_i32 s10, 0x7fff
	s_mov_b32 s46, 0xb204000
	v_add3_u32 v105, v4, v5, s10
	v_add_co_u32_e32 v4, vcc, s46, v18
	s_mov_b32 s28, 0xb206000
	s_nop 0
	v_addc_co_u32_e32 v5, vcc, 0, v19, vcc
	global_load_ushort v106, v[4:5], off offset:-4096
	global_load_ushort v107, v[4:5], off offset:512
	global_load_ushort v87, v[0:1], off offset:3584
	global_load_ushort v110, v[0:1], off offset:2560
	global_load_ushort v111, v[2:3], off offset:3584
	v_add_co_u32_e32 v2, vcc, s28, v18
	s_mov_b32 s29, 0xb208000
	s_nop 0
	v_addc_co_u32_e32 v3, vcc, 0, v19, vcc
	global_load_ushort v156, v[6:7], off offset:1536
	global_load_ushort v157, v[8:9], off offset:2560
	global_load_ushort v158, v[10:11], off offset:3584
	global_load_ushort v116, v[6:7], off offset:2048
	global_load_ushort v117, v[8:9], off offset:3072
	global_load_ushort v121, v[10:11], off offset:3072
	global_load_ushort v120, v[8:9], off offset:2048
	global_load_ushort v126, v[6:7], off offset:1024
	v_add_co_u32_e32 v6, vcc, s29, v18
	s_mov_b32 s42, 0xb20a000
	s_nop 0
	v_addc_co_u32_e32 v7, vcc, 0, v19, vcc
	v_add_co_u32_e32 v8, vcc, s42, v18
	s_mov_b32 s6, 0xb20c000
	s_nop 0
	v_addc_co_u32_e32 v9, vcc, 0, v19, vcc
	v_add_co_u32_e32 v10, vcc, s6, v18
	s_mov_b32 s49, 0xb20d000
	s_nop 0
	v_addc_co_u32_e32 v11, vcc, 0, v19, vcc
	v_add_co_u32_e32 v66, vcc, s49, v18
	s_mov_b32 s4, 0xb20f000
	s_nop 0
	v_addc_co_u32_e32 v67, vcc, 0, v19, vcc
	v_add_co_u32_e32 v74, vcc, s4, v18
	s_mov_b32 s4, 0xb211000
	s_nop 0
	v_addc_co_u32_e32 v75, vcc, 0, v19, vcc
	v_add_co_u32_e32 v84, vcc, s4, v18
	s_mov_b32 s4, 0xb223000
	s_nop 0
	v_addc_co_u32_e32 v85, vcc, 0, v19, vcc
	global_load_ushort v159, v[62:63], off offset:512
	global_load_ushort v162, v[64:65], off offset:1536
	global_load_ushort v163, v[76:77], off offset:2560
	global_load_ushort v164, v[102:103], off offset:3584
	global_load_ushort v127, v[62:63], off offset:1024
	global_load_ushort v137, v[64:65], off offset:2048
	global_load_ushort v141, v[64:65], off offset:1024
	global_load_ushort v131, v[62:63], off
	v_add_co_u32_e32 v62, vcc, s4, v18
	s_mov_b32 s4, 0xb221000
	s_nop 0
	v_addc_co_u32_e32 v63, vcc, 0, v19, vcc
	v_add_co_u32_e32 v64, vcc, s4, v18
	s_mov_b32 s4, 0xb21f000
	s_nop 0
	v_addc_co_u32_e32 v65, vcc, 0, v19, vcc
	v_add_co_u32_e32 v70, vcc, s4, v18
	s_mov_b32 s97, 0xb21c000
	s_nop 0
	v_addc_co_u32_e32 v71, vcc, 0, v19, vcc
	v_add_co_u32_e32 v72, vcc, s97, v18
	s_mov_b32 s4, 0xb21a000
	s_nop 0
	v_addc_co_u32_e32 v73, vcc, 0, v19, vcc
	v_add_co_u32_e32 v108, vcc, s4, v18
	s_mov_b32 s48, 0xb218000
	s_nop 0
	v_addc_co_u32_e32 v109, vcc, 0, v19, vcc
	v_add_co_u32_e32 v112, vcc, s48, v18
	s_mov_b32 s47, 0xb216000
	s_nop 0
	v_addc_co_u32_e32 v113, vcc, 0, v19, vcc
	v_add_co_u32_e32 v114, vcc, s47, v18
	s_mov_b32 s43, 0xb213000
	s_nop 0
	v_addc_co_u32_e32 v115, vcc, 0, v19, vcc
	v_add_co_u32_e32 v124, vcc, s43, v18
	global_load_ushort v165, v[78:79], off offset:512
	global_load_ushort v166, v[82:83], off offset:1536
	global_load_ushort v167, v[20:21], off offset:2560
	global_load_ushort v168, v[68:69], off offset:3584
	global_load_ushort v169, v[22:23], off offset:512
	global_load_ushort v170, v[24:25], off offset:1536
	global_load_ushort v171, v[22:23], off offset:-4096
	global_load_ushort v172, v[78:79], off offset:-4096
	v_addc_co_u32_e32 v125, vcc, 0, v19, vcc
	global_load_ushort v128, v[66:67], off offset:-4096
	global_load_ushort v129, v[66:67], off offset:512
	global_load_ushort v173, v[112:113], off offset:1024
	s_nop 0
	global_load_ushort v66, v[66:67], off
	s_nop 0
	global_load_ushort v67, v[4:5], off
	s_nop 0
	global_load_ushort v4, v[124:125], off offset:3072
	global_load_ushort v5, v[2:3], off offset:1536
	global_load_ushort v130, v[2:3], off offset:512
	global_load_ushort v136, v[6:7], off offset:1536
	global_load_ushort v174, v[2:3], off offset:1024
	global_load_ushort v175, v[0:1], off offset:3072
	s_waitcnt vmcnt(37)
	v_lshlrev_b32_e32 v0, 16, v87
	v_max_f32_e32 v0, v0, v0
	v_med3_f32 v0, v0, s9, v244
	v_mul_f32_e32 v0, 0xbfb8aa3b, v0
	v_exp_f32_e32 v87, v0
	global_load_ushort v0, v[74:75], off offset:1536
	global_load_ushort v1, v[84:85], off offset:2560
	global_load_ushort v2, v[84:85], off offset:1536
	global_load_ushort v3, v[62:63], off offset:2048
	global_load_ushort v176, v[64:65], off offset:1024
	global_load_ushort v177, v[72:73], off offset:3072
	global_load_ushort v178, v[108:109], off offset:2048
	global_load_ushort v179, v[84:85], off offset:2048
	global_load_ushort v138, v[6:7], off offset:2560
	global_load_ushort v139, v[8:9], off offset:3584
	global_load_ushort v140, v[8:9], off offset:2560
	s_nop 0
	global_load_ushort v10, v[10:11], off offset:3584
	s_nop 0
	global_load_ushort v11, v[74:75], off offset:512
	global_load_ushort v180, v[74:75], off offset:1024
	s_nop 0
	global_load_ushort v8, v[8:9], off offset:3072
	s_nop 0
	global_load_ushort v181, v[6:7], off offset:2048
	v_lshlrev_b32_e32 v7, 16, v106
	v_max_f32_e32 v7, v7, v7
	v_add_f32_e32 v84, 1.0, v87
	v_med3_f32 v7, v7, s9, v244
	v_rcp_f32_e32 v119, v84
	v_mul_f32_e32 v7, 0xbfb8aa3b, v7
	v_exp_f32_e32 v84, v7
	s_waitcnt vmcnt(52)
	v_lshlrev_b32_e32 v7, 16, v110
	v_fma_f32 v6, v80, v119, v149
	v_mul_f32_e32 v6, v15, v6
	v_add_f32_e32 v9, 1.0, v84
	v_max_f32_e32 v6, 0xda24260, v6
	v_rcp_f32_e32 v132, v9
	v_mul_f32_e32 v7, v6, v7
	v_bfe_u32 v9, v7, 16, 1
	v_lshl_add_u32 v17, v16, 1, v92
	v_add3_u32 v7, v7, v9, s10
	ds_write_b16_d16_hi v17, v7 offset:144
	v_fma_f32 v7, v80, v132, v149
	v_rcp_f32_e32 v123, v6
	v_mul_f32_e32 v6, v6, v7
	v_lshlrev_b32_e32 v7, 16, v107
	v_max_f32_e32 v7, v7, v7
	v_med3_f32 v7, v7, s9, v244
	v_mul_f32_e32 v7, 0xbfb8aa3b, v7
	v_exp_f32_e32 v85, v7
	v_max_f32_e32 v6, 0xda24260, v6
	v_lshlrev_b32_e32 v7, 16, v104
	v_mul_f32_e32 v7, v6, v7
	v_add_f32_e32 v9, 1.0, v85
	v_rcp_f32_e32 v133, v9
	v_bfe_u32 v9, v7, 16, 1
	v_add3_u32 v7, v7, v9, s10
	ds_write_b16_d16_hi v17, v7 offset:288
	v_fma_f32 v7, v80, v133, v149
	v_rcp_f32_e32 v134, v6
	v_mul_f32_e32 v6, v6, v7
	v_lshlrev_b32_e32 v7, 16, v88
	v_max_f32_e32 v7, v7, v7
	v_med3_f32 v7, v7, s9, v244
	v_mul_f32_e32 v7, 0xbfb8aa3b, v7
	v_exp_f32_e32 v74, v7
	v_max_f32_e32 v6, 0xda24260, v6
	s_waitcnt vmcnt(51)
	v_lshlrev_b32_e32 v7, 16, v111
	v_mul_f32_e32 v7, v6, v7
	v_add_f32_e32 v9, 1.0, v74
	v_rcp_f32_e32 v144, v9
	v_bfe_u32 v9, v7, 16, 1
	v_add3_u32 v7, v7, v9, s10
	ds_write_b16_d16_hi v17, v7 offset:432
	v_fma_f32 v7, v80, v144, v149
	v_rcp_f32_e32 v135, v6
	v_mul_f32_e32 v6, v6, v7
	v_max_f32_e32 v6, 0xda24260, v6
	v_rcp_f32_e32 v146, v6
	ds_write_b16_d16_hi v17, v105
	v_rcp_f32_e32 v122, v15
	v_pk_mul_f32 v[84:85], v[84:85], v[132:133]
	v_pk_mul_f32 v[86:87], v[86:87], v[118:119]
	v_pk_mul_f32 v[84:85], v[80:81], v[84:85] op_sel_hi:[0,1]
	v_pk_mul_f32 v[86:87], v[80:81], v[86:87] op_sel_hi:[0,1]
	s_movk_i32 s4, 0x50
	v_pk_mul_f32 v[84:85], v[84:85], v[134:135]
	v_pk_mul_f32 v[86:87], v[86:87], v[122:123]
	v_and_b32_sdwa v132, v85, v239 dst_sel:DWORD dst_unused:UNUSED_PAD src0_sel:WORD_1 src1_sel:DWORD
	s_waitcnt vmcnt(23)
	v_lshl_or_b32 v9, v66, 16, v158
	s_waitcnt vmcnt(22)
	v_lshl_or_b32 v13, v67, 16, v13
	v_mad_u64_u32 v[66:67], s[4:5], v16, s4, v[92:93]
	s_waitcnt vmcnt(20)
	v_lshlrev_b32_e32 v5, 16, v5
	v_max_f32_e32 v5, v5, v5
	v_med3_f32 v5, v5, s9, v244
	v_mul_f32_e32 v5, 0xbfb8aa3b, v5
	v_exp_f32_e32 v75, v5
	v_lshlrev_b32_e32 v5, 16, v95
	v_mul_f32_e32 v5, v6, v5
	s_waitcnt vmcnt(15)
	v_lshlrev_b32_e32 v0, 16, v0
	v_add_f32_e32 v7, 1.0, v75
	v_rcp_f32_e32 v145, v7
	v_bfe_u32 v7, v5, 16, 1
	v_add3_u32 v5, v5, v7, s10
	ds_write_b16_d16_hi v17, v5 offset:576
	v_fma_f32 v5, v80, v145, v149
	v_mul_f32_e32 v5, v6, v5
	v_lshlrev_b32_e32 v6, 16, v116
	v_max_f32_e32 v6, v6, v6
	v_med3_f32 v6, v6, s9, v244
	v_mul_f32_e32 v6, 0xbfb8aa3b, v6
	v_exp_f32_e32 v150, v6
	v_max_f32_e32 v5, 0xda24260, v5
	v_lshlrev_b32_e32 v6, 16, v130
	v_mul_f32_e32 v6, v5, v6
	v_add_f32_e32 v7, 1.0, v150
	v_rcp_f32_e32 v152, v7
	v_bfe_u32 v7, v6, 16, 1
	v_add3_u32 v6, v6, v7, s10
	ds_write_b16_d16_hi v17, v6 offset:720
	v_fma_f32 v6, v80, v152, v149
	v_rcp_f32_e32 v147, v5
	v_mul_f32_e32 v5, v5, v6
	s_waitcnt vmcnt(7)
	v_lshlrev_b32_e32 v6, 16, v138
	v_max_f32_e32 v6, v6, v6
	v_med3_f32 v6, v6, s9, v244
	v_mul_f32_e32 v6, 0xbfb8aa3b, v6
	v_exp_f32_e32 v151, v6
	v_max_f32_e32 v5, 0xda24260, v5
	v_lshlrev_b32_e32 v6, 16, v126
	v_mul_f32_e32 v6, v5, v6
	v_add_f32_e32 v7, 1.0, v151
	v_rcp_f32_e32 v153, v7
	v_bfe_u32 v7, v6, 16, 1
	v_add3_u32 v6, v6, v7, s10
	ds_write_b16_d16_hi v17, v6 offset:864
	v_fma_f32 v6, v80, v153, v149
	v_rcp_f32_e32 v154, v5
	v_mul_f32_e32 v5, v5, v6
	v_lshlrev_b32_e32 v6, 16, v117
	v_max_f32_e32 v6, v6, v6
	v_med3_f32 v6, v6, s9, v244
	v_mul_f32_e32 v6, 0xbfb8aa3b, v6
	v_exp_f32_e32 v104, v6
	v_max_f32_e32 v5, 0xda24260, v5
	v_lshlrev_b32_e32 v6, 16, v136
	v_mul_f32_e32 v6, v5, v6
	v_add_f32_e32 v7, 1.0, v104
	v_rcp_f32_e32 v106, v7
	v_bfe_u32 v7, v6, 16, 1
	v_add3_u32 v6, v6, v7, s10
	ds_write_b16_d16_hi v17, v6 offset:1008
	v_fma_f32 v6, v80, v106, v149
	v_rcp_f32_e32 v155, v5
	v_mul_f32_e32 v5, v5, v6
	s_waitcnt vmcnt(6)
	v_lshlrev_b32_e32 v6, 16, v139
	v_max_f32_e32 v6, v6, v6
	v_med3_f32 v6, v6, s9, v244
	v_mul_f32_e32 v6, 0xbfb8aa3b, v6
	v_exp_f32_e32 v105, v6
	v_max_f32_e32 v5, 0xda24260, v5
	v_lshlrev_b32_e32 v6, 16, v120
	v_mul_f32_e32 v6, v5, v6
	v_add_f32_e32 v7, 1.0, v105
	v_rcp_f32_e32 v107, v7
	v_bfe_u32 v7, v6, 16, 1
	v_add3_u32 v88, v6, v7, s10
	v_rcp_f32_e32 v110, v5
	v_fma_f32 v6, v80, v107, v149
	v_mul_f32_e32 v5, v5, v6
	v_lshlrev_b32_e32 v6, 16, v128
	v_max_f32_e32 v6, v6, v6
	v_med3_f32 v6, v6, s9, v244
	v_mul_f32_e32 v6, 0xbfb8aa3b, v6
	v_exp_f32_e32 v116, v6
	v_max_f32_e32 v5, 0xda24260, v5
	s_waitcnt vmcnt(5)
	v_lshlrev_b32_e32 v6, 16, v140
	v_mul_f32_e32 v6, v5, v6
	v_add_f32_e32 v7, 1.0, v116
	v_rcp_f32_e32 v120, v7
	v_bfe_u32 v7, v6, 16, 1
	v_add3_u32 v95, v6, v7, s10
	v_rcp_f32_e32 v111, v5
	v_fma_f32 v6, v80, v120, v149
	v_mul_f32_e32 v5, v5, v6
	v_lshlrev_b32_e32 v6, 16, v129
	v_max_f32_e32 v6, v6, v6
	v_med3_f32 v6, v6, s9, v244
	v_mul_f32_e32 v6, 0xbfb8aa3b, v6
	v_exp_f32_e32 v117, v6
	v_lshlrev_b32_e32 v6, 16, v121
	v_max_f32_e32 v5, 0xda24260, v5
	v_mul_f32_e32 v6, v5, v6
	v_add_f32_e32 v7, 1.0, v117
	v_rcp_f32_e32 v121, v7
	v_bfe_u32 v7, v6, 16, 1
	v_add3_u32 v182, v6, v7, s10
	v_rcp_f32_e32 v126, v5
	v_fma_f32 v6, v80, v121, v149
	v_mul_f32_e32 v5, v5, v6
	v_lshlrev_b32_e32 v6, 16, v127
	v_max_f32_e32 v6, v6, v6
	v_med3_f32 v6, v6, s9, v244
	v_mul_f32_e32 v6, 0xbfb8aa3b, v6
	v_exp_f32_e32 v128, v6
	v_max_f32_e32 v0, v0, v0
	v_med3_f32 v0, v0, s9, v244
	v_mul_f32_e32 v0, 0xbfb8aa3b, v0
	v_add_f32_e32 v7, 1.0, v128
	v_rcp_f32_e32 v130, v7
	v_max_f32_e32 v5, 0xda24260, v5
	s_waitcnt vmcnt(4)
	v_lshlrev_b32_e32 v6, 16, v10
	v_exp_f32_e32 v129, v0
	v_mul_f32_e32 v6, v5, v6
	v_bfe_u32 v7, v6, 16, 1
	v_add3_u32 v183, v6, v7, s10
	v_fma_f32 v6, v80, v130, v149
	v_rcp_f32_e32 v127, v5
	v_mul_f32_e32 v5, v5, v6
	v_add_f32_e32 v6, 1.0, v129
	v_max_f32_e32 v0, 0xda24260, v5
	v_lshlrev_b32_e32 v5, 16, v131
	v_rcp_f32_e32 v131, v6
	v_mul_f32_e32 v5, v0, v5
	v_bfe_u32 v6, v5, 16, 1
	v_add3_u32 v184, v5, v6, s10
	v_fma_f32 v5, v80, v131, v149
	v_rcp_f32_e32 v136, v0
	v_mul_f32_e32 v0, v0, v5
	v_lshlrev_b32_e32 v5, 16, v137
	v_max_f32_e32 v5, v5, v5
	v_med3_f32 v5, v5, s9, v244
	v_mul_f32_e32 v5, 0xbfb8aa3b, v5
	v_exp_f32_e32 v138, v5
	v_lshlrev_b32_e32 v1, 16, v1
	v_max_f32_e32 v1, v1, v1
	v_med3_f32 v1, v1, s9, v244
	v_add_f32_e32 v6, 1.0, v138
	v_rcp_f32_e32 v140, v6
	v_mul_f32_e32 v1, 0xbfb8aa3b, v1
	v_max_f32_e32 v0, 0xda24260, v0
	s_waitcnt vmcnt(3)
	v_lshlrev_b32_e32 v5, 16, v11
	v_exp_f32_e32 v139, v1
	v_mul_f32_e32 v5, v0, v5
	v_bfe_u32 v6, v5, 16, 1
	v_add3_u32 v185, v5, v6, s10
	v_fma_f32 v5, v80, v140, v149
	v_rcp_f32_e32 v137, v0
	v_mul_f32_e32 v0, v0, v5
	v_add_f32_e32 v5, 1.0, v139
	v_lshlrev_b32_e32 v1, 16, v141
	v_rcp_f32_e32 v141, v5
	v_max_f32_e32 v0, 0xda24260, v0
	v_mul_f32_e32 v1, v0, v1
	v_bfe_u32 v5, v1, 16, 1
	v_add3_u32 v186, v1, v5, s10
	v_fma_f32 v1, v80, v141, v149
	v_pk_mul_f32 v[150:151], v[150:151], v[152:153]
	v_pk_mul_f32 v[74:75], v[74:75], v[144:145]
	v_rcp_f32_e32 v142, v0
	v_mul_f32_e32 v0, v0, v1
	v_pk_mul_f32 v[150:151], v[80:81], v[150:151] op_sel_hi:[0,1]
	v_pk_mul_f32 v[74:75], v[80:81], v[74:75] op_sel_hi:[0,1]
	v_max_f32_e32 v187, 0xda24260, v0
	v_lshlrev_b32_e32 v0, 16, v2
	v_pk_mul_f32 v[150:151], v[150:151], v[154:155]
	v_pk_mul_f32 v[74:75], v[74:75], v[146:147]
	v_mul_f32_e32 v0, v187, v0
	v_and_b32_sdwa v152, v150, v239 dst_sel:DWORD dst_unused:UNUSED_PAD src0_sel:WORD_1 src1_sel:DWORD
	v_and_b32_sdwa v144, v75, v239 dst_sel:DWORD dst_unused:UNUSED_PAD src0_sel:WORD_1 src1_sel:DWORD
	v_and_b32_sdwa v145, v74, v239 dst_sel:DWORD dst_unused:UNUSED_PAD src0_sel:WORD_1 src1_sel:DWORD
	v_and_b32_sdwa v133, v84, v239 dst_sel:DWORD dst_unused:UNUSED_PAD src0_sel:WORD_1 src1_sel:DWORD
	v_and_b32_sdwa v118, v87, v239 dst_sel:DWORD dst_unused:UNUSED_PAD src0_sel:WORD_1 src1_sel:DWORD
	v_and_b32_sdwa v119, v86, v239 dst_sel:DWORD dst_unused:UNUSED_PAD src0_sel:WORD_1 src1_sel:DWORD
	v_bfe_u32 v1, v0, 16, 1
	v_and_b32_sdwa v67, v151, v239 dst_sel:DWORD dst_unused:UNUSED_PAD src0_sel:WORD_1 src1_sel:DWORD
	v_add3_u32 v150, v150, v152, s10
	v_add3_u32 v75, v75, v144, s10
	v_add3_u32 v74, v74, v145, s10
	v_add3_u32 v85, v85, v132, s10
	v_add3_u32 v84, v84, v133, s10
	v_add3_u32 v87, v87, v118, s10
	v_add3_u32 v86, v86, v119, s10
	v_rcp_f32_e32 v143, v187
	v_add3_u32 v188, v0, v1, s10
	v_lshl_or_b32 v3, v3, 16, v170
	v_lshl_or_b32 v2, v176, 16, v169
	v_lshl_or_b32 v1, v171, 16, v168
	v_lshl_or_b32 v0, v177, 16, v167
	v_lshl_or_b32 v7, v178, 16, v166
	v_lshl_or_b32 v6, v173, 16, v165
	v_lshl_or_b32 v5, v172, 16, v164
	v_lshl_or_b32 v4, v4, 16, v163
	v_lshl_or_b32 v11, v179, 16, v162
	s_waitcnt vmcnt(2)
	v_lshl_or_b32 v10, v180, 16, v159
	s_waitcnt vmcnt(1)
	v_lshl_or_b32 v8, v8, 16, v157
	s_waitcnt vmcnt(0)
	v_lshl_or_b32 v15, v181, 16, v156
	v_lshl_or_b32 v14, v174, 16, v14
	v_lshl_or_b32 v12, v175, 16, v12
	s_movk_i32 s16, 0x50
	v_add3_u32 v67, v151, v67, s10
	ds_write_b16_d16_hi v17, v150 offset:5472
	ds_write_b16_d16_hi v17, v67 offset:5616
	ds_write_b16_d16_hi v17, v74 offset:5184
	ds_write_b16_d16_hi v17, v75 offset:5328
	v_and_b32_e32 v75, 0xffff0000, v75
	v_and_b32_e32 v74, 0xffff0000, v74
	ds_write_b16_d16_hi v17, v84 offset:4896
	ds_write_b16_d16_hi v17, v85 offset:5040
	v_and_b32_e32 v85, 0xffff0000, v85
	v_and_b32_e32 v84, 0xffff0000, v84
	ds_write_b16_d16_hi v17, v86 offset:4608
	ds_write_b16_d16_hi v17, v87 offset:4752
	v_and_b32_e32 v87, 0xffff0000, v87
	v_and_b32_e32 v86, 0xffff0000, v86
	global_load_ushort v118, v[76:77], off offset:3072
	s_nop 0
	global_load_ushort v102, v[102:103], off offset:3072
	s_nop 0
	global_load_ushort v103, v[78:79], off offset:1024
	global_load_ushort v119, v[82:83], off offset:1024
	global_load_ushort v123, v[82:83], off offset:2048
	s_nop 0
	global_load_ushort v78, v[78:79], off
	s_nop 0
	global_load_ushort v79, v[76:77], off offset:2048
	global_load_ushort v82, v[124:125], off offset:3584
	s_mov_b32 s5, 0xb215000
	v_add_co_u32_e32 v76, vcc, s5, v18
	v_pk_mul_f32 v[138:139], v[138:139], v[140:141]
	s_nop 0
	v_addc_co_u32_e32 v77, vcc, 0, v19, vcc
	global_load_ushort v83, v[76:77], off
	s_nop 0
	global_load_ushort v76, v[76:77], off offset:3584
	s_nop 0
	global_load_ushort v77, v[124:125], off offset:2560
	s_nop 0
	global_load_ushort v114, v[114:115], off offset:512
	s_nop 0
	global_load_ushort v115, v[112:113], off offset:1536
	global_load_ushort v144, v[108:109], off offset:1536
	ds_write_b16_d16_hi v17, v88 offset:1152
	ds_write_b16_d16_hi v17, v95 offset:1296
	ds_write_b16_d16_hi v17, v182 offset:1440
	ds_write_b16_d16_hi v17, v183 offset:1584
	ds_write_b16_d16_hi v17, v184 offset:1728
	ds_write_b16_d16_hi v17, v185 offset:1872
	ds_write_b16_d16_hi v17, v186 offset:2016
	ds_write_b16_d16_hi v17, v188 offset:2160
	global_load_ushort v88, v[112:113], off offset:512
	global_load_ushort v95, v[108:109], off offset:2560
	v_pk_mul_f32 v[128:129], v[128:129], v[130:131]
	v_pk_mul_f32 v[116:117], v[116:117], v[120:121]
	v_pk_mul_f32 v[104:105], v[104:105], v[106:107]
	v_pk_mul_f32 v[138:139], v[80:81], v[138:139] op_sel_hi:[0,1]
	v_pk_mul_f32 v[128:129], v[80:81], v[128:129] op_sel_hi:[0,1]
	v_pk_mul_f32 v[116:117], v[80:81], v[116:117] op_sel_hi:[0,1]
	v_pk_mul_f32 v[104:105], v[80:81], v[104:105] op_sel_hi:[0,1]
	v_pk_mul_f32 v[138:139], v[138:139], v[142:143]
	v_pk_mul_f32 v[128:129], v[128:129], v[136:137]
	v_pk_mul_f32 v[116:117], v[116:117], v[126:127]
	v_pk_mul_f32 v[104:105], v[104:105], v[110:111]
	v_and_b32_sdwa v140, v138, v239 dst_sel:DWORD dst_unused:UNUSED_PAD src0_sel:WORD_1 src1_sel:DWORD
	v_and_b32_sdwa v130, v129, v239 dst_sel:DWORD dst_unused:UNUSED_PAD src0_sel:WORD_1 src1_sel:DWORD
	v_and_b32_sdwa v131, v128, v239 dst_sel:DWORD dst_unused:UNUSED_PAD src0_sel:WORD_1 src1_sel:DWORD
	v_and_b32_sdwa v120, v117, v239 dst_sel:DWORD dst_unused:UNUSED_PAD src0_sel:WORD_1 src1_sel:DWORD
	v_and_b32_sdwa v121, v116, v239 dst_sel:DWORD dst_unused:UNUSED_PAD src0_sel:WORD_1 src1_sel:DWORD
	v_and_b32_sdwa v106, v105, v239 dst_sel:DWORD dst_unused:UNUSED_PAD src0_sel:WORD_1 src1_sel:DWORD
	v_and_b32_sdwa v107, v104, v239 dst_sel:DWORD dst_unused:UNUSED_PAD src0_sel:WORD_1 src1_sel:DWORD
	v_add3_u32 v142, v138, v140, s10
	v_add3_u32 v129, v129, v130, s10
	v_add3_u32 v128, v128, v131, s10
	v_add3_u32 v117, v117, v120, s10
	v_add3_u32 v116, v116, v121, s10
	v_add3_u32 v105, v105, v106, s10
	v_add3_u32 v104, v104, v107, s10
	s_waitcnt vmcnt(15)
	v_lshlrev_b32_e32 v108, 16, v118
	s_waitcnt vmcnt(14)
	v_lshlrev_b32_e32 v113, 16, v102
	s_waitcnt vmcnt(10)
	v_lshlrev_b32_e32 v118, 16, v78
	v_max_f32_e32 v78, v108, v108
	s_waitcnt vmcnt(9)
	v_lshlrev_b32_e32 v112, 16, v79
	s_waitcnt vmcnt(8)
	v_lshlrev_b32_e32 v79, 16, v82
	v_med3_f32 v78, v78, s9, v244
	v_lshlrev_b32_e32 v82, 16, v103
	v_max_f32_e32 v79, v79, v79
	v_mul_f32_e32 v78, 0xbfb8aa3b, v78
	s_waitcnt vmcnt(5)
	v_lshlrev_b32_e32 v122, 16, v77
	v_lshlrev_b32_e32 v77, 16, v83
	v_lshlrev_b32_e32 v124, 16, v76
	v_max_f32_e32 v76, v82, v82
	s_waitcnt vmcnt(3)
	v_lshlrev_b32_e32 v82, 16, v115
	v_med3_f32 v79, v79, s9, v244
	v_exp_f32_e32 v102, v78
	v_max_f32_e32 v77, v77, v77
	v_max_f32_e32 v82, v82, v82
	v_mul_f32_e32 v79, 0xbfb8aa3b, v79
	v_lshlrev_b32_e32 v83, 16, v114
	v_med3_f32 v76, v76, s9, v244
	v_med3_f32 v77, v77, s9, v244
	v_med3_f32 v82, v82, s9, v244
	v_exp_f32_e32 v103, v79
	v_max_f32_e32 v83, v83, v83
	v_mul_f32_e32 v76, 0xbfb8aa3b, v76
	v_mul_f32_e32 v77, 0xbfb8aa3b, v77
	v_mul_f32_e32 v82, 0xbfb8aa3b, v82
	v_med3_f32 v83, v83, s9, v244
	v_exp_f32_e32 v76, v76
	v_exp_f32_e32 v78, v77
	v_exp_f32_e32 v77, v82
	v_add_f32_e32 v82, 1.0, v102
	v_mul_f32_e32 v79, 0xbfb8aa3b, v83
	v_rcp_f32_e32 v114, v82
	v_exp_f32_e32 v79, v79
	v_add_f32_e32 v83, 1.0, v103
	v_rcp_f32_e32 v115, v83
	v_add_f32_e32 v108, 1.0, v76
	v_add_f32_e32 v83, 1.0, v78
	v_rcp_f32_e32 v82, v108
	v_rcp_f32_e32 v108, v83
	v_fma_f32 v83, v80, v114, v149
	v_add_f32_e32 v109, 1.0, v79
	v_mul_f32_e32 v83, v187, v83
	v_rcp_f32_e32 v109, v109
	v_fma_f32 v125, v80, v115, v149
	v_max_f32_e32 v83, 0xda24260, v83
	v_rcp_f32_e32 v134, v83
	v_mul_f32_e32 v112, v83, v112
	v_mul_f32_e32 v83, v83, v125
	v_fma_f32 v132, v80, v108, v149
	v_bfe_u32 v125, v112, 16, 1
	v_max_f32_e32 v83, 0xda24260, v83
	v_add3_u32 v146, v112, v125, s10
	v_rcp_f32_e32 v135, v83
	v_mul_f32_e32 v112, v83, v122
	v_mul_f32_e32 v83, v83, v132
	v_fma_f32 v133, v80, v109, v149
	v_bfe_u32 v122, v112, 16, 1
	v_max_f32_e32 v83, 0xda24260, v83
	v_add3_u32 v147, v112, v122, s10
	v_rcp_f32_e32 v132, v83
	v_mul_f32_e32 v112, v83, v113
	v_mul_f32_e32 v83, v83, v133
	v_fma_f32 v145, v80, v82, v149
	v_bfe_u32 v113, v112, 16, 1
	v_max_f32_e32 v83, 0xda24260, v83
	v_add3_u32 v151, v112, v113, s10
	v_rcp_f32_e32 v133, v83
	v_mul_f32_e32 v112, v83, v124
	v_mul_f32_e32 v83, v83, v145
	v_max_f32_e32 v124, 0xda24260, v83
	v_add_f32_e32 v83, 1.0, v77
	v_rcp_f32_e32 v83, v83
	v_bfe_u32 v113, v112, 16, 1
	v_add3_u32 v152, v112, v113, s10
	v_mul_f32_e32 v112, v124, v118
	v_bfe_u32 v113, v112, 16, 1
	v_add3_u32 v153, v112, v113, s10
	v_fma_f32 v112, v80, v83, v149
	v_mul_f32_e32 v113, v124, v112
	v_lshlrev_b32_e32 v112, 16, v123
	v_max_f32_e32 v112, v112, v112
	v_med3_f32 v112, v112, s9, v244
	v_mul_f32_e32 v112, 0xbfb8aa3b, v112
	v_exp_f32_e32 v112, v112
	v_max_f32_e32 v113, 0xda24260, v113
	s_waitcnt vmcnt(1)
	v_lshlrev_b32_e32 v88, 16, v88
	s_waitcnt vmcnt(0)
	v_lshlrev_b32_e32 v95, 16, v95
	v_add_f32_e32 v118, 1.0, v112
	v_rcp_f32_e32 v118, v118
	v_mul_f32_e32 v88, v113, v88
	v_max_f32_e32 v95, v95, v95
	v_rcp_f32_e32 v122, v124
	v_bfe_u32 v124, v88, 16, 1
	v_med3_f32 v95, v95, s9, v244
	v_add3_u32 v88, v88, v124, s10
	v_fma_f32 v124, v80, v118, v149
	v_mul_f32_e32 v95, 0xbfb8aa3b, v95
	v_rcp_f32_e32 v123, v113
	v_mul_f32_e32 v124, v113, v124
	v_exp_f32_e32 v113, v95
	v_lshlrev_b32_e32 v125, 16, v119
	v_max_f32_e32 v95, 0xda24260, v124
	v_mul_f32_e32 v125, v95, v125
	v_add_f32_e32 v119, 1.0, v113
	v_rcp_f32_e32 v119, v119
	v_bfe_u32 v145, v125, 16, 1
	v_add3_u32 v154, v125, v145, s10
	v_rcp_f32_e32 v124, v95
	v_fma_f32 v125, v80, v119, v149
	v_mul_f32_e32 v95, v95, v125
	v_max_f32_e32 v95, 0xda24260, v95
	v_lshlrev_b32_e32 v144, 16, v144
	v_mul_f32_e32 v144, v95, v144
	v_bfe_u32 v145, v144, 16, 1
	v_add3_u32 v155, v144, v145, s10
	v_and_b32_e32 v145, 0xffff0000, v67
	v_and_b32_sdwa v67, v139, v239 dst_sel:DWORD dst_unused:UNUSED_PAD src0_sel:WORD_1 src1_sel:DWORD
	v_rcp_f32_e32 v125, v95
	v_and_b32_e32 v144, 0xffff0000, v150
	v_add3_u32 v67, v139, v67, s10
	ds_write_b16_d16_hi v17, v142 offset:6624
	ds_write_b16_d16_hi v17, v67 offset:6768
	ds_write_b16_d16_hi v17, v128 offset:6336
	ds_write_b16_d16_hi v17, v129 offset:6480
	v_and_b32_e32 v129, 0xffff0000, v129
	v_and_b32_e32 v128, 0xffff0000, v128
	ds_write_b16_d16_hi v17, v116 offset:6048
	ds_write_b16_d16_hi v17, v117 offset:6192
	v_and_b32_e32 v117, 0xffff0000, v117
	v_and_b32_e32 v116, 0xffff0000, v116
	ds_write_b16_d16_hi v17, v104 offset:5760
	ds_write_b16_d16_hi v17, v105 offset:5904
	v_and_b32_e32 v105, 0xffff0000, v105
	v_and_b32_e32 v104, 0xffff0000, v104
	global_load_ushort v106, v[20:21], off offset:3072
	s_nop 0
	global_load_ushort v68, v[68:69], off offset:3072
	s_nop 0
	global_load_ushort v69, v[22:23], off offset:1024
	global_load_ushort v139, v[24:25], off offset:1024
	global_load_ushort v131, v[24:25], off offset:2048
	s_nop 0
	global_load_ushort v22, v[22:23], off
	s_nop 0
	global_load_ushort v20, v[20:21], off offset:2048
	s_nop 0
	global_load_ushort v21, v[72:73], off offset:3584
	s_mov_b32 s4, 0xb21e000
	v_add_co_u32_e32 v18, vcc, s4, v18
	s_waitcnt vmcnt(6)
	v_lshlrev_b32_e32 v68, 16, v68
	v_addc_co_u32_e32 v19, vcc, 0, v19, vcc
	global_load_ushort v23, v[18:19], off
	s_nop 0
	global_load_ushort v18, v[18:19], off offset:3584
	s_nop 0
	global_load_ushort v19, v[72:73], off offset:2560
	global_load_ushort v24, v[70:71], off offset:512
	global_load_ushort v25, v[64:65], off offset:1536
	s_nop 0
	global_load_ushort v70, v[62:63], off offset:1536
	ds_write_b16_d16_hi v17, v146 offset:2304
	ds_write_b16_d16_hi v17, v147 offset:2448
	ds_write_b16_d16_hi v17, v151 offset:2592
	ds_write_b16_d16_hi v17, v152 offset:2736
	ds_write_b16_d16_hi v17, v153 offset:2880
	ds_write_b16_d16_hi v17, v88 offset:3024
	ds_write_b16_d16_hi v17, v154 offset:3168
	ds_write_b16_d16_hi v17, v155 offset:3312
	global_load_ushort v64, v[64:65], off offset:512
	s_nop 0
	global_load_ushort v62, v[62:63], off offset:2560
	v_lshlrev_b32_e32 v63, 16, v106
	s_waitcnt vmcnt(9)
	v_lshlrev_b32_e32 v65, 16, v20
	s_waitcnt vmcnt(8)
	v_lshlrev_b32_e32 v20, 16, v21
	v_lshlrev_b32_e32 v21, 16, v69
	v_lshlrev_b32_e32 v69, 16, v22
	v_max_f32_e32 v22, v63, v63
	v_med3_f32 v22, v22, s9, v244
	v_max_f32_e32 v20, v20, v20
	v_mul_f32_e32 v22, 0xbfb8aa3b, v22
	v_med3_f32 v20, v20, s9, v244
	v_mul_f32_e32 v20, 0xbfb8aa3b, v20
	s_waitcnt vmcnt(6)
	v_lshlrev_b32_e32 v71, 16, v18
	s_waitcnt vmcnt(5)
	v_lshlrev_b32_e32 v63, 16, v19
	v_lshlrev_b32_e32 v19, 16, v23
	s_waitcnt vmcnt(4)
	v_lshlrev_b32_e32 v23, 16, v24
	v_exp_f32_e32 v24, v22
	v_max_f32_e32 v18, v21, v21
	s_waitcnt vmcnt(3)
	v_lshlrev_b32_e32 v21, 16, v25
	v_max_f32_e32 v19, v19, v19
	v_max_f32_e32 v23, v23, v23
	v_max_f32_e32 v21, v21, v21
	v_med3_f32 v19, v19, s9, v244
	v_med3_f32 v23, v23, s9, v244
	v_exp_f32_e32 v25, v20
	v_med3_f32 v21, v21, s9, v244
	v_mul_f32_e32 v19, 0xbfb8aa3b, v19
	v_mul_f32_e32 v22, 0xbfb8aa3b, v23
	v_med3_f32 v18, v18, s9, v244
	v_mul_f32_e32 v23, 0xbfb8aa3b, v21
	v_exp_f32_e32 v20, v19
	v_exp_f32_e32 v21, v22
	v_add_f32_e32 v22, 1.0, v24
	v_mul_f32_e32 v18, 0xbfb8aa3b, v18
	v_rcp_f32_e32 v106, v22
	v_exp_f32_e32 v18, v18
	v_exp_f32_e32 v19, v23
	v_add_f32_e32 v23, 1.0, v25
	v_rcp_f32_e32 v107, v23
	v_add_f32_e32 v23, 1.0, v20
	v_rcp_f32_e32 v110, v23
	v_fma_f32 v23, v80, v106, v149
	v_add_f32_e32 v72, 1.0, v18
	v_add_f32_e32 v73, 1.0, v21
	v_mul_f32_e32 v23, v95, v23
	v_rcp_f32_e32 v22, v72
	v_rcp_f32_e32 v111, v73
	v_fma_f32 v72, v80, v107, v149
	v_max_f32_e32 v23, 0xda24260, v23
	v_rcp_f32_e32 v120, v23
	v_mul_f32_e32 v65, v23, v65
	v_mul_f32_e32 v23, v23, v72
	v_fma_f32 v88, v80, v110, v149
	v_max_f32_e32 v23, 0xda24260, v23
	v_bfe_u32 v72, v65, 16, 1
	v_rcp_f32_e32 v121, v23
	v_mul_f32_e32 v63, v23, v63
	v_mul_f32_e32 v23, v23, v88
	v_fma_f32 v95, v80, v111, v149
	v_add3_u32 v143, v65, v72, s10
	v_bfe_u32 v65, v63, 16, 1
	v_max_f32_e32 v23, 0xda24260, v23
	v_add3_u32 v146, v63, v65, s10
	v_rcp_f32_e32 v126, v23
	v_mul_f32_e32 v63, v23, v68
	v_mul_f32_e32 v23, v23, v95
	v_fma_f32 v73, v80, v22, v149
	v_bfe_u32 v65, v63, 16, 1
	v_max_f32_e32 v23, 0xda24260, v23
	v_add3_u32 v95, v63, v65, s10
	v_rcp_f32_e32 v127, v23
	v_mul_f32_e32 v63, v23, v71
	v_mul_f32_e32 v23, v23, v73
	v_bfe_u32 v65, v63, 16, 1
	v_max_f32_e32 v68, 0xda24260, v23
	v_add3_u32 v147, v63, v65, s10
	v_mul_f32_e32 v63, v68, v69
	v_bfe_u32 v65, v63, 16, 1
	v_add3_u32 v150, v63, v65, s10
	v_lshlrev_b32_e32 v65, 16, v131
	v_max_f32_e32 v65, v65, v65
	v_med3_f32 v65, v65, s9, v244
	v_add_f32_e32 v23, 1.0, v19
	v_mul_f32_e32 v65, 0xbfb8aa3b, v65
	v_rcp_f32_e32 v23, v23
	v_exp_f32_e32 v136, v65
	s_waitcnt vmcnt(0)
	v_lshlrev_b32_e32 v62, 16, v62
	v_max_f32_e32 v62, v62, v62
	v_fma_f32 v63, v80, v23, v149
	v_add_f32_e32 v65, 1.0, v136
	v_med3_f32 v62, v62, s9, v244
	v_mul_f32_e32 v63, v68, v63
	v_rcp_f32_e32 v138, v65
	v_mul_f32_e32 v62, 0xbfb8aa3b, v62
	v_max_f32_e32 v63, 0xda24260, v63
	v_lshlrev_b32_e32 v64, 16, v64
	v_exp_f32_e32 v137, v62
	v_mul_f32_e32 v64, v63, v64
	v_bfe_u32 v65, v64, 16, 1
	v_add3_u32 v151, v64, v65, s10
	v_fma_f32 v64, v80, v138, v149
	v_rcp_f32_e32 v131, v63
	v_mul_f32_e32 v63, v63, v64
	v_add_f32_e32 v64, 1.0, v137
	v_max_f32_e32 v62, 0xda24260, v63
	v_lshlrev_b32_e32 v63, 16, v139
	v_rcp_f32_e32 v139, v64
	v_mul_f32_e32 v63, v62, v63
	v_bfe_u32 v64, v63, 16, 1
	v_add3_u32 v152, v63, v64, s10
	v_fma_f32 v63, v80, v139, v149
	v_rcp_f32_e32 v140, v62
	v_mul_f32_e32 v62, v62, v63
	v_max_f32_e32 v88, 0xda24260, v62
	v_lshlrev_b32_e32 v62, 16, v70
	v_mul_f32_e32 v62, v88, v62
	v_bfe_u32 v63, v62, 16, 1
	v_add3_u32 v153, v62, v63, s10
	v_pk_mul_f32 v[62:63], v[88:89], v[86:87] op_sel_hi:[0,1]
	v_pk_mul_f32 v[64:65], v[88:89], v[84:85] op_sel_hi:[0,1]
	v_rcp_f32_e32 v130, v68
	v_cvt_pk_bf16_f32 v62, v62, v63
	v_cvt_pk_bf16_f32 v63, v64, v65
	v_pk_mul_f32 v[64:65], v[88:89], v[74:75] op_sel_hi:[0,1]
	v_pk_mul_f32 v[68:69], v[88:89], v[144:145] op_sel_hi:[0,1]
	v_cvt_pk_bf16_f32 v64, v64, v65
	v_cvt_pk_bf16_f32 v65, v68, v69
	v_pk_mul_f32 v[68:69], v[88:89], v[104:105] op_sel_hi:[0,1]
	v_pk_mul_f32 v[70:71], v[88:89], v[116:117] op_sel_hi:[0,1]
	v_and_b32_e32 v73, 0xffff0000, v67
	v_and_b32_e32 v72, 0xffff0000, v142
	v_cvt_pk_bf16_f32 v68, v68, v69
	v_cvt_pk_bf16_f32 v69, v70, v71
	v_pk_mul_f32 v[70:71], v[88:89], v[128:129] op_sel_hi:[0,1]
	v_pk_mul_f32 v[72:73], v[88:89], v[72:73] op_sel_hi:[0,1]
	v_cvt_pk_bf16_f32 v70, v70, v71
	v_cvt_pk_bf16_f32 v71, v72, v73
	v_pk_mul_f32 v[72:73], v[102:103], v[114:115]
	v_rcp_f32_e32 v141, v88
	v_pk_mul_f32 v[72:73], v[80:81], v[72:73] op_sel_hi:[0,1]
	v_pk_mul_f32 v[72:73], v[72:73], v[134:135]
	s_nop 0
	v_and_b32_sdwa v67, v73, v239 dst_sel:DWORD dst_unused:UNUSED_PAD src0_sel:WORD_1 src1_sel:DWORD
	v_and_b32_sdwa v74, v72, v239 dst_sel:DWORD dst_unused:UNUSED_PAD src0_sel:WORD_1 src1_sel:DWORD
	v_add3_u32 v67, v73, v67, s10
	v_add3_u32 v72, v72, v74, s10
	v_pk_mul_f32 v[74:75], v[78:79], v[108:109]
	ds_write_b16_d16_hi v17, v72 offset:6912
	ds_write_b16_d16_hi v17, v67 offset:7056
	v_and_b32_e32 v73, 0xffff0000, v67
	v_and_b32_e32 v72, 0xffff0000, v72
	v_pk_mul_f32 v[74:75], v[80:81], v[74:75] op_sel_hi:[0,1]
	v_pk_mul_f32 v[72:73], v[88:89], v[72:73] op_sel_hi:[0,1]
	v_pk_mul_f32 v[74:75], v[74:75], v[132:133]
	v_cvt_pk_bf16_f32 v72, v72, v73
	v_and_b32_sdwa v67, v75, v239 dst_sel:DWORD dst_unused:UNUSED_PAD src0_sel:WORD_1 src1_sel:DWORD
	v_and_b32_sdwa v73, v74, v239 dst_sel:DWORD dst_unused:UNUSED_PAD src0_sel:WORD_1 src1_sel:DWORD
	v_add3_u32 v67, v75, v67, s10
	v_add3_u32 v73, v74, v73, s10
	v_and_b32_e32 v75, 0xffff0000, v67
	v_and_b32_e32 v74, 0xffff0000, v73
	v_pk_mul_f32 v[74:75], v[88:89], v[74:75] op_sel_hi:[0,1]
	ds_write_b16_d16_hi v17, v73 offset:7200
	ds_write_b16_d16_hi v17, v67 offset:7344
	v_cvt_pk_bf16_f32 v73, v74, v75
	v_pk_mul_f32 v[74:75], v[76:77], v[82:83]
	s_nop 0
	v_pk_mul_f32 v[74:75], v[80:81], v[74:75] op_sel_hi:[0,1]
	v_pk_mul_f32 v[74:75], v[74:75], v[122:123]
	s_nop 0
	v_and_b32_sdwa v67, v75, v239 dst_sel:DWORD dst_unused:UNUSED_PAD src0_sel:WORD_1 src1_sel:DWORD
	v_and_b32_sdwa v76, v74, v239 dst_sel:DWORD dst_unused:UNUSED_PAD src0_sel:WORD_1 src1_sel:DWORD
	v_add3_u32 v67, v75, v67, s10
	v_add3_u32 v74, v74, v76, s10
	v_pk_mul_f32 v[76:77], v[112:113], v[118:119]
	ds_write_b16_d16_hi v17, v74 offset:7488
	ds_write_b16_d16_hi v17, v67 offset:7632
	v_and_b32_e32 v75, 0xffff0000, v67
	v_and_b32_e32 v74, 0xffff0000, v74
	v_pk_mul_f32 v[76:77], v[80:81], v[76:77] op_sel_hi:[0,1]
	v_pk_mul_f32 v[74:75], v[88:89], v[74:75] op_sel_hi:[0,1]
	v_pk_mul_f32 v[76:77], v[76:77], v[124:125]
	v_cvt_pk_bf16_f32 v74, v74, v75
	v_and_b32_sdwa v75, v76, v239 dst_sel:DWORD dst_unused:UNUSED_PAD src0_sel:WORD_1 src1_sel:DWORD
	v_and_b32_sdwa v67, v77, v239 dst_sel:DWORD dst_unused:UNUSED_PAD src0_sel:WORD_1 src1_sel:DWORD
	v_add3_u32 v75, v76, v75, s10
	v_add3_u32 v67, v77, v67, s10
	ds_write_b16_d16_hi v17, v75 offset:7776
	ds_write_b16_d16_hi v17, v67 offset:7920
	v_pk_mul_f32 v[24:25], v[24:25], v[106:107]
	v_and_b32_e32 v77, 0xffff0000, v67
	v_and_b32_e32 v76, 0xffff0000, v75
	v_pk_mul_f32 v[24:25], v[80:81], v[24:25] op_sel_hi:[0,1]
	v_pk_mul_f32 v[76:77], v[88:89], v[76:77] op_sel_hi:[0,1]
	v_pk_mul_f32 v[24:25], v[24:25], v[120:121]
	v_cvt_pk_bf16_f32 v75, v76, v77
	v_and_b32_sdwa v67, v25, v239 dst_sel:DWORD dst_unused:UNUSED_PAD src0_sel:WORD_1 src1_sel:DWORD
	v_and_b32_sdwa v76, v24, v239 dst_sel:DWORD dst_unused:UNUSED_PAD src0_sel:WORD_1 src1_sel:DWORD
	v_add3_u32 v25, v25, v67, s10
	v_add3_u32 v24, v24, v76, s10
	v_pk_mul_f32 v[20:21], v[20:21], v[110:111]
	ds_write_b16_d16_hi v17, v143 offset:3456
	ds_write_b16_d16_hi v17, v146 offset:3600
	ds_write_b16_d16_hi v17, v95 offset:3744
	ds_write_b16_d16_hi v17, v147 offset:3888
	ds_write_b16_d16_hi v17, v150 offset:4032
	ds_write_b16_d16_hi v17, v151 offset:4176
	ds_write_b16_d16_hi v17, v152 offset:4320
	ds_write_b16_d16_hi v17, v153 offset:4464
	ds_write_b16_d16_hi v17, v24 offset:8064
	ds_write_b16_d16_hi v17, v25 offset:8208
	v_and_b32_e32 v25, 0xffff0000, v25
	v_and_b32_e32 v24, 0xffff0000, v24
	v_pk_mul_f32 v[20:21], v[80:81], v[20:21] op_sel_hi:[0,1]
	v_pk_mul_f32 v[24:25], v[88:89], v[24:25] op_sel_hi:[0,1]
	v_pk_mul_f32 v[20:21], v[20:21], v[126:127]
	v_cvt_pk_bf16_f32 v76, v24, v25
	v_and_b32_sdwa v24, v21, v239 dst_sel:DWORD dst_unused:UNUSED_PAD src0_sel:WORD_1 src1_sel:DWORD
	v_and_b32_sdwa v25, v20, v239 dst_sel:DWORD dst_unused:UNUSED_PAD src0_sel:WORD_1 src1_sel:DWORD
	v_add3_u32 v21, v21, v24, s10
	v_add3_u32 v20, v20, v25, s10
	v_pk_mul_f32 v[18:19], v[18:19], v[22:23]
	ds_write_b16_d16_hi v17, v20 offset:8352
	ds_write_b16_d16_hi v17, v21 offset:8496
	v_and_b32_e32 v21, 0xffff0000, v21
	v_and_b32_e32 v20, 0xffff0000, v20
	v_pk_mul_f32 v[18:19], v[80:81], v[18:19] op_sel_hi:[0,1]
	v_pk_mul_f32 v[20:21], v[88:89], v[20:21] op_sel_hi:[0,1]
	v_pk_mul_f32 v[18:19], v[18:19], v[130:131]
	v_cvt_pk_bf16_f32 v77, v20, v21
	v_and_b32_sdwa v20, v19, v239 dst_sel:DWORD dst_unused:UNUSED_PAD src0_sel:WORD_1 src1_sel:DWORD
	v_and_b32_sdwa v21, v18, v239 dst_sel:DWORD dst_unused:UNUSED_PAD src0_sel:WORD_1 src1_sel:DWORD
	v_add3_u32 v19, v19, v20, s10
	v_add3_u32 v18, v18, v21, s10
	ds_write_b16_d16_hi v17, v18 offset:8640
	ds_write_b16_d16_hi v17, v19 offset:8784
	v_and_b32_e32 v19, 0xffff0000, v19
	v_and_b32_e32 v18, 0xffff0000, v18
	v_pk_mul_f32 v[18:19], v[88:89], v[18:19] op_sel_hi:[0,1]
	v_cvt_pk_bf16_f32 v78, v18, v19
	v_pk_mul_f32 v[18:19], v[136:137], v[138:139]
	s_nop 0
	v_pk_mul_f32 v[18:19], v[80:81], v[18:19] op_sel_hi:[0,1]
	v_pk_mul_f32 v[18:19], v[18:19], v[140:141]
	s_nop 0
	v_and_b32_sdwa v21, v18, v239 dst_sel:DWORD dst_unused:UNUSED_PAD src0_sel:WORD_1 src1_sel:DWORD
	v_and_b32_sdwa v20, v19, v239 dst_sel:DWORD dst_unused:UNUSED_PAD src0_sel:WORD_1 src1_sel:DWORD
	v_add3_u32 v18, v18, v21, s10
	v_add3_u32 v19, v19, v20, s10
	ds_write_b16_d16_hi v17, v18 offset:8928
	ds_write_b16_d16_hi v17, v19 offset:9072
	v_and_b32_e32 v19, 0xffff0000, v19
	v_and_b32_e32 v18, 0xffff0000, v18
	v_pk_mul_f32 v[18:19], v[88:89], v[18:19] op_sel_hi:[0,1]
	v_cvt_pk_bf16_f32 v79, v18, v19
	v_lshl_add_u32 v16, v16, 2, v92
	ds_write_b128 v66, v[62:65] offset:9216
	ds_write_b128 v66, v[68:71] offset:9232
	ds_write_b128 v66, v[72:75] offset:9248
	ds_write_b128 v66, v[76:79] offset:9264
	ds_write_b32 v16, v88 offset:19456
	ds_write_b128 v66, v[12:15] offset:14336
	ds_write_b128 v66, v[8:11] offset:14352
	ds_write_b128 v66, v[4:7] offset:14368
	ds_write_b128 v66, v[0:3] offset:14384
	s_waitcnt lgkmcnt(0)
	s_movk_i32 s17, 0x90
	v_mad_u32_u24 v72, v35, s17, v92
	v_lshlrev_b32_e32 v73, 4, v81
	v_add_u32_e32 v66, v72, v73
	ds_read_b128 v[0:3], v66 offset:4608
	ds_read_b128 v[4:7], v66
	ds_read_b128 v[18:21], v66 offset:32
	ds_read_b128 v[22:25], v66 offset:4640
	ds_read_b128 v[62:65], v66 offset:4672
	s_waitcnt lgkmcnt(3)
	v_mfma_f32_32x32x16_bf16 v[2:17], v[0:3], v[4:7], 0
	v_lshlrev_b32_e32 v70, 2, v81
	v_cmp_le_i32_e32 vcc, v70, v35
	v_or_b32_e32 v74, 2, v70
	v_or_b32_e32 v75, 3, v70
	v_or_b32_e32 v88, v93, v35
	v_add_u32_e32 v76, 8, v70
	v_lshlrev_b64 v[0:1], 11, v[88:89]
	s_waitcnt lgkmcnt(1)
	v_mfma_f32_32x32x16_bf16 v[2:17], v[22:25], v[18:21], v[2:17]
	ds_read_b128 v[18:21], v66 offset:64
	ds_read_b128 v[22:25], v66 offset:4704
	ds_read_b128 v[66:69], v66 offset:96
	v_lshl_add_u64 v[0:1], s[2:3], 0, v[0:1]
	v_ashrrev_i32_e32 v71, 31, v70
	v_lshl_add_u64 v[0:1], v[0:1], 0, v[90:91]
	v_lshl_add_u64 v[84:85], v[70:71], 1, v[0:1]
	v_add_u32_e32 v0, 16, v70
	s_waitcnt lgkmcnt(2)
	v_mfma_f32_32x32x16_bf16 v[2:17], v[62:65], v[18:21], v[2:17]
	v_add_u32_e32 v18, 9, v70
	v_add_u32_e32 v19, 10, v70
	v_add_u32_e32 v20, 11, v70
	v_lshlrev_b32_e32 v138, 16, v42
	v_and_b32_e32 v139, 0xffff0000, v42
	v_lshlrev_b32_e32 v42, 16, v43
	v_and_b32_e32 v43, 0xffff0000, v43
	s_waitcnt lgkmcnt(0)
	v_mfma_f32_32x32x16_bf16 v[2:17], v[22:25], v[66:69], v[2:17]
	v_lshlrev_b32_e32 v140, 16, v36
	v_and_b32_e32 v141, 0xffff0000, v36
	v_lshlrev_b32_e32 v142, 16, v37
	v_and_b32_e32 v143, 0xffff0000, v37
	v_cvt_pk_bf16_f32 v130, v138, v139
	v_cvt_pk_bf16_f32 v131, v42, v43
	v_cvt_pk_bf16_f32 v132, v140, v141
	s_nop 4
	v_cndmask_b32_e32 v21, 0, v2, vcc
	v_cmp_lt_i32_e32 vcc, v70, v35
	v_cvt_pk_bf16_f32 v133, v142, v143
	v_add_u32_e32 v95, v92, v73
	v_cndmask_b32_e32 v22, 0, v3, vcc
	v_cmp_le_i32_e32 vcc, v74, v35
	v_lshlrev_b32_e32 v74, 3, v81
	v_add_u32_e32 v88, v72, v74
	v_cndmask_b32_e32 v4, 0, v4, vcc
	v_cmp_le_i32_e32 vcc, v75, v35
	v_mad_u32_u24 v144, v35, s16, v95
	v_cvt_pk_bf16_f32 v36, v44, v45
	v_cndmask_b32_e32 v5, 0, v5, vcc
	v_cmp_le_i32_e32 vcc, v76, v35
	v_cvt_pk_bf16_f32 v37, v46, v47
	v_lshlrev_b32_e32 v78, 16, v60
	v_cndmask_b32_e32 v6, 0, v6, vcc
	v_cmp_le_i32_e32 vcc, v18, v35
	v_cvt_pk_bf16_f32 v18, v21, v22
	v_and_b32_e32 v79, 0xffff0000, v60
	v_cndmask_b32_e32 v7, 0, v7, vcc
	v_cmp_le_i32_e32 vcc, v19, v35
	v_cvt_pk_bf16_f32 v19, v4, v5
	v_lshlrev_b32_e32 v82, 16, v61
	v_cndmask_b32_e32 v8, 0, v8, vcc
	v_cmp_le_i32_e32 vcc, v20, v35
	v_cvt_pk_bf16_f32 v20, v6, v7
	v_and_b32_e32 v83, 0xffff0000, v61
	v_cndmask_b32_e32 v9, 0, v9, vcc
	v_cmp_le_i32_e32 vcc, v0, v35
	v_add_u32_e32 v0, 17, v70
	v_cvt_pk_bf16_f32 v21, v8, v9
	v_cndmask_b32_e32 v23, 0, v10, vcc
	v_cmp_le_i32_e32 vcc, v0, v35
	v_add_u32_e32 v0, 18, v70
	v_add_u32_e32 v10, 26, v70
	v_cndmask_b32_e32 v24, 0, v11, vcc
	v_cmp_le_i32_e32 vcc, v0, v35
	v_add_u32_e32 v0, 19, v70
	v_cvt_pk_bf16_f32 v22, v23, v24
	v_cndmask_b32_e32 v25, 0, v12, vcc
	v_cmp_le_i32_e32 vcc, v0, v35
	v_add_u32_e32 v0, 24, v70
	v_lshlrev_b32_e32 v60, 16, v58
	v_cndmask_b32_e32 v68, 0, v13, vcc
	v_cmp_le_i32_e32 vcc, v0, v35
	v_add_u32_e32 v0, 25, v70
	v_add_u32_e32 v70, 27, v70
	v_cndmask_b32_e32 v69, 0, v14, vcc
	v_cmp_le_i32_e32 vcc, v0, v35
	v_mul_u32_u24_e32 v0, 0x50, v35
	v_add3_u32 v81, v92, v74, v0
	v_add_u32_e32 v11, 0x3800, v81
	ds_read2_b64 v[0:3], v11 offset1:2
	ds_read2_b64 v[64:67], v11 offset0:4 offset1:6
	v_cndmask_b32_e32 v71, 0, v15, vcc
	v_cmp_le_i32_e32 vcc, v10, v35
	s_waitcnt lgkmcnt(1)
	v_mfma_f32_32x32x16_bf16 v[0:15], v[0:3], v[18:21], 0
	v_cndmask_b32_e32 v16, 0, v16, vcc
	v_cmp_le_i32_e32 vcc, v70, v35
	v_cvt_pk_bf16_f32 v23, v25, v68
	v_cvt_pk_bf16_f32 v24, v69, v71
	v_cndmask_b32_e32 v17, 0, v17, vcc
	v_cvt_pk_bf16_f32 v25, v16, v17
	ds_read2_b64 v[106:109], v88 offset1:2
	ds_read2_b64 v[110:113], v88 offset0:4 offset1:6
	ds_read2_b64 v[114:117], v88 offset0:8 offset1:10
	ds_read2_b64 v[118:121], v88 offset0:12 offset1:14
	s_waitcnt lgkmcnt(4)
	v_mfma_f32_32x32x16_bf16 v[0:15], v[64:67], v[22:25], v[0:15]
	v_cvt_pk_bf16_f32 v35, v40, v41
	v_and_b32_e32 v61, 0xffff0000, v58
	v_lshlrev_b32_e32 v58, 16, v59
	v_and_b32_e32 v59, 0xffff0000, v59
	v_cvt_pk_bf16_f32 v122, v78, v79
	v_cvt_pk_bf16_f32 v123, v82, v83
	v_cvt_pk_bf16_f32 v124, v60, v61
	s_waitcnt lgkmcnt(3)
	v_mfma_f32_32x32x16_bf16 v[0:15], v[130:133], v[106:109], v[0:15]
	v_lshlrev_b32_e32 v106, 16, v34
	v_and_b32_e32 v107, 0xffff0000, v34
	v_cvt_pk_bf16_f32 v34, v106, v107
	v_cvt_pk_bf16_f32 v125, v58, v59
	v_lshlrev_b32_e32 v86, 16, v56
	v_and_b32_e32 v87, 0xffff0000, v56
	v_lshlrev_b32_e32 v56, 16, v57
	s_waitcnt lgkmcnt(2)
	v_mfma_f32_32x32x16_bf16 v[0:15], v[34:37], v[110:113], v[0:15]
	v_and_b32_e32 v57, 0xffff0000, v57
	v_lshlrev_b32_e32 v102, 16, v54
	v_and_b32_e32 v103, 0xffff0000, v54
	v_lshlrev_b32_e32 v104, 16, v55
	v_and_b32_e32 v105, 0xffff0000, v55
	v_cvt_pk_bf16_f32 v126, v86, v87
	v_cvt_pk_bf16_f32 v127, v56, v57
	s_waitcnt lgkmcnt(1)
	v_mfma_f32_32x32x16_bf16 v[0:15], v[122:125], v[114:117], v[0:15]
	v_cvt_pk_bf16_f32 v128, v102, v103
	v_cvt_pk_bf16_f32 v129, v104, v105
	s_mov_b64 s[2:3], 0x16f00600
	v_lshl_add_u64 v[62:63], v[84:85], 0, s[2:3]
	s_mov_b32 s2, 0x16f00000
	v_lshlrev_b32_e32 v16, 16, v26
	v_and_b32_e32 v17, 0xffff0000, v26
	s_waitcnt lgkmcnt(0)
	v_mfma_f32_32x32x16_bf16 v[0:15], v[126:129], v[118:121], v[0:15]
	v_lshlrev_b32_e32 v64, 16, v27
	v_and_b32_e32 v65, 0xffff0000, v27
	v_lshlrev_b32_e32 v66, 16, v28
	v_and_b32_e32 v67, 0xffff0000, v28
	v_lshlrev_b32_e32 v68, 16, v29
	v_and_b32_e32 v69, 0xffff0000, v29
	v_lshlrev_b32_e32 v70, 16, v30
	s_nop 4
	v_cvt_pk_bf16_f32 v0, v0, v1
	v_cvt_pk_bf16_f32 v1, v2, v3
	v_add_co_u32_e32 v2, vcc, s2, v84
	v_and_b32_e32 v71, 0xffff0000, v30
	s_nop 0
	v_addc_co_u32_e32 v3, vcc, 0, v85, vcc
	global_store_dwordx2 v[2:3], v[0:1], off offset:1536
	v_cvt_pk_bf16_f32 v0, v4, v5
	v_cvt_pk_bf16_f32 v1, v6, v7
	global_store_dwordx2 v[62:63], v[0:1], off offset:16
	v_cvt_pk_bf16_f32 v0, v8, v9
	v_cvt_pk_bf16_f32 v1, v10, v11
	v_lshlrev_b32_e32 v72, 16, v31
	v_and_b32_e32 v73, 0xffff0000, v31
	v_lshlrev_b32_e32 v74, 16, v32
	v_and_b32_e32 v75, 0xffff0000, v32
	v_lshlrev_b32_e32 v76, 16, v33
	v_and_b32_e32 v77, 0xffff0000, v33
	v_lshlrev_b32_e32 v54, 16, v52
	v_and_b32_e32 v55, 0xffff0000, v52
	v_lshlrev_b32_e32 v52, 16, v53
	v_and_b32_e32 v53, 0xffff0000, v53
	v_lshlrev_b32_e32 v130, 16, v50
	v_and_b32_e32 v131, 0xffff0000, v50
	v_lshlrev_b32_e32 v50, 16, v51
	v_and_b32_e32 v51, 0xffff0000, v51
	v_lshlrev_b32_e32 v132, 16, v48
	v_and_b32_e32 v133, 0xffff0000, v48
	v_lshlrev_b32_e32 v48, 16, v49
	v_and_b32_e32 v49, 0xffff0000, v49
	v_lshlrev_b32_e32 v114, 16, v38
	v_and_b32_e32 v115, 0xffff0000, v38
	v_lshlrev_b32_e32 v116, 16, v39
	v_and_b32_e32 v117, 0xffff0000, v39
	global_store_dwordx2 v[62:63], v[0:1], off offset:32
	v_cvt_pk_bf16_f32 v0, v12, v13
	v_cvt_pk_bf16_f32 v1, v14, v15
	v_cvt_pk_bf16_f32 v26, v16, v17
	v_cvt_pk_bf16_f32 v27, v64, v65
	v_cvt_pk_bf16_f32 v28, v66, v67
	v_cvt_pk_bf16_f32 v29, v68, v69
	v_cvt_pk_bf16_f32 v30, v70, v71
	v_cvt_pk_bf16_f32 v31, v72, v73
	v_cvt_pk_bf16_f32 v32, v74, v75
	v_cvt_pk_bf16_f32 v33, v76, v77
	v_cvt_pk_bf16_f32 v134, v54, v55
	v_cvt_pk_bf16_f32 v135, v52, v53
	v_cvt_pk_bf16_f32 v136, v130, v131
	v_cvt_pk_bf16_f32 v137, v50, v51
	v_cvt_pk_bf16_f32 v34, v132, v133
	v_cvt_pk_bf16_f32 v35, v48, v49
	v_cvt_pk_bf16_f32 v36, v114, v115
	v_cvt_pk_bf16_f32 v37, v116, v117
	global_store_dwordx2 v[62:63], v[0:1], off offset:48
	v_add_u32_e32 v38, 0x4000, v81
	ds_read2_b64 v[0:3], v38 offset0:64 offset1:66
	s_waitcnt lgkmcnt(0)
	v_mfma_f32_32x32x16_bf16 v[0:15], v[0:3], v[18:21], 0
	ds_read2_b64 v[18:21], v38 offset0:68 offset1:70
	s_waitcnt lgkmcnt(0)
	v_mfma_f32_32x32x16_bf16 v[0:15], v[18:21], v[22:25], v[0:15]
	ds_read2_b64 v[18:21], v88 offset1:2
	s_waitcnt lgkmcnt(0)
	v_mfma_f32_32x32x16_bf16 v[0:15], v[134:137], v[18:21], v[0:15]
	ds_read2_b64 v[18:21], v88 offset0:4 offset1:6
	s_waitcnt lgkmcnt(0)
	v_mfma_f32_32x32x16_bf16 v[0:15], v[34:37], v[18:21], v[0:15]
	ds_read2_b64 v[18:21], v88 offset0:8 offset1:10
	s_waitcnt lgkmcnt(0)
	v_mfma_f32_32x32x16_bf16 v[0:15], v[26:29], v[18:21], v[0:15]
	ds_read2_b64 v[18:21], v88 offset0:12 offset1:14
	s_waitcnt lgkmcnt(0)
	v_mfma_f32_32x32x16_bf16 v[0:15], v[30:33], v[18:21], v[0:15]
	s_nop 11
	v_cvt_pk_bf16_f32 v0, v0, v1
	v_cvt_pk_bf16_f32 v1, v2, v3
	v_cvt_pk_bf16_f32 v2, v4, v5
	v_cvt_pk_bf16_f32 v3, v6, v7
	v_cvt_pk_bf16_f32 v4, v8, v9
	v_cvt_pk_bf16_f32 v5, v10, v11
	v_cvt_pk_bf16_f32 v6, v12, v13
	v_cvt_pk_bf16_f32 v7, v14, v15
	global_store_dwordx2 v[62:63], v[0:1], off offset:64
	global_store_dwordx2 v[62:63], v[2:3], off offset:80
	global_store_dwordx2 v[62:63], v[4:5], off offset:96
	global_store_dwordx2 v[62:63], v[6:7], off offset:112
	ds_read_b128 v[0:3], v95 offset:19456
	ds_read_b128 v[4:7], v95 offset:19488
	ds_read_b128 v[8:11], v95 offset:19520
	ds_read_b128 v[12:15], v95 offset:19552
	ds_read_b128 v[18:21], v144 offset:9216
	s_waitcnt lgkmcnt(4)
	v_pk_mul_f32 v[34:35], v[2:3], v[42:43]
	ds_read_b128 v[22:25], v144 offset:14336
	s_waitcnt lgkmcnt(3)
	v_pk_mul_f32 v[42:43], v[10:11], v[40:41]
	v_pk_mul_f32 v[40:41], v[8:9], v[106:107]
	ds_read_b128 v[26:29], v144 offset:9248
	ds_read_b128 v[106:109], v144 offset:14368
	ds_read_b128 v[110:113], v144 offset:16896
	v_pk_mul_f32 v[32:33], v[0:1], v[138:139]
	v_pk_mul_f32 v[38:39], v[6:7], v[142:143]
	v_pk_mul_f32 v[36:37], v[4:5], v[140:141]
	s_waitcnt lgkmcnt(5)
	v_pk_mul_f32 v[46:47], v[14:15], v[46:47]
	v_pk_mul_f32 v[44:45], v[12:13], v[44:45]
	v_pk_mul_f32 v[0:1], v[0:1], v[54:55]
	v_pk_mul_f32 v[2:3], v[2:3], v[52:53]
	v_pk_mul_f32 v[4:5], v[4:5], v[130:131]
	v_pk_mul_f32 v[6:7], v[6:7], v[50:51]
	v_pk_mul_f32 v[8:9], v[8:9], v[132:133]
	v_pk_mul_f32 v[10:11], v[10:11], v[48:49]
	v_pk_mul_f32 v[12:13], v[12:13], v[114:115]
	v_pk_mul_f32 v[14:15], v[14:15], v[116:117]
	s_waitcnt lgkmcnt(3)
	v_mfma_f32_32x32x16_bf16 v[32:47], v[18:21], v[22:25], v[32:47]
	ds_read_b128 v[114:117], v144 offset:16928
	s_waitcnt lgkmcnt(1)
	v_mfma_f32_32x32x16_bf16 v[0:15], v[18:21], v[110:113], v[0:15]
	v_mfma_f32_32x32x16_bf16 v[32:47], v[26:29], v[106:109], v[32:47]
	s_waitcnt lgkmcnt(0)
	v_mfma_f32_32x32x16_bf16 v[0:15], v[26:29], v[114:117], v[0:15]
	ds_read_b128 v[18:21], v95 offset:19584
	ds_read_b128 v[26:29], v95 offset:19616
	ds_read_b128 v[118:121], v95 offset:19648
	ds_read_b128 v[122:125], v95 offset:19680
	ds_read_b128 v[126:129], v144 offset:11776
	s_waitcnt lgkmcnt(4)
	v_pk_mul_f32 v[50:51], v[20:21], v[82:83]
	v_pk_mul_f32 v[48:49], v[18:19], v[78:79]
	s_waitcnt lgkmcnt(3)
	v_pk_mul_f32 v[54:55], v[28:29], v[58:59]
	v_pk_mul_f32 v[52:53], v[26:27], v[60:61]
	s_waitcnt lgkmcnt(2)
	v_pk_mul_f32 v[58:59], v[120:121], v[56:57]
	v_pk_mul_f32 v[56:57], v[118:119], v[86:87]
	s_waitcnt lgkmcnt(1)
	v_pk_mul_f32 v[62:63], v[124:125], v[104:105]
	v_pk_mul_f32 v[60:61], v[122:123], v[102:103]
	ds_read_b128 v[82:85], v144 offset:11808
	v_pk_mul_f32 v[16:17], v[18:19], v[16:17]
	s_waitcnt lgkmcnt(1)
	v_mfma_f32_32x32x16_bf16 v[48:63], v[126:129], v[22:25], v[48:63]
	v_mul_f32_e64 v18, v20, v64
	v_mul_f32_e64 v19, v21, v65
	v_mul_f32_e64 v20, v26, v66
	v_mul_f32_e64 v21, v27, v67
	v_mul_f32_e64 v22, v28, v68
	v_mul_f32_e64 v23, v29, v69
	v_pk_mul_f32 v[24:25], v[118:119], v[70:71]
	v_pk_mul_f32 v[26:27], v[120:121], v[72:73]
	v_pk_mul_f32 v[28:29], v[122:123], v[74:75]
	v_pk_mul_f32 v[30:31], v[124:125], v[76:77]
	s_waitcnt lgkmcnt(0)
	s_waitcnt lgkmcnt(0)
	v_mfma_f32_32x32x16_bf16 v[48:63], v[82:85], v[106:109], v[48:63]
	v_mfma_f32_32x32x16_bf16 v[16:31], v[126:129], v[110:113], v[16:31]
	v_mfma_f32_32x32x16_bf16 v[16:31], v[82:85], v[114:117], v[16:31]
	v_mov_b32_e32 v82, v94
	s_mov_b64 s[16:17], s[44:45]
	v_or_b32_e32 v95, 32, v93
	v_and_b32_e32 v124, 31, v82
	v_ashrrev_i32_e32 v125, 5, v82
	v_mov_b64_e32 v[64:65], s[16:17]
	s_movk_i32 s2, 0x1200
	v_mad_i64_i32 v[64:65], s[2:3], v95, s2, v[64:65]
	v_ashrrev_i32_e32 v83, 31, v82
	v_lshl_add_u64 v[64:65], v[64:65], 0, v[90:91]
	v_lshl_add_u64 v[64:65], v[82:83], 1, v[64:65]
	v_lshl_add_u64 v[114:115], v[64:65], 0, s[0:1]
	global_load_ushort v88, v[114:115], off offset:2560
	global_load_ushort v81, v[114:115], off offset:3072
	v_add_co_u32_e32 v112, vcc, s7, v64
	s_mov_b32 s0, 0xb20f000
	s_nop 0
	v_addc_co_u32_e32 v113, vcc, 0, v65, vcc
	global_load_ushort v126, v[112:113], off offset:3584
	v_add_co_u32_e32 v110, vcc, s11, v64
	v_lshl_add_u32 v83, v82, 1, v92
	s_nop 0
	v_addc_co_u32_e32 v111, vcc, 0, v65, vcc
	v_add_co_u32_e32 v108, vcc, s12, v64
	s_waitcnt vmcnt(1)
	v_lshlrev_b32_e32 v81, 16, v81
	v_max_f32_e32 v81, v81, v81
	v_med3_f32 v81, v81, s9, v244
	v_mul_f32_e32 v81, 0xbfb8aa3b, v81
	v_exp_f32_e32 v81, v81
	v_addc_co_u32_e32 v109, vcc, 0, v65, vcc
	v_add_co_u32_e32 v106, vcc, s13, v64
	v_add_f32_e32 v116, 1.0, v81
	v_rcp_f32_e32 v116, v116
	v_addc_co_u32_e32 v107, vcc, 0, v65, vcc
	v_add_co_u32_e32 v104, vcc, s14, v64
	v_fma_f32 v117, v80, v116, v149
	v_max_f32_e32 v183, 0xda24260, v117
	v_mul_f32_e32 v81, v81, v116
	v_rcp_f32_e32 v116, v183
	v_mul_f32_e32 v81, v80, v81
	v_addc_co_u32_e32 v105, vcc, 0, v65, vcc
	v_mul_f32_e32 v81, v81, v116
	v_bfe_u32 v116, v81, 16, 1
	v_add3_u32 v133, v81, v116, s10
	global_load_ushort v81, v[114:115], off offset:2048
	global_load_ushort v127, v[110:111], off offset:512
	global_load_ushort v128, v[108:109], off offset:1536
	global_load_ushort v129, v[106:107], off offset:2560
	global_load_ushort v130, v[104:105], off offset:3584
	v_add_co_u32_e32 v102, vcc, s15, v64
	s_waitcnt vmcnt(4)
	v_lshlrev_b32_e32 v81, 16, v81
	v_addc_co_u32_e32 v103, vcc, 0, v65, vcc
	v_add_co_u32_e32 v86, vcc, s18, v64
	global_load_ushort v131, v[102:103], off offset:512
	s_nop 0
	v_addc_co_u32_e32 v87, vcc, 0, v65, vcc
	v_add_co_u32_e32 v74, vcc, s19, v64
	global_load_ushort v132, v[86:87], off offset:1536
	s_nop 0
	v_addc_co_u32_e32 v75, vcc, 0, v65, vcc
	v_add_co_u32_e32 v78, vcc, s21, v64
	global_load_ushort v134, v[74:75], off offset:2560
	s_nop 0
	v_addc_co_u32_e32 v79, vcc, 0, v65, vcc
	v_add_co_u32_e32 v76, vcc, s30, v64
	global_load_ushort v135, v[78:79], off offset:3584
	s_nop 0
	v_addc_co_u32_e32 v77, vcc, 0, v65, vcc
	v_add_co_u32_e32 v84, vcc, s31, v64
	v_mul_f32_e32 v81, v183, v81
	s_nop 0
	v_addc_co_u32_e32 v85, vcc, 0, v65, vcc
	v_add_co_u32_e32 v66, vcc, s34, v64
	global_load_ushort v137, v[84:85], off offset:1536
	global_load_ushort v136, v[76:77], off offset:512
	v_addc_co_u32_e32 v67, vcc, 0, v65, vcc
	v_add_co_u32_e32 v72, vcc, s35, v64
	global_load_ushort v138, v[66:67], off offset:2560
	s_nop 0
	v_addc_co_u32_e32 v73, vcc, 0, v65, vcc
	v_add_co_u32_e32 v68, vcc, s36, v64
	global_load_ushort v139, v[72:73], off offset:3584
	s_nop 0
	v_addc_co_u32_e32 v69, vcc, 0, v65, vcc
	v_add_co_u32_e32 v70, vcc, s37, v64
	global_load_ushort v140, v[68:69], off offset:512
	s_nop 0
	v_addc_co_u32_e32 v71, vcc, 0, v65, vcc
	v_add_co_u32_e32 v116, vcc, s40, v64
	global_load_ushort v141, v[70:71], off offset:1536
	s_nop 0
	v_addc_co_u32_e32 v117, vcc, 0, v65, vcc
	global_load_ushort v187, v[116:117], off offset:3584
	global_load_ushort v182, v[116:117], off offset:2560
	v_bfe_u32 v114, v81, 16, 1
	v_add3_u32 v188, v81, v114, s10
	v_add_co_u32_e32 v114, vcc, s41, v64
	s_nop 1
	v_addc_co_u32_e32 v115, vcc, 0, v65, vcc
	v_add_co_u32_e32 v118, vcc, s46, v64
	s_nop 1
	v_addc_co_u32_e32 v119, vcc, 0, v65, vcc
	global_load_ushort v180, v[118:119], off offset:-4096
	global_load_ushort v176, v[112:113], off offset:3072
	global_load_ushort v175, v[118:119], off offset:512
	global_load_ushort v170, v[114:115], off offset:3584
	global_load_ushort v181, v[110:111], off offset:1024
	global_load_ushort v178, v[110:111], off
	v_add_co_u32_e32 v120, vcc, s28, v64
	s_nop 1
	v_addc_co_u32_e32 v121, vcc, 0, v65, vcc
	v_add_co_u32_e32 v122, vcc, s29, v64
	global_load_ushort v186, v[120:121], off offset:1536
	global_load_ushort v185, v[120:121], off offset:512
	global_load_ushort v184, v[108:109], off offset:2048
	global_load_ushort v179, v[108:109], off offset:1024
	v_addc_co_u32_e32 v123, vcc, 0, v65, vcc
	v_add_co_u32_e32 v190, vcc, s42, v64
	global_load_ushort v177, v[122:123], off offset:2560
	global_load_ushort v173, v[122:123], off offset:1536
	global_load_ushort v174, v[106:107], off offset:3072
	global_load_ushort v172, v[106:107], off offset:2048
	v_addc_co_u32_e32 v191, vcc, 0, v65, vcc
	v_add_co_u32_e32 v106, vcc, s6, v64
	global_load_ushort v171, v[190:191], off offset:3584
	global_load_ushort v169, v[190:191], off offset:2560
	v_addc_co_u32_e32 v107, vcc, 0, v65, vcc
	v_add_co_u32_e32 v154, vcc, s49, v64
	s_waitcnt vmcnt(4)
	v_lshlrev_b32_e32 v173, 16, v173
	v_addc_co_u32_e32 v155, vcc, 0, v65, vcc
	v_add_co_u32_e32 v192, vcc, s0, v64
	s_mov_b32 s0, 0xb211000
	s_nop 0
	v_addc_co_u32_e32 v193, vcc, 0, v65, vcc
	v_add_co_u32_e32 v194, vcc, s0, v64
	s_mov_b32 s0, 0xb21a000
	s_nop 0
	v_addc_co_u32_e32 v195, vcc, 0, v65, vcc
	v_add_co_u32_e32 v108, vcc, s43, v64
	global_load_ushort v166, v[154:155], off offset:-4096
	global_load_ushort v164, v[104:105], off offset:3072
	global_load_ushort v167, v[154:155], off offset:512
	global_load_ushort v158, v[106:107], off offset:3584
	global_load_ushort v168, v[102:103], off offset:1024
	global_load_ushort v163, v[102:103], off
	v_addc_co_u32_e32 v109, vcc, 0, v65, vcc
	v_add_co_u32_e32 v110, vcc, s47, v64
	global_load_ushort v165, v[192:193], off offset:1536
	global_load_ushort v157, v[192:193], off offset:512
	global_load_ushort v162, v[86:87], off offset:2048
	global_load_ushort v156, v[86:87], off offset:1024
	v_addc_co_u32_e32 v111, vcc, 0, v65, vcc
	v_add_co_u32_e32 v112, vcc, s48, v64
	global_load_ushort v159, v[194:195], off offset:2560
	global_load_ushort v81, v[194:195], off offset:1536
	v_addc_co_u32_e32 v113, vcc, 0, v65, vcc
	v_add_co_u32_e32 v114, vcc, s0, v64
	s_mov_b32 s0, 0xb223000
	s_nop 0
	v_addc_co_u32_e32 v115, vcc, 0, v65, vcc
	v_add_co_u32_e32 v86, vcc, s0, v64
	s_mov_b32 s0, 0xb221000
	s_nop 0
	v_addc_co_u32_e32 v87, vcc, 0, v65, vcc
	v_add_co_u32_e32 v102, vcc, s0, v64
	s_mov_b32 s0, 0xb21f000
	s_nop 0
	v_addc_co_u32_e32 v103, vcc, 0, v65, vcc
	v_add_co_u32_e32 v104, vcc, s0, v64
	global_load_ushort v142, v[86:87], off offset:2048
	global_load_ushort v143, v[102:103], off offset:1024
	global_load_ushort v145, v[68:69], off offset:-4096
	v_addc_co_u32_e32 v105, vcc, 0, v65, vcc
	v_add_co_u32_e32 v106, vcc, s97, v64
	s_nop 1
	v_addc_co_u32_e32 v107, vcc, 0, v65, vcc
	global_load_ushort v146, v[106:107], off offset:3072
	global_load_ushort v147, v[114:115], off offset:2048
	global_load_ushort v150, v[112:113], off offset:1024
	global_load_ushort v151, v[76:77], off offset:-4096
	global_load_ushort v152, v[108:109], off offset:3072
	global_load_ushort v153, v[194:195], off offset:2048
	global_load_ushort v144, v[192:193], off offset:1024
	s_nop 0
	global_load_ushort v154, v[154:155], off
	s_nop 0
	global_load_ushort v155, v[190:191], off offset:3072
	s_nop 0
	global_load_ushort v122, v[122:123], off offset:2048
	s_nop 0
	global_load_ushort v120, v[120:121], off offset:1024
	s_nop 0
	global_load_ushort v118, v[118:119], off
	s_nop 0
	global_load_ushort v121, v[116:117], off offset:3072
	v_lshlrev_b32_e32 v116, 16, v187
	v_max_f32_e32 v116, v116, v116
	v_med3_f32 v116, v116, s9, v244
	v_mul_f32_e32 v116, 0xbfb8aa3b, v116
	v_exp_f32_e32 v116, v116
	ds_write_b16_d16_hi v83, v188
	ds_write_b16_d16_hi v83, v133 offset:4608
	v_add_f32_e32 v117, 1.0, v116
	v_rcp_f32_e32 v117, v117
	s_nop 0
	v_fma_f32 v119, v80, v117, v149
	v_mul_f32_e32 v116, v116, v117
	v_mul_f32_e32 v117, v183, v119
	v_max_f32_e32 v117, 0xda24260, v117
	v_rcp_f32_e32 v119, v117
	v_mul_f32_e32 v116, v80, v116
	v_mul_f32_e32 v116, v116, v119
	v_bfe_u32 v119, v116, 16, 1
	v_add3_u32 v119, v116, v119, s10
	v_lshlrev_b32_e32 v116, 16, v182
	v_mul_f32_e32 v116, v117, v116
	v_bfe_u32 v123, v116, 16, 1
	v_add3_u32 v116, v116, v123, s10
	ds_write_b16_d16_hi v83, v116 offset:144
	ds_write_b16_d16_hi v83, v119 offset:4752
	v_lshlrev_b32_e32 v116, 16, v180
	v_max_f32_e32 v116, v116, v116
	v_med3_f32 v116, v116, s9, v244
	v_mul_f32_e32 v116, 0xbfb8aa3b, v116
	v_exp_f32_e32 v116, v116
	s_nop 0
	v_add_f32_e32 v123, 1.0, v116
	v_rcp_f32_e32 v123, v123
	s_nop 0
	v_fma_f32 v180, v80, v123, v149
	v_mul_f32_e32 v117, v117, v180
	v_max_f32_e32 v117, 0xda24260, v117
	v_mul_f32_e32 v116, v116, v123
	v_rcp_f32_e32 v123, v117
	v_mul_f32_e32 v116, v80, v116
	v_mul_f32_e32 v116, v116, v123
	v_bfe_u32 v123, v116, 16, 1
	v_add3_u32 v116, v116, v123, s10
	v_lshlrev_b32_e32 v123, 16, v176
	v_mul_f32_e32 v123, v117, v123
	v_bfe_u32 v176, v123, 16, 1
	v_add3_u32 v123, v123, v176, s10
	ds_write_b16_d16_hi v83, v123 offset:288
	ds_write_b16_d16_hi v83, v116 offset:4896
	v_lshlrev_b32_e32 v123, 16, v175
	v_max_f32_e32 v123, v123, v123
	v_med3_f32 v123, v123, s9, v244
	v_mul_f32_e32 v123, 0xbfb8aa3b, v123
	v_exp_f32_e32 v123, v123
	s_nop 0
	v_add_f32_e32 v175, 1.0, v123
	v_rcp_f32_e32 v175, v175
	s_nop 0
	v_fma_f32 v176, v80, v175, v149
	v_mul_f32_e32 v117, v117, v176
	v_mul_f32_e32 v123, v123, v175
	v_max_f32_e32 v175, 0xda24260, v117
	v_rcp_f32_e32 v117, v175
	v_mul_f32_e32 v123, v80, v123
	v_mul_f32_e32 v117, v123, v117
	v_bfe_u32 v123, v117, 16, 1
	v_add3_u32 v117, v117, v123, s10
	v_lshlrev_b32_e32 v123, 16, v170
	v_mul_f32_e32 v123, v175, v123
	v_bfe_u32 v170, v123, 16, 1
	v_add3_u32 v123, v123, v170, s10
	ds_write_b16_d16_hi v83, v123 offset:432
	ds_write_b16_d16_hi v83, v117 offset:5040
	v_lshlrev_b32_e32 v123, 16, v181
	v_max_f32_e32 v123, v123, v123
	v_med3_f32 v123, v123, s9, v244
	v_mul_f32_e32 v123, 0xbfb8aa3b, v123
	v_exp_f32_e32 v123, v123
	s_nop 0
	v_add_f32_e32 v170, 1.0, v123
	v_rcp_f32_e32 v170, v170
	s_nop 0
	v_fma_f32 v176, v80, v170, v149
	v_mul_f32_e32 v123, v123, v170
	v_mul_f32_e32 v170, v175, v176
	v_max_f32_e32 v170, 0xda24260, v170
	v_rcp_f32_e32 v175, v170
	v_mul_f32_e32 v123, v80, v123
	v_mul_f32_e32 v123, v123, v175
	v_bfe_u32 v175, v123, 16, 1
	v_add3_u32 v123, v123, v175, s10
	v_lshlrev_b32_e32 v175, 16, v178
	v_mul_f32_e32 v175, v170, v175
	v_bfe_u32 v176, v175, 16, 1
	v_add3_u32 v175, v175, v176, s10
	ds_write_b16_d16_hi v83, v175 offset:576
	ds_write_b16_d16_hi v83, v123 offset:5184
	v_lshlrev_b32_e32 v175, 16, v186
	v_max_f32_e32 v175, v175, v175
	v_med3_f32 v175, v175, s9, v244
	v_mul_f32_e32 v175, 0xbfb8aa3b, v175
	v_exp_f32_e32 v175, v175
	s_nop 0
	v_add_f32_e32 v176, 1.0, v175
	v_rcp_f32_e32 v176, v176
	s_nop 0
	v_fma_f32 v178, v80, v176, v149
	v_mul_f32_e32 v170, v170, v178
	v_max_f32_e32 v170, 0xda24260, v170
	v_mul_f32_e32 v175, v175, v176
	v_rcp_f32_e32 v176, v170
	v_mul_f32_e32 v175, v80, v175
	v_mul_f32_e32 v175, v175, v176
	v_bfe_u32 v176, v175, 16, 1
	v_add3_u32 v175, v175, v176, s10
	v_lshlrev_b32_e32 v176, 16, v185
	v_mul_f32_e32 v176, v170, v176
	v_bfe_u32 v178, v176, 16, 1
	v_add3_u32 v176, v176, v178, s10
	ds_write_b16_d16_hi v83, v176 offset:720
	ds_write_b16_d16_hi v83, v175 offset:5328
	v_lshlrev_b32_e32 v176, 16, v184
	v_max_f32_e32 v176, v176, v176
	v_med3_f32 v176, v176, s9, v244
	v_mul_f32_e32 v176, 0xbfb8aa3b, v176
	v_exp_f32_e32 v176, v176
	s_nop 0
	v_add_f32_e32 v178, 1.0, v176
	v_rcp_f32_e32 v178, v178
	s_nop 0
	v_fma_f32 v180, v80, v178, v149
	v_mul_f32_e32 v170, v170, v180
	v_mul_f32_e32 v176, v176, v178
	v_max_f32_e32 v178, 0xda24260, v170
	v_rcp_f32_e32 v170, v178
	v_mul_f32_e32 v176, v80, v176
	v_mul_f32_e32 v170, v176, v170
	v_bfe_u32 v176, v170, 16, 1
	v_add3_u32 v170, v170, v176, s10
	v_lshlrev_b32_e32 v176, 16, v179
	v_mul_f32_e32 v176, v178, v176
	v_bfe_u32 v179, v176, 16, 1
	v_add3_u32 v176, v176, v179, s10
	ds_write_b16_d16_hi v83, v176 offset:864
	ds_write_b16_d16_hi v83, v170 offset:5472
	v_lshlrev_b32_e32 v176, 16, v177
	v_max_f32_e32 v176, v176, v176
	v_med3_f32 v176, v176, s9, v244
	v_mul_f32_e32 v176, 0xbfb8aa3b, v176
	v_exp_f32_e32 v176, v176
	s_nop 0
	v_add_f32_e32 v177, 1.0, v176
	v_rcp_f32_e32 v177, v177
	s_nop 0
	v_fma_f32 v179, v80, v177, v149
	v_mul_f32_e32 v176, v176, v177
	v_mul_f32_e32 v177, v178, v179
	v_max_f32_e32 v177, 0xda24260, v177
	v_rcp_f32_e32 v178, v177
	v_mul_f32_e32 v176, v80, v176
	v_mul_f32_e32 v173, v177, v173
	v_mul_f32_e32 v176, v176, v178
	v_bfe_u32 v178, v176, 16, 1
	v_add3_u32 v176, v176, v178, s10
	v_bfe_u32 v178, v173, 16, 1
	v_add3_u32 v173, v173, v178, s10
	ds_write_b16_d16_hi v83, v173 offset:1008
	ds_write_b16_d16_hi v83, v176 offset:5616
	s_waitcnt vmcnt(31)
	v_lshlrev_b32_e32 v173, 16, v174
	v_max_f32_e32 v173, v173, v173
	v_med3_f32 v173, v173, s9, v244
	v_mul_f32_e32 v173, 0xbfb8aa3b, v173
	v_exp_f32_e32 v173, v173
	s_waitcnt vmcnt(29)
	v_lshlrev_b32_e32 v171, 16, v171
	v_max_f32_e32 v171, v171, v171
	v_med3_f32 v171, v171, s9, v244
	v_add_f32_e32 v174, 1.0, v173
	v_rcp_f32_e32 v174, v174
	v_mul_f32_e32 v171, 0xbfb8aa3b, v171
	v_exp_f32_e32 v178, v171
	v_lshlrev_b32_e32 v172, 16, v172
	v_fma_f32 v171, v80, v174, v149
	v_mul_f32_e32 v171, v177, v171
	v_max_f32_e32 v177, 0xda24260, v171
	v_rcp_f32_e32 v171, v177
	v_mul_f32_e32 v173, v173, v174
	v_mul_f32_e32 v173, v80, v173
	v_mul_f32_e32 v172, v177, v172
	v_mul_f32_e32 v171, v173, v171
	v_bfe_u32 v173, v171, 16, 1
	v_add3_u32 v171, v171, v173, s10
	v_add_f32_e32 v173, 1.0, v178
	v_rcp_f32_e32 v173, v173
	v_bfe_u32 v174, v172, 16, 1
	v_add3_u32 v172, v172, v174, s10
	ds_write_b16_d16_hi v83, v172 offset:1152
	v_fma_f32 v172, v80, v173, v149
	v_mul_f32_e32 v172, v177, v172
	v_max_f32_e32 v174, 0xda24260, v172
	v_rcp_f32_e32 v172, v174
	v_mul_f32_e32 v173, v178, v173
	v_mul_f32_e32 v173, v80, v173
	s_waitcnt vmcnt(28)
	v_lshlrev_b32_e32 v169, 16, v169
	v_mul_f32_e32 v172, v173, v172
	v_bfe_u32 v173, v172, 16, 1
	v_mul_f32_e32 v169, v174, v169
	ds_write_b16_d16_hi v83, v171 offset:5760
	v_add3_u32 v172, v172, v173, s10
	v_bfe_u32 v173, v169, 16, 1
	v_add3_u32 v169, v169, v173, s10
	global_load_ushort v173, v[74:75], off offset:3072
	global_load_ushort v177, v[108:109], off offset:2560
	s_nop 0
	global_load_ushort v78, v[78:79], off offset:3072
	s_nop 0
	global_load_ushort v79, v[76:77], off offset:1024
	global_load_ushort v178, v[84:85], off offset:2048
	s_nop 0
	global_load_ushort v85, v[84:85], off offset:1024
	s_nop 0
	global_load_ushort v76, v[76:77], off
	s_nop 0
	global_load_ushort v77, v[74:75], off offset:2048
	s_waitcnt vmcnt(35)
	v_lshlrev_b32_e32 v74, 16, v166
	v_max_f32_e32 v74, v74, v74
	v_med3_f32 v74, v74, s9, v244
	v_mul_f32_e32 v74, 0xbfb8aa3b, v74
	v_exp_f32_e32 v84, v74
	v_add_co_u32_e32 v74, vcc, s5, v64
	s_waitcnt vmcnt(32)
	v_lshlrev_b32_e32 v158, 16, v158
	v_addc_co_u32_e32 v75, vcc, 0, v65, vcc
	v_add_f32_e32 v166, 1.0, v84
	global_load_ushort v108, v[108:109], off offset:3584
	s_nop 0
	global_load_ushort v109, v[74:75], off
	s_nop 0
	global_load_ushort v110, v[110:111], off offset:512
	s_nop 0
	global_load_ushort v74, v[74:75], off offset:3584
	s_nop 0
	global_load_ushort v75, v[112:113], off offset:1536
	global_load_ushort v111, v[114:115], off offset:2560
	s_nop 0
	global_load_ushort v114, v[114:115], off offset:1536
	s_nop 0
	global_load_ushort v112, v[112:113], off offset:512
	v_rcp_f32_e32 v166, v166
	s_waitcnt vmcnt(37)
	v_lshlrev_b32_e32 v165, 16, v165
	v_max_f32_e32 v165, v165, v165
	v_med3_f32 v165, v165, s9, v244
	v_fma_f32 v113, v80, v166, v149
	v_mul_f32_e32 v113, v174, v113
	v_mul_f32_e32 v84, v84, v166
	v_lshlrev_b32_e32 v166, 16, v167
	v_max_f32_e32 v113, 0xda24260, v113
	v_max_f32_e32 v166, v166, v166
	v_rcp_f32_e32 v115, v113
	v_med3_f32 v166, v166, s9, v244
	v_mul_f32_e32 v166, 0xbfb8aa3b, v166
	v_exp_f32_e32 v166, v166
	v_mul_f32_e32 v84, v80, v84
	v_mul_f32_e32 v84, v84, v115
	v_bfe_u32 v115, v84, 16, 1
	v_add3_u32 v84, v84, v115, s10
	v_lshlrev_b32_e32 v115, 16, v164
	v_add_f32_e32 v164, 1.0, v166
	v_rcp_f32_e32 v164, v164
	v_mul_f32_e32 v115, v113, v115
	v_bfe_u32 v167, v115, 16, 1
	v_add3_u32 v115, v115, v167, s10
	ds_write_b16_d16_hi v83, v115 offset:1440
	v_fma_f32 v115, v80, v164, v149
	v_mul_f32_e32 v113, v113, v115
	v_mul_f32_e32 v164, v166, v164
	v_lshlrev_b32_e32 v166, 16, v168
	v_max_f32_e32 v113, 0xda24260, v113
	v_max_f32_e32 v166, v166, v166
	v_rcp_f32_e32 v115, v113
	v_med3_f32 v166, v166, s9, v244
	v_mul_f32_e32 v166, 0xbfb8aa3b, v166
	v_exp_f32_e32 v166, v166
	v_mul_f32_e32 v164, v80, v164
	v_mul_f32_e32 v115, v164, v115
	v_bfe_u32 v164, v115, 16, 1
	v_add3_u32 v115, v115, v164, s10
	v_add_f32_e32 v164, 1.0, v166
	v_rcp_f32_e32 v164, v164
	v_mul_f32_e32 v158, v113, v158
	v_bfe_u32 v167, v158, 16, 1
	v_add3_u32 v158, v158, v167, s10
	ds_write_b16_d16_hi v83, v158 offset:1584
	v_fma_f32 v158, v80, v164, v149
	v_mul_f32_e32 v113, v113, v158
	v_max_f32_e32 v113, 0xda24260, v113
	v_rcp_f32_e32 v158, v113
	v_mul_f32_e32 v165, 0xbfb8aa3b, v165
	v_mul_f32_e32 v164, v166, v164
	v_exp_f32_e32 v165, v165
	v_mul_f32_e32 v164, v80, v164
	v_mul_f32_e32 v158, v164, v158
	v_bfe_u32 v164, v158, 16, 1
	v_add3_u32 v158, v158, v164, s10
	v_add_f32_e32 v164, 1.0, v165
	v_lshlrev_b32_e32 v163, 16, v163
	v_rcp_f32_e32 v164, v164
	v_mul_f32_e32 v163, v113, v163
	v_bfe_u32 v166, v163, 16, 1
	v_add3_u32 v163, v163, v166, s10
	ds_write_b16_d16_hi v83, v163 offset:1728
	v_fma_f32 v163, v80, v164, v149
	v_mul_f32_e32 v113, v113, v163
	s_waitcnt vmcnt(35)
	v_lshlrev_b32_e32 v162, 16, v162
	v_max_f32_e32 v113, 0xda24260, v113
	v_max_f32_e32 v162, v162, v162
	v_rcp_f32_e32 v163, v113
	v_med3_f32 v162, v162, s9, v244
	v_mul_f32_e32 v162, 0xbfb8aa3b, v162
	v_mul_f32_e32 v164, v165, v164
	v_exp_f32_e32 v162, v162
	v_mul_f32_e32 v164, v80, v164
	v_mul_f32_e32 v163, v164, v163
	v_bfe_u32 v164, v163, 16, 1
	v_add3_u32 v163, v163, v164, s10
	v_add_f32_e32 v164, 1.0, v162
	v_lshlrev_b32_e32 v157, 16, v157
	v_rcp_f32_e32 v164, v164
	v_mul_f32_e32 v157, v113, v157
	v_bfe_u32 v165, v157, 16, 1
	v_add3_u32 v157, v157, v165, s10
	ds_write_b16_d16_hi v83, v157 offset:1872
	v_fma_f32 v157, v80, v164, v149
	v_mul_f32_e32 v113, v113, v157
	s_waitcnt vmcnt(33)
	v_lshlrev_b32_e32 v159, 16, v159
	v_max_f32_e32 v113, 0xda24260, v113
	v_max_f32_e32 v159, v159, v159
	v_rcp_f32_e32 v157, v113
	v_med3_f32 v159, v159, s9, v244
	v_mul_f32_e32 v159, 0xbfb8aa3b, v159
	v_mul_f32_e32 v162, v162, v164
	v_exp_f32_e32 v159, v159
	v_mul_f32_e32 v162, v80, v162
	v_mul_f32_e32 v157, v162, v157
	v_bfe_u32 v162, v157, 16, 1
	v_add3_u32 v157, v157, v162, s10
	v_add_f32_e32 v162, 1.0, v159
	v_lshlrev_b32_e32 v156, 16, v156
	v_rcp_f32_e32 v162, v162
	v_mul_f32_e32 v156, v113, v156
	v_bfe_u32 v164, v156, 16, 1
	v_add3_u32 v156, v156, v164, s10
	ds_write_b16_d16_hi v83, v156 offset:2016
	v_fma_f32 v156, v80, v162, v149
	v_mul_f32_e32 v113, v113, v156
	v_max_f32_e32 v113, 0xda24260, v113
	v_rcp_f32_e32 v156, v113
	v_mul_f32_e32 v159, v159, v162
	v_mul_f32_e32 v159, v80, v159
	s_waitcnt vmcnt(32)
	v_lshlrev_b32_e32 v81, 16, v81
	v_mul_f32_e32 v156, v159, v156
	v_bfe_u32 v159, v156, 16, 1
	v_mul_f32_e32 v81, v113, v81
	v_add3_u32 v159, v156, v159, s10
	v_bfe_u32 v156, v81, 16, 1
	v_add3_u32 v81, v81, v156, s10
	ds_write_b16_d16_hi v83, v169 offset:1296
	ds_write_b16_d16_hi v83, v172 offset:5904
	ds_write_b16_d16_hi v83, v84 offset:6048
	ds_write_b16_d16_hi v83, v115 offset:6192
	ds_write_b16_d16_hi v83, v158 offset:6336
	ds_write_b16_d16_hi v83, v163 offset:6480
	ds_write_b16_d16_hi v83, v157 offset:6624
	ds_write_b16_d16_hi v83, v81 offset:2160
	ds_write_b16_d16_hi v83, v159 offset:6768
	s_waitcnt vmcnt(15)
	v_lshlrev_b32_e32 v81, 16, v173
	v_max_f32_e32 v81, v81, v81
	v_med3_f32 v81, v81, s9, v244
	v_mul_f32_e32 v81, 0xbfb8aa3b, v81
	v_exp_f32_e32 v81, v81
	s_waitcnt vmcnt(7)
	v_lshlrev_b32_e32 v108, 16, v108
	v_max_f32_e32 v108, v108, v108
	v_med3_f32 v108, v108, s9, v244
	v_add_f32_e32 v156, 1.0, v81
	v_rcp_f32_e32 v156, v156
	v_mul_f32_e32 v108, 0xbfb8aa3b, v108
	v_exp_f32_e32 v108, v108
	v_lshlrev_b32_e32 v77, 16, v77
	v_fma_f32 v162, v80, v156, v149
	v_mul_f32_e32 v113, v113, v162
	v_max_f32_e32 v113, 0xda24260, v113
	v_rcp_f32_e32 v162, v113
	v_mul_f32_e32 v81, v81, v156
	v_mul_f32_e32 v81, v80, v81
	v_mul_f32_e32 v77, v113, v77
	v_mul_f32_e32 v81, v81, v162
	v_bfe_u32 v156, v81, 16, 1
	v_add3_u32 v156, v81, v156, s10
	v_add_f32_e32 v81, 1.0, v108
	v_rcp_f32_e32 v81, v81
	v_bfe_u32 v162, v77, 16, 1
	v_add3_u32 v77, v77, v162, s10
	ds_write_b16_d16_hi v83, v77 offset:2304
	v_fma_f32 v77, v80, v81, v149
	ds_write_b16_d16_hi v83, v156 offset:6912
	v_mul_f32_e32 v77, v113, v77
	global_load_ushort v162, v[66:67], off offset:3072
	global_load_ushort v164, v[72:73], off offset:3072
	global_load_ushort v165, v[68:69], off offset:1024
	global_load_ushort v166, v[70:71], off offset:2048
	global_load_ushort v167, v[86:87], off offset:1536
	global_load_ushort v168, v[70:71], off offset:1024
	global_load_ushort v169, v[68:69], off
	global_load_ushort v173, v[66:67], off offset:2048
	s_waitcnt vmcnt(14)
	v_lshlrev_b32_e32 v66, 16, v109
	v_max_f32_e32 v77, 0xda24260, v77
	v_max_f32_e32 v66, v66, v66
	v_rcp_f32_e32 v113, v77
	v_med3_f32 v66, v66, s9, v244
	v_mul_f32_e32 v66, 0xbfb8aa3b, v66
	v_mul_f32_e32 v81, v108, v81
	v_exp_f32_e32 v66, v66
	v_mul_f32_e32 v81, v80, v81
	v_mul_f32_e32 v81, v81, v113
	v_bfe_u32 v108, v81, 16, 1
	v_add_co_u32_e32 v64, vcc, s4, v64
	v_add3_u32 v108, v81, v108, s10
	v_lshlrev_b32_e32 v81, 16, v177
	v_addc_co_u32_e32 v65, vcc, 0, v65, vcc
	v_add_f32_e32 v67, 1.0, v66
	global_load_ushort v174, v[106:107], off offset:3584
	global_load_ushort v177, v[64:65], off
	global_load_ushort v179, v[64:65], off offset:3584
	s_nop 0
	global_load_ushort v106, v[106:107], off offset:2560
	s_nop 0
	global_load_ushort v104, v[104:105], off offset:512
	s_nop 0
	global_load_ushort v180, v[102:103], off offset:1536
	s_nop 0
	global_load_ushort v102, v[102:103], off offset:512
	s_nop 0
	global_load_ushort v86, v[86:87], off offset:2560
	v_rcp_f32_e32 v67, v67
	v_mul_f32_e32 v81, v77, v81
	v_bfe_u32 v113, v81, 16, 1
	v_add3_u32 v81, v81, v113, s10
	v_fma_f32 v64, v80, v67, v149
	v_mul_f32_e32 v64, v77, v64
	v_mul_f32_e32 v66, v66, v67
	s_waitcnt vmcnt(21)
	v_lshlrev_b32_e32 v67, 16, v110
	v_max_f32_e32 v64, 0xda24260, v64
	v_max_f32_e32 v67, v67, v67
	v_rcp_f32_e32 v65, v64
	v_med3_f32 v67, v67, s9, v244
	v_mul_f32_e32 v67, 0xbfb8aa3b, v67
	v_exp_f32_e32 v67, v67
	v_mul_f32_e32 v66, v80, v66
	v_mul_f32_e32 v65, v66, v65
	v_bfe_u32 v66, v65, 16, 1
	v_add3_u32 v181, v65, v66, s10
	v_add_f32_e32 v66, 1.0, v67
	v_lshlrev_b32_e32 v65, 16, v78
	v_rcp_f32_e32 v66, v66
	v_mul_f32_e32 v65, v64, v65
	v_bfe_u32 v68, v65, 16, 1
	v_add3_u32 v65, v65, v68, s10
	ds_write_b16_d16_hi v83, v65 offset:2592
	v_fma_f32 v65, v80, v66, v149
	v_mul_f32_e32 v66, v67, v66
	v_lshlrev_b32_e32 v67, 16, v79
	v_mul_f32_e32 v64, v64, v65
	v_max_f32_e32 v67, v67, v67
	v_max_f32_e32 v64, 0xda24260, v64
	v_med3_f32 v67, v67, s9, v244
	v_rcp_f32_e32 v65, v64
	v_mul_f32_e32 v67, 0xbfb8aa3b, v67
	v_exp_f32_e32 v67, v67
	v_mul_f32_e32 v66, v80, v66
	v_mul_f32_e32 v65, v66, v65
	v_bfe_u32 v66, v65, 16, 1
	v_add_f32_e32 v68, 1.0, v67
	v_add3_u32 v65, v65, v66, s10
	s_waitcnt vmcnt(20)
	v_lshlrev_b32_e32 v66, 16, v74
	v_rcp_f32_e32 v68, v68
	v_mul_f32_e32 v66, v64, v66
	v_bfe_u32 v69, v66, 16, 1
	v_add3_u32 v66, v66, v69, s10
	ds_write_b16_d16_hi v83, v66 offset:2736
	v_fma_f32 v66, v80, v68, v149
	v_mul_f32_e32 v64, v64, v66
	v_mul_f32_e32 v67, v67, v68
	s_waitcnt vmcnt(19)
	v_lshlrev_b32_e32 v68, 16, v75
	v_max_f32_e32 v64, 0xda24260, v64
	v_max_f32_e32 v68, v68, v68
	v_rcp_f32_e32 v66, v64
	v_med3_f32 v68, v68, s9, v244
	v_mul_f32_e32 v68, 0xbfb8aa3b, v68
	v_exp_f32_e32 v68, v68
	v_mul_f32_e32 v67, v80, v67
	v_mul_f32_e32 v66, v67, v66
	v_bfe_u32 v67, v66, 16, 1
	v_add3_u32 v182, v66, v67, s10
	v_add_f32_e32 v67, 1.0, v68
	v_lshlrev_b32_e32 v66, 16, v76
	v_rcp_f32_e32 v67, v67
	v_mul_f32_e32 v66, v64, v66
	v_bfe_u32 v69, v66, 16, 1
	v_add3_u32 v66, v66, v69, s10
	ds_write_b16_d16_hi v83, v66 offset:2880
	v_fma_f32 v66, v80, v67, v149
	v_mul_f32_e32 v67, v68, v67
	v_lshlrev_b32_e32 v68, 16, v178
	v_mul_f32_e32 v64, v64, v66
	v_max_f32_e32 v68, v68, v68
	v_max_f32_e32 v64, 0xda24260, v64
	v_med3_f32 v68, v68, s9, v244
	v_rcp_f32_e32 v66, v64
	v_mul_f32_e32 v68, 0xbfb8aa3b, v68
	v_exp_f32_e32 v68, v68
	v_mul_f32_e32 v67, v80, v67
	v_mul_f32_e32 v66, v67, v66
	v_bfe_u32 v67, v66, 16, 1
	v_add_f32_e32 v69, 1.0, v68
	v_add3_u32 v66, v66, v67, s10
	s_waitcnt vmcnt(16)
	v_lshlrev_b32_e32 v67, 16, v112
	v_rcp_f32_e32 v69, v69
	v_mul_f32_e32 v67, v64, v67
	v_bfe_u32 v70, v67, 16, 1
	v_add3_u32 v67, v67, v70, s10
	ds_write_b16_d16_hi v83, v67 offset:3024
	v_fma_f32 v67, v80, v69, v149
	v_mul_f32_e32 v64, v64, v67
	v_mul_f32_e32 v68, v68, v69
	v_lshlrev_b32_e32 v69, 16, v111
	v_max_f32_e32 v64, 0xda24260, v64
	v_max_f32_e32 v69, v69, v69
	v_rcp_f32_e32 v67, v64
	v_med3_f32 v69, v69, s9, v244
	v_mul_f32_e32 v69, 0xbfb8aa3b, v69
	v_exp_f32_e32 v69, v69
	v_mul_f32_e32 v68, v80, v68
	v_mul_f32_e32 v67, v68, v67
	v_bfe_u32 v68, v67, 16, 1
	v_add3_u32 v178, v67, v68, s10
	v_add_f32_e32 v68, 1.0, v69
	v_lshlrev_b32_e32 v67, 16, v85
	v_rcp_f32_e32 v68, v68
	v_mul_f32_e32 v67, v64, v67
	v_bfe_u32 v70, v67, 16, 1
	v_add3_u32 v67, v67, v70, s10
	ds_write_b16_d16_hi v83, v67 offset:3168
	v_fma_f32 v67, v80, v68, v149
	v_mul_f32_e32 v64, v64, v67
	v_max_f32_e32 v76, 0xda24260, v64
	v_rcp_f32_e32 v64, v76
	v_mul_f32_e32 v67, v69, v68
	v_mul_f32_e32 v67, v80, v67
	ds_write_b16_d16_hi v83, v81 offset:2448
	v_mul_f32_e32 v64, v67, v64
	v_bfe_u32 v67, v64, 16, 1
	v_add3_u32 v64, v64, v67, s10
	v_lshlrev_b32_e32 v67, 16, v114
	v_mul_f32_e32 v67, v76, v67
	v_bfe_u32 v68, v67, 16, 1
	v_add3_u32 v67, v67, v68, s10
	ds_write_b16_d16_hi v83, v108 offset:7056
	ds_write_b16_d16_hi v83, v181 offset:7200
	ds_write_b16_d16_hi v83, v65 offset:7344
	ds_write_b16_d16_hi v83, v182 offset:7488
	ds_write_b16_d16_hi v83, v66 offset:7632
	ds_write_b16_d16_hi v83, v178 offset:7776
	ds_write_b16_d16_hi v83, v67 offset:3312
	ds_write_b16_d16_hi v83, v64 offset:7920
	s_waitcnt vmcnt(15)
	v_lshlrev_b32_e32 v72, 16, v162
	v_max_f32_e32 v72, v72, v72
	v_med3_f32 v72, v72, s9, v244
	v_mul_f32_e32 v72, 0xbfb8aa3b, v72
	v_and_b32_e32 v103, 0xffff0000, v108
	v_exp_f32_e32 v108, v72
	v_lshl_or_b32 v78, v120, 16, v127
	s_waitcnt vmcnt(4)
	v_lshlrev_b32_e32 v106, 16, v106
	s_waitcnt vmcnt(3)
	v_lshlrev_b32_e32 v104, 16, v104
	v_add_f32_e32 v77, 1.0, v108
	v_rcp_f32_e32 v110, v77
	v_max_f32_e32 v104, v104, v104
	v_med3_f32 v104, v104, s9, v244
	v_mul_f32_e32 v104, 0xbfb8aa3b, v104
	v_fma_f32 v112, v80, v110, v149
	v_mul_f32_e32 v76, v76, v112
	v_max_f32_e32 v112, 0xda24260, v76
	v_lshl_or_b32 v76, v121, 16, v88
	v_mul_f32_e32 v88, v108, v110
	v_lshlrev_b32_e32 v110, 16, v174
	v_max_f32_e32 v110, v110, v110
	v_rcp_f32_e32 v114, v112
	v_med3_f32 v110, v110, s9, v244
	v_mul_f32_e32 v110, 0xbfb8aa3b, v110
	v_exp_f32_e32 v110, v110
	v_mul_f32_e32 v88, v80, v88
	v_mul_f32_e32 v88, v88, v114
	v_bfe_u32 v108, v88, 16, 1
	v_add3_u32 v120, v88, v108, s10
	v_add_f32_e32 v108, 1.0, v110
	v_lshlrev_b32_e32 v88, 16, v173
	v_rcp_f32_e32 v108, v108
	v_mul_f32_e32 v88, v112, v88
	v_bfe_u32 v114, v88, 16, 1
	v_add3_u32 v88, v88, v114, s10
	ds_write_b16_d16_hi v83, v88 offset:3456
	v_fma_f32 v88, v80, v108, v149
	v_mul_f32_e32 v88, v112, v88
	v_max_f32_e32 v88, 0xda24260, v88
	v_rcp_f32_e32 v112, v88
	v_mul_f32_e32 v108, v110, v108
	v_mul_f32_e32 v108, v80, v108
	v_mul_f32_e32 v106, v88, v106
	v_mul_f32_e32 v108, v108, v112
	v_bfe_u32 v110, v108, 16, 1
	v_add3_u32 v108, v108, v110, s10
	v_lshlrev_b32_e32 v110, 16, v177
	v_max_f32_e32 v110, v110, v110
	v_med3_f32 v110, v110, s9, v244
	v_mul_f32_e32 v110, 0xbfb8aa3b, v110
	v_exp_f32_e32 v110, v110
	v_bfe_u32 v114, v106, 16, 1
	v_add3_u32 v106, v106, v114, s10
	ds_write_b16_d16_hi v83, v106 offset:3600
	v_add_f32_e32 v112, 1.0, v110
	v_rcp_f32_e32 v112, v112
	v_and_b32_e32 v121, 0xffff0000, v108
	ds_write_b16_d16_hi v83, v108 offset:8208
	v_exp_f32_e32 v104, v104
	v_fma_f32 v106, v80, v112, v149
	v_mul_f32_e32 v88, v88, v106
	v_max_f32_e32 v88, 0xda24260, v88
	v_rcp_f32_e32 v106, v88
	v_mul_f32_e32 v108, v110, v112
	v_mul_f32_e32 v108, v80, v108
	v_lshl_or_b32 v79, v122, 16, v128
	v_mul_f32_e32 v106, v108, v106
	v_bfe_u32 v108, v106, 16, 1
	v_add3_u32 v122, v106, v108, s10
	v_add_f32_e32 v108, 1.0, v104
	v_lshlrev_b32_e32 v106, 16, v164
	v_rcp_f32_e32 v108, v108
	v_mul_f32_e32 v106, v88, v106
	v_bfe_u32 v110, v106, 16, 1
	v_add3_u32 v106, v106, v110, s10
	ds_write_b16_d16_hi v83, v106 offset:3744
	v_fma_f32 v106, v80, v108, v149
	v_mul_f32_e32 v88, v88, v106
	v_max_f32_e32 v88, 0xda24260, v88
	v_rcp_f32_e32 v106, v88
	v_mul_f32_e32 v104, v104, v108
	v_mul_f32_e32 v104, v80, v104
	v_lshlrev_b32_e32 v108, 16, v179
	v_mul_f32_e32 v104, v104, v106
	v_bfe_u32 v106, v104, 16, 1
	v_add3_u32 v104, v104, v106, s10
	v_lshlrev_b32_e32 v106, 16, v165
	v_max_f32_e32 v106, v106, v106
	v_med3_f32 v106, v106, s9, v244
	v_mul_f32_e32 v106, 0xbfb8aa3b, v106
	v_exp_f32_e32 v106, v106
	v_mul_f32_e32 v108, v88, v108
	v_bfe_u32 v112, v108, 16, 1
	v_add3_u32 v108, v108, v112, s10
	v_add_f32_e32 v110, 1.0, v106
	v_rcp_f32_e32 v110, v110
	ds_write_b16_d16_hi v83, v108 offset:3888
	v_lshl_or_b32 v74, v144, 16, v131
	v_and_b32_e32 v131, 0xffff0000, v104
	v_fma_f32 v108, v80, v110, v149
	v_mul_f32_e32 v88, v88, v108
	v_max_f32_e32 v88, 0xda24260, v88
	v_rcp_f32_e32 v108, v88
	ds_write_b16_d16_hi v83, v104 offset:8496
	v_mul_f32_e32 v104, v106, v110
	v_mul_f32_e32 v104, v80, v104
	v_mul_f32_e32 v104, v104, v108
	s_waitcnt vmcnt(2)
	v_lshlrev_b32_e32 v108, 16, v180
	v_max_f32_e32 v108, v108, v108
	v_med3_f32 v108, v108, s9, v244
	v_mul_f32_e32 v108, 0xbfb8aa3b, v108
	v_exp_f32_e32 v108, v108
	v_bfe_u32 v106, v104, 16, 1
	v_lshl_or_b32 v75, v153, 16, v132
	v_add3_u32 v132, v104, v106, s10
	v_add_f32_e32 v106, 1.0, v108
	v_lshlrev_b32_e32 v104, 16, v169
	v_rcp_f32_e32 v106, v106
	v_mul_f32_e32 v104, v88, v104
	v_bfe_u32 v110, v104, 16, 1
	v_add3_u32 v104, v104, v110, s10
	ds_write_b16_d16_hi v83, v104 offset:4032
	v_fma_f32 v104, v80, v106, v149
	v_mul_f32_e32 v88, v88, v104
	v_max_f32_e32 v88, 0xda24260, v88
	v_rcp_f32_e32 v104, v88
	v_mul_f32_e32 v106, v108, v106
	v_mul_f32_e32 v106, v80, v106
	s_waitcnt vmcnt(1)
	v_lshlrev_b32_e32 v102, 16, v102
	v_mul_f32_e32 v104, v106, v104
	v_bfe_u32 v106, v104, 16, 1
	v_add3_u32 v104, v104, v106, s10
	v_lshlrev_b32_e32 v106, 16, v166
	v_max_f32_e32 v106, v106, v106
	v_med3_f32 v106, v106, s9, v244
	v_mul_f32_e32 v106, 0xbfb8aa3b, v106
	v_exp_f32_e32 v106, v106
	v_mul_f32_e32 v102, v88, v102
	v_bfe_u32 v110, v102, 16, 1
	v_add3_u32 v102, v102, v110, s10
	v_add_f32_e32 v108, 1.0, v106
	v_rcp_f32_e32 v108, v108
	ds_write_b16_d16_hi v83, v102 offset:4176
	s_waitcnt vmcnt(0)
	v_lshlrev_b32_e32 v86, 16, v86
	v_max_f32_e32 v86, v86, v86
	v_fma_f32 v102, v80, v108, v149
	v_mul_f32_e32 v88, v88, v102
	v_max_f32_e32 v88, 0xda24260, v88
	v_rcp_f32_e32 v102, v88
	v_med3_f32 v86, v86, s9, v244
	v_mul_f32_e32 v86, 0xbfb8aa3b, v86
	v_lshl_or_b32 v69, v151, 16, v135
	v_and_b32_e32 v135, 0xffff0000, v104
	ds_write_b16_d16_hi v83, v104 offset:8784
	v_mul_f32_e32 v104, v106, v108
	v_exp_f32_e32 v86, v86
	v_mul_f32_e32 v104, v80, v104
	v_mul_f32_e32 v102, v104, v102
	v_bfe_u32 v104, v102, 16, 1
	v_lshl_or_b32 v70, v150, 16, v136
	v_add3_u32 v136, v102, v104, s10
	v_add_f32_e32 v104, 1.0, v86
	v_rcp_f32_e32 v104, v104
	v_lshlrev_b32_e32 v102, 16, v168
	v_mul_f32_e32 v102, v88, v102
	v_bfe_u32 v106, v102, 16, 1
	v_fmac_f32_e32 v149, v80, v104
	v_mul_f32_e32 v88, v88, v149
	v_add3_u32 v102, v102, v106, s10
	v_max_f32_e32 v88, 0xda24260, v88
	ds_write_b16_d16_hi v83, v102 offset:4320
	v_rcp_f32_e32 v102, v88
	v_mul_f32_e32 v86, v86, v104
	v_mul_f32_e32 v80, v80, v86
	v_and_b32_e32 v81, 0xffff0000, v64
	v_mul_f32_e32 v80, v80, v102
	v_bfe_u32 v86, v80, 16, 1
	v_add3_u32 v80, v80, v86, s10
	v_lshlrev_b32_e32 v86, 16, v167
	v_mul_f32_e32 v86, v88, v86
	v_bfe_u32 v102, v86, 16, 1
	v_add3_u32 v86, v86, v102, s10
	v_and_b32_e32 v85, 0xffff0000, v66
	v_and_b32_e32 v87, 0xffff0000, v65
	v_and_b32_e32 v105, 0xffff0000, v159
	v_and_b32_e32 v107, 0xffff0000, v163
	v_and_b32_e32 v109, 0xffff0000, v115
	v_and_b32_e32 v111, 0xffff0000, v172
	v_and_b32_e32 v113, 0xffff0000, v176
	v_and_b32_e32 v115, 0xffff0000, v175
	v_and_b32_e32 v117, 0xffff0000, v117
	v_and_b32_e32 v119, 0xffff0000, v119
	v_lshl_or_b32 v67, v142, 16, v141
	v_lshl_or_b32 v66, v143, 16, v140
	v_lshl_or_b32 v65, v145, 16, v139
	v_lshl_or_b32 v64, v146, 16, v138
	v_lshl_or_b32 v71, v147, 16, v137
	v_lshl_or_b32 v68, v152, 16, v134
	v_lshl_or_b32 v73, v154, 16, v130
	v_lshl_or_b32 v72, v155, 16, v129
	v_lshl_or_b32 v77, v118, 16, v126
	ds_write_b16_d16_hi v83, v120 offset:8064
	ds_write_b16_d16_hi v83, v122 offset:8352
	ds_write_b16_d16_hi v83, v132 offset:8640
	ds_write_b16_d16_hi v83, v136 offset:8928
	v_and_b32_e32 v137, 0xffff0000, v80
	ds_write_b16_d16_hi v83, v86 offset:4464
	ds_write_b16_d16_hi v83, v80 offset:9072
	v_and_b32_e32 v112, 0xffff0000, v170
	v_and_b32_e32 v104, 0xffff0000, v157
	v_and_b32_e32 v80, 0xffff0000, v178
	v_pk_mul_f32 v[112:113], v[88:89], v[112:113] op_sel_hi:[0,1]
	v_and_b32_e32 v108, 0xffff0000, v84
	v_pk_mul_f32 v[104:105], v[88:89], v[104:105] op_sel_hi:[0,1]
	v_and_b32_e32 v84, 0xffff0000, v182
	v_pk_mul_f32 v[80:81], v[88:89], v[80:81] op_sel_hi:[0,1]
	v_and_b32_e32 v120, 0xffff0000, v120
	v_cvt_pk_bf16_f32 v129, v112, v113
	v_cvt_pk_bf16_f32 v113, v104, v105
	v_pk_mul_f32 v[84:85], v[88:89], v[84:85] op_sel_hi:[0,1]
	v_cvt_pk_bf16_f32 v105, v80, v81
	v_pk_mul_f32 v[80:81], v[88:89], v[120:121] op_sel_hi:[0,1]
	v_and_b32_e32 v130, 0xffff0000, v122
	v_and_b32_e32 v102, 0xffff0000, v156
	v_and_b32_e32 v86, 0xffff0000, v181
	v_cvt_pk_bf16_f32 v104, v84, v85
	v_cvt_pk_bf16_f32 v84, v80, v81
	v_pk_mul_f32 v[80:81], v[88:89], v[130:131] op_sel_hi:[0,1]
	v_and_b32_e32 v134, 0xffff0000, v132
	v_and_b32_e32 v118, 0xffff0000, v133
	v_and_b32_e32 v116, 0xffff0000, v116
	v_and_b32_e32 v114, 0xffff0000, v123
	v_and_b32_e32 v110, 0xffff0000, v171
	v_and_b32_e32 v106, 0xffff0000, v158
	v_pk_mul_f32 v[102:103], v[88:89], v[102:103] op_sel_hi:[0,1]
	v_pk_mul_f32 v[86:87], v[88:89], v[86:87] op_sel_hi:[0,1]
	v_cvt_pk_bf16_f32 v85, v80, v81
	v_pk_mul_f32 v[80:81], v[88:89], v[134:135] op_sel_hi:[0,1]
	v_and_b32_e32 v136, 0xffff0000, v136
	s_movk_i32 s0, 0x50
	v_pk_mul_f32 v[118:119], v[88:89], v[118:119] op_sel_hi:[0,1]
	v_pk_mul_f32 v[116:117], v[88:89], v[116:117] op_sel_hi:[0,1]
	v_pk_mul_f32 v[114:115], v[88:89], v[114:115] op_sel_hi:[0,1]
	v_pk_mul_f32 v[110:111], v[88:89], v[110:111] op_sel_hi:[0,1]
	v_pk_mul_f32 v[108:109], v[88:89], v[108:109] op_sel_hi:[0,1]
	v_pk_mul_f32 v[106:107], v[88:89], v[106:107] op_sel_hi:[0,1]
	v_cvt_pk_bf16_f32 v102, v102, v103
	v_cvt_pk_bf16_f32 v103, v86, v87
	v_cvt_pk_bf16_f32 v86, v80, v81
	v_pk_mul_f32 v[80:81], v[88:89], v[136:137] op_sel_hi:[0,1]
	v_mad_u64_u32 v[138:139], s[2:3], v82, s0, v[92:93]
	v_cvt_pk_bf16_f32 v126, v118, v119
	v_cvt_pk_bf16_f32 v127, v116, v117
	v_cvt_pk_bf16_f32 v128, v114, v115
	v_cvt_pk_bf16_f32 v110, v110, v111
	v_cvt_pk_bf16_f32 v111, v108, v109
	v_cvt_pk_bf16_f32 v112, v106, v107
	v_cvt_pk_bf16_f32 v87, v80, v81
	v_lshl_add_u32 v80, v82, 2, v92
	ds_write_b128 v138, v[126:129] offset:9216
	ds_write_b128 v138, v[110:113] offset:9232
	ds_write_b128 v138, v[102:105] offset:9248
	ds_write_b128 v138, v[84:87] offset:9264
	ds_write_b32 v80, v88 offset:19456
	ds_write_b128 v138, v[76:79] offset:14336
	ds_write_b128 v138, v[72:75] offset:14352
	ds_write_b128 v138, v[68:71] offset:14368
	ds_write_b128 v138, v[64:67] offset:14384
	s_waitcnt lgkmcnt(0)
	v_or_b32_e32 v88, v95, v124
	v_lshlrev_b64 v[64:65], 11, v[88:89]
	v_lshl_add_u64 v[64:65], s[16:17], 0, v[64:65]
	v_lshlrev_b32_e32 v80, 2, v125
	s_movk_i32 s48, 0x90
	v_lshl_add_u64 v[64:65], v[64:65], 0, v[90:91]
	v_ashrrev_i32_e32 v81, 31, v80
	v_mad_u32_u24 v88, v124, s48, v92
	v_lshl_add_u64 v[104:105], v[80:81], 1, v[64:65]
	v_lshl_add_u32 v81, v125, 4, v88
	ds_read_b128 v[64:67], v81 offset:4608
	ds_read_b128 v[68:71], v81
	ds_read_b128 v[82:85], v81 offset:32
	ds_read_b128 v[106:109], v81 offset:4640
	s_waitcnt lgkmcnt(2)
	v_mfma_f32_32x32x16_bf16 v[64:79], v[64:67], v[68:71], 0
	v_cmp_le_i32_e32 vcc, v80, v124
	v_cvt_pk_bf16_f32 v32, v32, v33
	v_cvt_pk_bf16_f32 v33, v34, v35
	v_cvt_pk_bf16_f32 v34, v36, v37
	v_cvt_pk_bf16_f32 v35, v38, v39
	v_cvt_pk_bf16_f32 v36, v48, v49
	v_cvt_pk_bf16_f32 v37, v50, v51
	s_waitcnt lgkmcnt(0)
	v_mfma_f32_32x32x16_bf16 v[64:79], v[106:109], v[82:85], v[64:79]
	ds_read_b128 v[82:85], v81 offset:4672
	ds_read_b128 v[106:109], v81 offset:64
	v_cvt_pk_bf16_f32 v38, v52, v53
	v_cvt_pk_bf16_f32 v39, v54, v55
	s_mov_b32 s6, 0x16f00000
	s_mov_b64 s[4:5], 0x16f00600
	v_lshl_add_u64 v[102:103], v[104:105], 0, s[4:5]
	s_waitcnt lgkmcnt(0)
	v_mfma_f32_32x32x16_bf16 v[64:79], v[82:85], v[106:109], v[64:79]
	ds_read_b128 v[82:85], v81 offset:4704
	ds_read_b128 v[106:109], v81 offset:96
	v_or_b32_e32 v81, 2, v80
	s_waitcnt lgkmcnt(0)
	v_mfma_f32_32x32x16_bf16 v[64:79], v[82:85], v[106:109], v[64:79]
	s_nop 11
	v_cndmask_b32_e32 v64, 0, v64, vcc
	v_cmp_lt_i32_e32 vcc, v80, v124
	s_nop 1
	v_cndmask_b32_e32 v65, 0, v65, vcc
	v_cmp_le_i32_e32 vcc, v81, v124
	v_or_b32_e32 v81, 3, v80
	v_cvt_pk_bf16_f32 v84, v64, v65
	v_cndmask_b32_e32 v66, 0, v66, vcc
	v_cmp_le_i32_e32 vcc, v81, v124
	v_add_u32_e32 v81, 8, v80
	v_lshlrev_b32_e32 v64, 3, v125
	v_cndmask_b32_e32 v67, 0, v67, vcc
	v_cmp_le_i32_e32 vcc, v81, v124
	v_add_u32_e32 v81, 9, v80
	v_mul_u32_u24_e32 v65, 0x50, v124
	v_cndmask_b32_e32 v68, 0, v68, vcc
	v_cmp_le_i32_e32 vcc, v81, v124
	v_add_u32_e32 v81, 10, v80
	v_add3_u32 v114, v92, v64, v65
	v_cndmask_b32_e32 v69, 0, v69, vcc
	v_cmp_le_i32_e32 vcc, v81, v124
	v_add_u32_e32 v81, 11, v80
	v_cvt_pk_bf16_f32 v86, v68, v69
	v_cndmask_b32_e32 v70, 0, v70, vcc
	v_cmp_le_i32_e32 vcc, v81, v124
	v_add_u32_e32 v81, 16, v80
	v_add_u32_e32 v68, 0x3800, v114
	v_cndmask_b32_e32 v71, 0, v71, vcc
	v_cmp_le_i32_e32 vcc, v81, v124
	v_add_u32_e32 v81, 17, v80
	v_cvt_pk_bf16_f32 v85, v66, v67
	v_cndmask_b32_e32 v72, 0, v72, vcc
	v_cmp_le_i32_e32 vcc, v81, v124
	v_add_u32_e32 v81, 18, v80
	v_add_u32_e32 v88, v88, v64
	v_cndmask_b32_e32 v73, 0, v73, vcc
	v_cmp_le_i32_e32 vcc, v81, v124
	v_add_u32_e32 v81, 19, v80
	ds_read2_b64 v[64:67], v68 offset1:2
	ds_read2_b64 v[106:109], v68 offset0:4 offset1:6
	v_cndmask_b32_e32 v74, 0, v74, vcc
	v_cmp_le_i32_e32 vcc, v81, v124
	v_add_u32_e32 v81, 24, v80
	v_cvt_pk_bf16_f32 v87, v70, v71
	v_cndmask_b32_e32 v75, 0, v75, vcc
	v_cmp_le_i32_e32 vcc, v81, v124
	v_add_u32_e32 v81, 25, v80
	s_nop 0
	v_cndmask_b32_e32 v76, 0, v76, vcc
	v_cmp_le_i32_e32 vcc, v81, v124
	v_add_u32_e32 v81, 26, v80
	v_add_u32_e32 v80, 27, v80
	v_cndmask_b32_e32 v77, 0, v77, vcc
	v_cmp_le_i32_e32 vcc, v81, v124
	v_cvt_pk_bf16_f32 v81, v74, v75
	v_cvt_pk_bf16_f32 v82, v76, v77
	v_cndmask_b32_e32 v78, 0, v78, vcc
	v_cmp_le_i32_e32 vcc, v80, v124
	v_cvt_pk_bf16_f32 v80, v72, v73
	s_nop 0
	v_cndmask_b32_e32 v79, 0, v79, vcc
	v_cvt_pk_bf16_f32 v83, v78, v79
	s_waitcnt lgkmcnt(1)
	v_mfma_f32_32x32x16_bf16 v[64:79], v[64:67], v[84:87], 0
	s_waitcnt lgkmcnt(0)
	v_mfma_f32_32x32x16_bf16 v[64:79], v[106:109], v[80:83], v[64:79]
	ds_read2_b64 v[106:109], v88 offset1:2
	ds_read2_b64 v[110:113], v88 offset0:4 offset1:6
	s_waitcnt lgkmcnt(1)
	v_mfma_f32_32x32x16_bf16 v[64:79], v[32:35], v[106:109], v[64:79]
	v_cvt_pk_bf16_f32 v32, v40, v41
	v_cvt_pk_bf16_f32 v33, v42, v43
	v_cvt_pk_bf16_f32 v34, v44, v45
	v_cvt_pk_bf16_f32 v35, v46, v47
	s_waitcnt lgkmcnt(0)
	s_nop 0
	v_mfma_f32_32x32x16_bf16 v[64:79], v[32:35], v[110:113], v[64:79]
	ds_read2_b64 v[32:35], v88 offset0:8 offset1:10
	s_waitcnt lgkmcnt(0)
	v_mfma_f32_32x32x16_bf16 v[64:79], v[36:39], v[32:35], v[64:79]
	ds_read2_b64 v[32:35], v88 offset0:12 offset1:14
	v_cvt_pk_bf16_f32 v36, v56, v57
	v_cvt_pk_bf16_f32 v37, v58, v59
	v_cvt_pk_bf16_f32 v38, v60, v61
	v_cvt_pk_bf16_f32 v39, v62, v63
	s_waitcnt lgkmcnt(0)
	s_nop 0
	v_mfma_f32_32x32x16_bf16 v[64:79], v[36:39], v[32:35], v[64:79]
	v_add_co_u32_e32 v34, vcc, s6, v104
	s_nop 1
	v_addc_co_u32_e32 v35, vcc, 0, v105, vcc
	s_nop 7
	v_cvt_pk_bf16_f32 v32, v64, v65
	v_cvt_pk_bf16_f32 v33, v66, v67
	global_store_dwordx2 v[34:35], v[32:33], off offset:1536
	v_cvt_pk_bf16_f32 v32, v68, v69
	v_cvt_pk_bf16_f32 v33, v70, v71
	global_store_dwordx2 v[102:103], v[32:33], off offset:16
	v_cvt_pk_bf16_f32 v32, v72, v73
	v_cvt_pk_bf16_f32 v33, v74, v75
	global_store_dwordx2 v[102:103], v[32:33], off offset:32
	v_cvt_pk_bf16_f32 v32, v76, v77
	v_cvt_pk_bf16_f32 v33, v78, v79
	global_store_dwordx2 v[102:103], v[32:33], off offset:48
	v_add_u32_e32 v48, 0x4000, v114
	ds_read2_b64 v[32:35], v48 offset0:64 offset1:66
	ds_read2_b64 v[48:51], v48 offset0:68 offset1:70
	ds_read2_b64 v[52:55], v88 offset1:2
	v_cvt_pk_bf16_f32 v0, v0, v1
	v_cvt_pk_bf16_f32 v1, v2, v3
	v_cvt_pk_bf16_f32 v2, v4, v5
	v_cvt_pk_bf16_f32 v3, v6, v7
	ds_read2_b64 v[4:7], v88 offset0:4 offset1:6
	v_cvt_pk_bf16_f32 v8, v8, v9
	v_cvt_pk_bf16_f32 v9, v10, v11
	s_waitcnt lgkmcnt(3)
	v_mfma_f32_32x32x16_bf16 v[32:47], v[32:35], v[84:87], 0
	v_cvt_pk_bf16_f32 v10, v12, v13
	v_cvt_pk_bf16_f32 v11, v14, v15
	v_cvt_pk_bf16_f32 v12, v16, v17
	v_cvt_pk_bf16_f32 v13, v18, v19
	v_cvt_pk_bf16_f32 v14, v20, v21
	v_cvt_pk_bf16_f32 v15, v22, v23
	s_waitcnt lgkmcnt(2)
	v_mfma_f32_32x32x16_bf16 v[32:47], v[48:51], v[80:83], v[32:47]
	s_waitcnt lgkmcnt(1)
	v_mfma_f32_32x32x16_bf16 v[32:47], v[0:3], v[52:55], v[32:47]
	ds_read2_b64 v[0:3], v88 offset0:8 offset1:10
	s_waitcnt lgkmcnt(1)
	v_mfma_f32_32x32x16_bf16 v[32:47], v[8:11], v[4:7], v[32:47]
	ds_read2_b64 v[4:7], v88 offset0:12 offset1:14
	v_cvt_pk_bf16_f32 v8, v24, v25
	v_cvt_pk_bf16_f32 v9, v26, v27
	v_cvt_pk_bf16_f32 v10, v28, v29
	v_cvt_pk_bf16_f32 v11, v30, v31
	s_waitcnt lgkmcnt(1)
	v_mfma_f32_32x32x16_bf16 v[32:47], v[12:15], v[0:3], v[32:47]
	s_waitcnt lgkmcnt(0)
	v_mfma_f32_32x32x16_bf16 v[32:47], v[8:11], v[4:7], v[32:47]
	s_nop 11
	v_cvt_pk_bf16_f32 v0, v32, v33
	v_cvt_pk_bf16_f32 v1, v34, v35
	v_cvt_pk_bf16_f32 v2, v36, v37
	v_cvt_pk_bf16_f32 v3, v38, v39
	v_cvt_pk_bf16_f32 v4, v40, v41
	v_cvt_pk_bf16_f32 v5, v42, v43
	v_cvt_pk_bf16_f32 v6, v44, v45
	v_cvt_pk_bf16_f32 v7, v46, v47
	global_store_dwordx2 v[102:103], v[0:1], off offset:64
	global_store_dwordx2 v[102:103], v[2:3], off offset:80
	global_store_dwordx2 v[102:103], v[4:5], off offset:96
	global_store_dwordx2 v[102:103], v[6:7], off offset:112
	s_waitcnt lgkmcnt(0)
	v_lshl_add_u64 v[0:1], s[44:45], 0, v[160:161]
	v_add_co_u32_e32 v2, vcc, s20, v0
	s_movk_i32 s11, 0x3000
	s_nop 0
	v_addc_co_u32_e32 v3, vcc, 0, v1, vcc
	v_add_co_u32_e32 v4, vcc, s11, v0
	s_movk_i32 s7, 0x4000
	s_nop 0
	v_addc_co_u32_e32 v5, vcc, 0, v1, vcc
	v_add_co_u32_e32 v0, vcc, s7, v0
	v_readlane_b32 s0, v255, 22
	s_nop 0
	v_addc_co_u32_e32 v1, vcc, 0, v1, vcc
	global_load_dword v24, v[2:3], off offset:3072
	global_load_dword v25, v[4:5], off offset:1024
	global_load_dword v26, v[4:5], off offset:3072
	global_load_dword v27, v[0:1], off offset:1024
	v_or_b32_e32 v0, 1, v148
	v_mad_i64_i32 v[0:1], s[2:3], v0, 36, v[96:97]
	v_lshlrev_b64 v[0:1], 13, v[0:1]
	v_readlane_b32 s1, v255, 23
	v_readlane_b32 s2, v255, 1
	v_readlane_b32 s3, v255, 2
	v_lshl_add_u64 v[0:1], s[0:1], 0, v[0:1]
	v_lshl_add_u64 v[0:1], v[0:1], 0, v[98:99]
	v_lshl_add_u64 v[0:1], v[0:1], 0, v[100:101]
	global_load_dwordx2 v[2:3], v[0:1], off
	global_load_dwordx2 v[4:5], v[0:1], off offset:16
	global_load_dwordx2 v[6:7], v[0:1], off offset:32
	global_load_dwordx2 v[8:9], v[0:1], off offset:48
	s_movk_i32 s0, 0x1000
	v_add_co_u32_e32 v10, vcc, s0, v0
	s_mov_b32 s1, 0xf149f2ca
	s_nop 0
	v_addc_co_u32_e32 v11, vcc, 0, v1, vcc
	global_load_dwordx2 v[12:13], v[10:11], off
	global_load_dwordx2 v[14:15], v[10:11], off offset:16
	global_load_dwordx2 v[16:17], v[10:11], off offset:32
	global_load_dwordx2 v[18:19], v[10:11], off offset:48
	global_load_dwordx2 v[20:21], v[0:1], off offset:64
	global_load_dwordx2 v[22:23], v[0:1], off offset:80
	global_load_dwordx2 v[58:59], v[0:1], off offset:96
	s_nop 0
	global_load_dwordx2 v[0:1], v[0:1], off offset:112
	s_nop 0
	global_load_dwordx2 v[64:65], v[10:11], off offset:64
	global_load_dwordx2 v[72:73], v[10:11], off offset:80
	global_load_dwordx2 v[76:77], v[10:11], off offset:96
	s_nop 0
	global_load_dwordx2 v[10:11], v[10:11], off offset:112
	s_mov_b64 s[40:41], s[44:45]
	s_mov_b64 s[12:13], s[44:45]
	s_waitcnt vmcnt(18)
	v_max3_f32 v28, v24, s1, v25
	s_waitcnt vmcnt(16)
	v_max3_f32 v28, v28, v26, v27
	v_sub_f32_e32 v25, v25, v28
	v_mul_f32_e32 v25, 0x3fb8aa3b, v25
	v_sub_f32_e32 v24, v24, v28
	v_sub_f32_e32 v26, v26, v28
	v_exp_f32_e32 v25, v25
	v_mul_f32_e32 v24, 0x3fb8aa3b, v24
	v_mul_f32_e32 v26, 0x3fb8aa3b, v26
	v_sub_f32_e32 v27, v27, v28
	v_exp_f32_e32 v50, v24
	v_exp_f32_e32 v51, v26
	v_mul_f32_e32 v27, 0x3fb8aa3b, v27
	v_exp_f32_e32 v52, v27
	s_waitcnt vmcnt(15)
	v_lshlrev_b32_e32 v32, 16, v2
	v_and_b32_e32 v33, 0xffff0000, v2
	v_add_f32_e32 v2, 0, v25
	v_cndmask_b32_e64 v2, v2, 0, s[2:3]
	v_readlane_b32 s2, v255, 3
	v_lshlrev_b32_e32 v34, 16, v3
	v_and_b32_e32 v35, 0xffff0000, v3
	s_waitcnt vmcnt(14)
	v_lshlrev_b32_e32 v36, 16, v4
	v_and_b32_e32 v37, 0xffff0000, v4
	v_add_f32_e32 v3, 0, v50
	v_add_f32_e32 v4, v51, v2
	v_readlane_b32 s3, v255, 4
	v_add_f32_e32 v3, v25, v3
	v_add_f32_e32 v3, v51, v3
	v_cndmask_b32_e64 v2, v4, v2, s[2:3]
	v_readlane_b32 s2, v255, 5
	v_add_f32_e32 v4, v52, v2
	v_readlane_b32 s3, v255, 6
	v_add_f32_e32 v3, v52, v3
	v_lshlrev_b32_e32 v38, 16, v5
	v_cndmask_b32_e64 v2, v4, v2, s[2:3]
	v_div_scale_f32 v4, s[2:3], v3, v3, v2
	v_and_b32_e32 v39, 0xffff0000, v5
	v_rcp_f32_e32 v5, v4
	s_waitcnt vmcnt(13)
	v_lshlrev_b32_e32 v42, 16, v7
	v_and_b32_e32 v43, 0xffff0000, v7
	v_lshlrev_b32_e32 v40, 16, v6
	v_fma_f32 v7, -v4, v5, 1.0
	v_and_b32_e32 v41, 0xffff0000, v6
	v_div_scale_f32 v6, vcc, v2, v3, v2
	v_fmac_f32_e32 v5, v7, v5
	v_mul_f32_e32 v7, v6, v5
	s_waitcnt vmcnt(12)
	v_lshlrev_b32_e32 v44, 16, v8
	v_and_b32_e32 v45, 0xffff0000, v8
	v_fma_f32 v8, -v4, v7, v6
	v_fmac_f32_e32 v7, v8, v5
	v_fma_f32 v4, -v4, v7, v6
	s_waitcnt vmcnt(9)
	v_lshlrev_b32_e32 v24, 16, v16
	v_and_b32_e32 v25, 0xffff0000, v16
	v_div_fmas_f32 v4, v4, v5, v7
	v_mov_b32_e32 v16, v94
	v_div_fixup_f32 v116, v4, v3, v2
	s_add_u32 s2, s40, 0xb200000
	v_lshlrev_b32_e32 v46, 16, v9
	v_and_b32_e32 v47, 0xffff0000, v9
	v_lshlrev_b32_e32 v26, 16, v12
	v_and_b32_e32 v27, 0xffff0000, v12
	v_lshlrev_b32_e32 v28, 16, v13
	v_and_b32_e32 v29, 0xffff0000, v13
	v_lshlrev_b32_e32 v30, 16, v14
	v_and_b32_e32 v31, 0xffff0000, v14
	v_lshlrev_b32_e32 v48, 16, v15
	v_and_b32_e32 v49, 0xffff0000, v15
	v_lshlrev_b32_e32 v84, 16, v17
	v_and_b32_e32 v85, 0xffff0000, v17
	s_waitcnt vmcnt(8)
	v_lshlrev_b32_e32 v86, 16, v18
	v_and_b32_e32 v87, 0xffff0000, v18
	v_lshlrev_b32_e32 v96, 16, v19
	v_and_b32_e32 v97, 0xffff0000, v19
	s_waitcnt vmcnt(7)
	v_lshlrev_b32_e32 v54, 16, v20
	v_and_b32_e32 v55, 0xffff0000, v20
	v_lshlrev_b32_e32 v50, 16, v21
	v_and_b32_e32 v51, 0xffff0000, v21
	s_waitcnt vmcnt(6)
	v_lshlrev_b32_e32 v52, 16, v22
	v_and_b32_e32 v53, 0xffff0000, v22
	v_lshlrev_b32_e32 v82, 16, v23
	v_and_b32_e32 v83, 0xffff0000, v23
	s_waitcnt vmcnt(5)
	v_lshlrev_b32_e32 v56, 16, v58
	v_and_b32_e32 v57, 0xffff0000, v58
	v_lshlrev_b32_e32 v58, 16, v59
	v_and_b32_e32 v59, 0xffff0000, v59
	s_waitcnt vmcnt(4)
	v_lshlrev_b32_e32 v60, 16, v0
	v_and_b32_e32 v61, 0xffff0000, v0
	v_lshlrev_b32_e32 v62, 16, v1
	v_and_b32_e32 v63, 0xffff0000, v1
	s_waitcnt vmcnt(3)
	v_lshlrev_b32_e32 v66, 16, v64
	v_and_b32_e32 v67, 0xffff0000, v64
	v_lshlrev_b32_e32 v68, 16, v65
	v_and_b32_e32 v69, 0xffff0000, v65
	s_waitcnt vmcnt(2)
	v_lshlrev_b32_e32 v70, 16, v72
	v_and_b32_e32 v71, 0xffff0000, v72
	v_lshlrev_b32_e32 v72, 16, v73
	v_and_b32_e32 v73, 0xffff0000, v73
	s_waitcnt vmcnt(1)
	v_lshlrev_b32_e32 v74, 16, v76
	v_and_b32_e32 v75, 0xffff0000, v76
	v_lshlrev_b32_e32 v76, 16, v77
	v_and_b32_e32 v77, 0xffff0000, v77
	s_waitcnt vmcnt(0)
	v_lshlrev_b32_e32 v78, 16, v10
	v_and_b32_e32 v79, 0xffff0000, v10
	v_lshlrev_b32_e32 v80, 16, v11
	v_and_b32_e32 v81, 0xffff0000, v11
	v_sub_f32_e32 v117, 1.0, v116
	v_and_b32_e32 v118, 31, v16
	v_ashrrev_i32_e32 v119, 5, v16
	s_addc_u32 s3, s41, 0
	v_mov_b64_e32 v[64:65], s[2:3]
	s_movk_i32 s1, 0x1200
	v_mad_i64_i32 v[0:1], s[2:3], v95, s1, v[64:65]
	v_ashrrev_i32_e32 v17, 31, v16
	v_lshl_add_u64 v[0:1], v[0:1], 0, v[90:91]
	v_lshl_add_u64 v[0:1], v[16:17], 1, v[0:1]
	s_mov_b32 s37, 0x23000
	v_add_co_u32_e32 v12, vcc, s37, v0
	s_movk_i32 s2, 0x5000
	s_nop 0
	v_addc_co_u32_e32 v13, vcc, 0, v1, vcc
	global_load_ushort v88, v[12:13], off offset:3072
	global_load_ushort v109, v[12:13], off offset:1536
	v_add_co_u32_e32 v2, vcc, s20, v0
	s_mov_b32 s28, 0x9000
	s_nop 0
	v_addc_co_u32_e32 v3, vcc, 0, v1, vcc
	v_add_co_u32_e32 v4, vcc, s2, v0
	s_movk_i32 s2, 0x7000
	s_nop 0
	v_addc_co_u32_e32 v5, vcc, 0, v1, vcc
	v_add_co_u32_e32 v6, vcc, s2, v0
	s_mov_b32 s29, 0xb000
	s_nop 0
	v_addc_co_u32_e32 v7, vcc, 0, v1, vcc
	v_add_co_u32_e32 v18, vcc, s28, v0
	s_mov_b32 s18, 0xe000
	s_nop 0
	v_addc_co_u32_e32 v19, vcc, 0, v1, vcc
	v_add_co_u32_e32 v20, vcc, s29, v0
	s_mov_b32 s2, 0x10000
	s_nop 0
	v_addc_co_u32_e32 v21, vcc, 0, v1, vcc
	v_add_co_u32_e32 v22, vcc, s18, v0
	s_mov_b32 s30, 0x17000
	s_nop 0
	v_addc_co_u32_e32 v23, vcc, 0, v1, vcc
	v_add_co_u32_e32 v98, vcc, s2, v0
	s_mov_b32 s2, 0x14000
	s_nop 0
	v_addc_co_u32_e32 v99, vcc, 0, v1, vcc
	v_add_co_u32_e32 v8, vcc, s51, v0
	s_mov_b32 s31, 0x19000
	s_nop 0
	v_addc_co_u32_e32 v9, vcc, 0, v1, vcc
	v_add_co_u32_e32 v10, vcc, s2, v0
	s_mov_b32 s34, 0x1b000
	s_nop 0
	v_addc_co_u32_e32 v11, vcc, 0, v1, vcc
	v_add_co_u32_e32 v14, vcc, s30, v0
	s_mov_b32 s35, 0x1d000
	s_nop 0
	v_addc_co_u32_e32 v15, vcc, 0, v1, vcc
	v_add_co_u32_e32 v100, vcc, s31, v0
	s_mov_b32 s19, 0x20000
	s_nop 0
	v_addc_co_u32_e32 v101, vcc, 0, v1, vcc
	v_add_co_u32_e32 v102, vcc, s34, v0
	s_mov_b32 s36, 0x22000
	s_nop 0
	v_addc_co_u32_e32 v103, vcc, 0, v1, vcc
	v_add_co_u32_e32 v104, vcc, s35, v0
	s_mov_b32 s21, 0x21000
	s_nop 0
	v_addc_co_u32_e32 v105, vcc, 0, v1, vcc
	v_add_co_u32_e32 v106, vcc, s19, v0
	s_mov_b32 s42, 0x1f000
	s_nop 0
	v_addc_co_u32_e32 v107, vcc, 0, v1, vcc
	v_add_co_u32_e32 v120, vcc, s36, v0
	s_mov_b32 s17, 0x1e000
	s_nop 0
	v_addc_co_u32_e32 v121, vcc, 0, v1, vcc
	v_add_co_u32_e32 v110, vcc, s21, v0
	s_mov_b32 s16, 0x1c000
	s_nop 0
	v_addc_co_u32_e32 v111, vcc, 0, v1, vcc
	global_load_ushort v113, v[110:111], off offset:512
	global_load_ushort v108, v[110:111], off offset:1024
	global_load_ushort v122, v[110:111], off offset:2048
	s_nop 0
	global_load_ushort v110, v[12:13], off offset:2048
	global_load_ushort v112, v[120:121], off offset:1536
	global_load_ushort v145, v[120:121], off offset:2560
	global_load_ushort v123, v[104:105], off offset:3584
	global_load_ushort v124, v[106:107], off offset:512
	global_load_ushort v154, v[120:121], off offset:1024
	global_load_ushort v155, v[106:107], off offset:1536
	global_load_ushort v156, v[106:107], off
	global_load_ushort v159, v[104:105], off offset:3072
	global_load_ushort v162, v[104:105], off
	global_load_ushort v166, v[102:103], off offset:3584
	s_waitcnt vmcnt(15)
	v_lshlrev_b32_e32 v12, 16, v88
	v_max_f32_e32 v12, v12, v12
	v_med3_f32 v12, v12, s9, v244
	v_mul_f32_e32 v12, 0xbfb8aa3b, v12
	v_exp_f32_e32 v88, v12
	v_add_co_u32_e32 v12, vcc, s42, v0
	s_mov_b32 s2, 0x1a000
	v_add_f32_e32 v111, 1.0, v88
	v_addc_co_u32_e32 v13, vcc, 0, v1, vcc
	v_rcp_f32_e32 v111, v111
	v_add_co_u32_e32 v136, vcc, s17, v0
	s_waitcnt vmcnt(14)
	v_lshlrev_b32_e32 v109, 16, v109
	v_addc_co_u32_e32 v137, vcc, 0, v1, vcc
	v_add_co_u32_e32 v134, vcc, s16, v0
	v_fma_f32 v114, v117, v111, v116
	s_nop 0
	v_addc_co_u32_e32 v135, vcc, 0, v1, vcc
	v_max_f32_e32 v152, 0xda24260, v114
	v_add_co_u32_e32 v120, vcc, s2, v0
	v_mul_f32_e32 v88, v88, v111
	v_rcp_f32_e32 v111, v152
	v_addc_co_u32_e32 v121, vcc, 0, v1, vcc
	s_mov_b32 s2, 0x18000
	v_add_co_u32_e32 v138, vcc, s2, v0
	s_mov_b32 s2, 0x16000
	s_nop 0
	v_addc_co_u32_e32 v139, vcc, 0, v1, vcc
	v_mul_f32_e32 v88, v117, v88
	v_mul_f32_e32 v109, v152, v109
	global_load_ushort v125, v[14:15], off offset:512
	global_load_ushort v127, v[100:101], off offset:1536
	global_load_ushort v128, v[102:103], off offset:2560
	global_load_ushort v167, v[102:103], off offset:2048
	global_load_ushort v169, v[100:101], off offset:2560
	global_load_ushort v172, v[100:101], off offset:1024
	global_load_ushort v168, v[14:15], off offset:1536
	global_load_ushort v164, v[14:15], off
	v_add_co_u32_e32 v14, vcc, s2, v0
	v_bfe_u32 v114, v109, 16, 1
	v_mul_f32_e32 v88, v88, v111
	v_addc_co_u32_e32 v15, vcc, 0, v1, vcc
	s_mov_b32 s43, 0x15000
	v_add3_u32 v153, v109, v114, s10
	v_bfe_u32 v109, v88, 16, 1
	v_add_co_u32_e32 v140, vcc, s43, v0
	v_add3_u32 v114, v88, v109, s10
	s_nop 0
	v_addc_co_u32_e32 v141, vcc, 0, v1, vcc
	global_load_ushort v126, v[22:23], off offset:512
	global_load_ushort v129, v[98:99], off offset:1536
	global_load_ushort v130, v[8:9], off offset:2560
	global_load_ushort v131, v[10:11], off offset:3584
	global_load_ushort v158, v[10:11], off offset:3072
	global_load_ushort v115, v[10:11], off
	global_load_ushort v111, v[8:9], off offset:3584
	global_load_ushort v109, v[8:9], off offset:2048
	global_load_ushort v173, v[12:13], off offset:1024
	global_load_ushort v174, v[136:137], off offset:3584
	global_load_ushort v175, v[134:135], off offset:2560
	global_load_ushort v176, v[120:121], off offset:1536
	global_load_ushort v133, v[120:121], off offset:2048
	s_nop 0
	global_load_ushort v134, v[134:135], off offset:3072
	s_nop 0
	global_load_ushort v177, v[136:137], off offset:512
	global_load_ushort v135, v[12:13], off
	global_load_ushort v178, v[120:121], off offset:3072
	global_load_ushort v171, v[138:139], off offset:2048
	global_load_ushort v170, v[138:139], off offset:512
	global_load_ushort v165, v[14:15], off offset:1024
	global_load_ushort v163, v[140:141], off offset:3584
	global_load_ushort v160, v[140:141], off offset:512
	global_load_ushort v137, v[14:15], off
	s_nop 0
	global_load_ushort v139, v[138:139], off offset:1024
	s_mov_b32 s44, 0x13000
	v_add_co_u32_e32 v146, vcc, s44, v0
	s_mov_b32 s45, 0x11000
	s_nop 0
	v_addc_co_u32_e32 v147, vcc, 0, v1, vcc
	v_add_co_u32_e32 v106, vcc, s45, v0
	s_mov_b32 s46, 0xf000
	s_nop 0
	v_addc_co_u32_e32 v107, vcc, 0, v1, vcc
	v_add_co_u32_e32 v102, vcc, s46, v0
	s_mov_b32 s47, 0xd000
	s_nop 0
	v_addc_co_u32_e32 v103, vcc, 0, v1, vcc
	v_add_co_u32_e32 v104, vcc, s47, v0
	s_mov_b32 s15, 0xa000
	s_nop 0
	v_addc_co_u32_e32 v105, vcc, 0, v1, vcc
	v_add_co_u32_e32 v100, vcc, s15, v0
	s_mov_b32 s14, 0x8000
	s_waitcnt vmcnt(40)
	v_lshlrev_b32_e32 v8, 16, v145
	v_max_f32_e32 v8, v8, v8
	v_med3_f32 v8, v8, s9, v244
	v_mul_f32_e32 v8, 0xbfb8aa3b, v8
	v_exp_f32_e32 v88, v8
	v_addc_co_u32_e32 v101, vcc, 0, v1, vcc
	v_lshlrev_b32_e32 v122, 16, v122
	v_add_f32_e32 v120, 1.0, v88
	v_rcp_f32_e32 v120, v120
	v_add_co_u32_e32 v10, vcc, s14, v0
	v_max_f32_e32 v122, v122, v122
	v_fma_f32 v121, v117, v120, v116
	v_mul_f32_e32 v121, v152, v121
	v_addc_co_u32_e32 v11, vcc, 0, v1, vcc
	v_max_f32_e32 v121, 0xda24260, v121
	v_med3_f32 v122, v122, s9, v244
	v_add_co_u32_e32 v12, vcc, s27, v0
	v_rcp_f32_e32 v152, v121
	v_mul_f32_e32 v122, 0xbfb8aa3b, v122
	v_addc_co_u32_e32 v13, vcc, 0, v1, vcc
	v_exp_f32_e32 v122, v122
	v_add_co_u32_e32 v14, vcc, s7, v0
	v_mul_f32_e32 v88, v88, v120
	s_nop 0
	v_addc_co_u32_e32 v15, vcc, 0, v1, vcc
	v_mul_f32_e32 v88, v117, v88
	v_add_co_u32_e32 v8, vcc, s0, v0
	v_mul_f32_e32 v88, v88, v152
	global_load_ushort v132, v[0:1], off offset:2560
	global_load_ushort v136, v[2:3], off offset:3584
	global_load_ushort v138, v[4:5], off offset:512
	global_load_ushort v140, v[6:7], off offset:1536
	global_load_ushort v141, v[18:19], off offset:2560
	global_load_ushort v143, v[20:21], off offset:3584
	global_load_ushort v144, v[22:23], off offset:-4096
	global_load_ushort v142, v[4:5], off offset:-4096
	v_addc_co_u32_e32 v9, vcc, 0, v1, vcc
	global_load_ushort v157, v[146:147], off offset:2560
	global_load_ushort v150, v[146:147], off offset:3072
	global_load_ushort v151, v[106:107], off offset:2048
	global_load_ushort v149, v[102:103], off offset:1024
	global_load_ushort v148, v[100:101], off offset:3072
	s_nop 0
	global_load_ushort v146, v[10:11], off offset:2048
	global_load_ushort v147, v[12:13], off offset:1024
	global_load_ushort v145, v[8:9], off offset:3072
	v_bfe_u32 v120, v88, 16, 1
	v_add_f32_e32 v152, 1.0, v122
	v_add3_u32 v88, v88, v120, s10
	s_waitcnt vmcnt(53)
	v_lshlrev_b32_e32 v120, 16, v154
	v_rcp_f32_e32 v152, v152
	v_lshl_add_u32 v17, v16, 1, v92
	v_mul_f32_e32 v120, v121, v120
	ds_write_b16_d16_hi v17, v153 offset:4464
	v_bfe_u32 v153, v120, 16, 1
	v_add3_u32 v120, v120, v153, s10
	ds_write_b16_d16_hi v17, v120 offset:4320
	v_fma_f32 v120, v117, v152, v116
	v_mul_f32_e32 v120, v121, v120
	v_mul_f32_e32 v122, v122, v152
	s_waitcnt vmcnt(52)
	v_lshlrev_b32_e32 v152, 16, v155
	v_max_f32_e32 v120, 0xda24260, v120
	v_max_f32_e32 v152, v152, v152
	v_rcp_f32_e32 v121, v120
	v_med3_f32 v152, v152, s9, v244
	v_mul_f32_e32 v152, 0xbfb8aa3b, v152
	v_exp_f32_e32 v152, v152
	v_mul_f32_e32 v122, v117, v122
	v_mul_f32_e32 v121, v122, v121
	v_bfe_u32 v122, v121, 16, 1
	v_add3_u32 v153, v121, v122, s10
	v_add_f32_e32 v121, 1.0, v152
	v_lshlrev_b32_e32 v113, 16, v113
	v_rcp_f32_e32 v121, v121
	v_mul_f32_e32 v113, v120, v113
	v_bfe_u32 v122, v113, 16, 1
	v_add3_u32 v113, v113, v122, s10
	ds_write_b16_d16_hi v17, v113 offset:4176
	v_fma_f32 v113, v117, v121, v116
	s_waitcnt vmcnt(31)
	v_lshlrev_b32_e32 v122, 16, v173
	v_mul_f32_e32 v113, v120, v113
	v_max_f32_e32 v122, v122, v122
	v_max_f32_e32 v113, 0xda24260, v113
	v_med3_f32 v122, v122, s9, v244
	v_rcp_f32_e32 v120, v113
	v_mul_f32_e32 v122, 0xbfb8aa3b, v122
	v_exp_f32_e32 v122, v122
	v_mul_f32_e32 v121, v152, v121
	v_mul_f32_e32 v121, v117, v121
	v_mul_f32_e32 v120, v121, v120
	v_bfe_u32 v121, v120, 16, 1
	v_add_f32_e32 v152, 1.0, v122
	v_add3_u32 v120, v120, v121, s10
	v_lshlrev_b32_e32 v121, 16, v156
	v_rcp_f32_e32 v152, v152
	v_mul_f32_e32 v121, v113, v121
	v_bfe_u32 v154, v121, 16, 1
	v_add3_u32 v121, v121, v154, s10
	ds_write_b16_d16_hi v17, v121 offset:4032
	v_fma_f32 v121, v117, v152, v116
	v_mul_f32_e32 v113, v113, v121
	v_mul_f32_e32 v122, v122, v152
	s_waitcnt vmcnt(25)
	v_lshlrev_b32_e32 v152, 16, v177
	v_max_f32_e32 v113, 0xda24260, v113
	v_max_f32_e32 v152, v152, v152
	v_rcp_f32_e32 v121, v113
	v_med3_f32 v152, v152, s9, v244
	v_mul_f32_e32 v152, 0xbfb8aa3b, v152
	v_exp_f32_e32 v152, v152
	v_mul_f32_e32 v122, v117, v122
	v_mul_f32_e32 v121, v122, v121
	v_bfe_u32 v122, v121, 16, 1
	v_add3_u32 v154, v121, v122, s10
	v_add_f32_e32 v122, 1.0, v152
	v_lshlrev_b32_e32 v121, 16, v174
	v_rcp_f32_e32 v122, v122
	v_mul_f32_e32 v121, v113, v121
	v_bfe_u32 v155, v121, 16, 1
	v_add3_u32 v121, v121, v155, s10
	ds_write_b16_d16_hi v17, v121 offset:3888
	v_fma_f32 v121, v117, v122, v116
	v_mul_f32_e32 v122, v152, v122
	v_lshlrev_b32_e32 v152, 16, v162
	v_mul_f32_e32 v113, v113, v121
	v_max_f32_e32 v152, v152, v152
	v_max_f32_e32 v113, 0xda24260, v113
	v_med3_f32 v152, v152, s9, v244
	v_rcp_f32_e32 v121, v113
	v_mul_f32_e32 v152, 0xbfb8aa3b, v152
	v_exp_f32_e32 v152, v152
	v_mul_f32_e32 v122, v117, v122
	v_mul_f32_e32 v121, v122, v121
	v_bfe_u32 v122, v121, 16, 1
	v_add_f32_e32 v155, 1.0, v152
	v_add3_u32 v121, v121, v122, s10
	v_lshlrev_b32_e32 v122, 16, v159
	v_rcp_f32_e32 v155, v155
	v_mul_f32_e32 v122, v113, v122
	v_bfe_u32 v156, v122, 16, 1
	v_add3_u32 v122, v122, v156, s10
	ds_write_b16_d16_hi v17, v122 offset:3744
	v_fma_f32 v122, v117, v155, v116
	v_mul_f32_e32 v113, v113, v122
	v_mul_f32_e32 v152, v152, v155
	v_lshlrev_b32_e32 v155, 16, v166
	v_max_f32_e32 v113, 0xda24260, v113
	v_max_f32_e32 v155, v155, v155
	v_rcp_f32_e32 v122, v113
	v_med3_f32 v155, v155, s9, v244
	v_mul_f32_e32 v155, 0xbfb8aa3b, v155
	v_exp_f32_e32 v156, v155
	v_mul_f32_e32 v152, v117, v152
	v_mul_f32_e32 v122, v152, v122
	v_bfe_u32 v152, v122, 16, 1
	v_add3_u32 v155, v122, v152, s10
	v_add_f32_e32 v152, 1.0, v156
	v_lshlrev_b32_e32 v122, 16, v175
	v_rcp_f32_e32 v152, v152
	v_mul_f32_e32 v122, v113, v122
	v_bfe_u32 v159, v122, 16, 1
	v_add3_u32 v122, v122, v159, s10
	ds_write_b16_d16_hi v17, v122 offset:3600
	v_fma_f32 v122, v117, v152, v116
	v_mul_f32_e32 v113, v113, v122
	v_max_f32_e32 v113, 0xda24260, v113
	v_rcp_f32_e32 v122, v113
	v_mul_f32_e32 v152, v156, v152
	v_mul_f32_e32 v152, v117, v152
	ds_write_b16_d16_hi v17, v114 offset:9072
	v_mul_f32_e32 v122, v152, v122
	v_bfe_u32 v152, v122, 16, 1
	v_add3_u32 v122, v122, v152, s10
	v_lshlrev_b32_e32 v152, 16, v167
	v_mul_f32_e32 v152, v113, v152
	v_bfe_u32 v156, v152, 16, 1
	v_add3_u32 v152, v152, v156, s10
	ds_write_b16_d16_hi v17, v88 offset:8928
	ds_write_b16_d16_hi v17, v153 offset:8784
	ds_write_b16_d16_hi v17, v120 offset:8640
	ds_write_b16_d16_hi v17, v154 offset:8496
	ds_write_b16_d16_hi v17, v121 offset:8352
	ds_write_b16_d16_hi v17, v155 offset:8208
	ds_write_b16_d16_hi v17, v152 offset:3456
	ds_write_b16_d16_hi v17, v122 offset:8064
	s_waitcnt vmcnt(23)
	v_lshlrev_b32_e32 v152, 16, v178
	v_max_f32_e32 v152, v152, v152
	v_med3_f32 v152, v152, s9, v244
	v_mul_f32_e32 v152, 0xbfb8aa3b, v152
	v_exp_f32_e32 v152, v152
	v_lshlrev_b32_e32 v109, 16, v109
	v_add_f32_e32 v156, 1.0, v152
	v_rcp_f32_e32 v156, v156
	s_nop 0
	v_fma_f32 v159, v117, v156, v116
	v_mul_f32_e32 v113, v113, v159
	v_max_f32_e32 v113, 0xda24260, v113
	v_mul_f32_e32 v152, v152, v156
	v_rcp_f32_e32 v156, v113
	v_mul_f32_e32 v152, v117, v152
	v_mul_f32_e32 v152, v152, v156
	v_bfe_u32 v156, v152, 16, 1
	v_add3_u32 v156, v152, v156, s10
	v_lshlrev_b32_e32 v152, 16, v176
	v_mul_f32_e32 v152, v113, v152
	v_bfe_u32 v159, v152, 16, 1
	v_add3_u32 v152, v152, v159, s10
	ds_write_b16_d16_hi v17, v152 offset:3312
	ds_write_b16_d16_hi v17, v156 offset:7920
	v_lshlrev_b32_e32 v152, 16, v169
	v_max_f32_e32 v152, v152, v152
	v_med3_f32 v152, v152, s9, v244
	v_mul_f32_e32 v152, 0xbfb8aa3b, v152
	v_exp_f32_e32 v152, v152
	s_nop 0
	v_add_f32_e32 v159, 1.0, v152
	v_rcp_f32_e32 v159, v159
	s_nop 0
	v_fma_f32 v162, v117, v159, v116
	v_mul_f32_e32 v113, v113, v162
	v_max_f32_e32 v173, 0xda24260, v113
	v_rcp_f32_e32 v113, v173
	v_mul_f32_e32 v152, v152, v159
	v_mul_f32_e32 v152, v117, v152
	v_mul_f32_e32 v113, v152, v113
	v_bfe_u32 v152, v113, 16, 1
	v_add3_u32 v152, v113, v152, s10
	v_lshlrev_b32_e32 v113, 16, v172
	v_mul_f32_e32 v113, v173, v113
	v_bfe_u32 v159, v113, 16, 1
	v_add3_u32 v172, v113, v159, s10
	global_load_ushort v169, v[106:107], off offset:3072
	global_load_ushort v167, v[106:107], off offset:1536
	global_load_ushort v166, v[98:99], off offset:2560
	global_load_ushort v162, v[98:99], off offset:1024
	global_load_ushort v159, v[102:103], off offset:2048
	global_load_ushort v113, v[102:103], off offset:512
	s_nop 0
	global_load_ushort v107, v[22:23], off offset:1536
	global_load_ushort v106, v[22:23], off
	s_nop 0
	global_load_ushort v104, v[104:105], off offset:1024
	v_add_co_u32_e32 v22, vcc, s50, v0
	s_nop 1
	v_addc_co_u32_e32 v23, vcc, 0, v1, vcc
	global_load_ushort v103, v[22:23], off offset:3584
	global_load_ushort v102, v[22:23], off offset:512
	global_load_ushort v99, v[20:21], off offset:3072
	global_load_ushort v98, v[20:21], off
	s_nop 0
	global_load_ushort v21, v[100:101], off offset:2560
	global_load_ushort v20, v[18:19], off offset:3584
	s_nop 0
	global_load_ushort v19, v[18:19], off offset:2048
	s_waitcnt vmcnt(38)
	v_lshlrev_b32_e32 v18, 16, v171
	v_max_f32_e32 v18, v18, v18
	v_med3_f32 v18, v18, s9, v244
	v_mul_f32_e32 v18, 0xbfb8aa3b, v18
	v_exp_f32_e32 v18, v18
	ds_write_b16_d16_hi v17, v172 offset:3168
	ds_write_b16_d16_hi v17, v152 offset:7776
	v_add_f32_e32 v22, 1.0, v18
	v_rcp_f32_e32 v22, v22
	s_nop 0
	v_fma_f32 v23, v117, v22, v116
	v_mul_f32_e32 v18, v18, v22
	v_mul_f32_e32 v22, v173, v23
	v_max_f32_e32 v22, 0xda24260, v22
	v_rcp_f32_e32 v23, v22
	v_mul_f32_e32 v18, v117, v18
	v_mul_f32_e32 v18, v18, v23
	v_bfe_u32 v23, v18, 16, 1
	v_add3_u32 v23, v18, v23, s10
	s_waitcnt vmcnt(37)
	v_lshlrev_b32_e32 v18, 16, v170
	v_mul_f32_e32 v18, v22, v18
	v_bfe_u32 v100, v18, 16, 1
	v_add3_u32 v18, v18, v100, s10
	ds_write_b16_d16_hi v17, v18 offset:3024
	ds_write_b16_d16_hi v17, v23 offset:7632
	v_lshlrev_b32_e32 v18, 16, v168
	v_max_f32_e32 v18, v18, v18
	v_med3_f32 v18, v18, s9, v244
	v_mul_f32_e32 v18, 0xbfb8aa3b, v18
	v_exp_f32_e32 v18, v18
	s_nop 0
	v_add_f32_e32 v100, 1.0, v18
	v_rcp_f32_e32 v100, v100
	s_nop 0
	v_fma_f32 v101, v117, v100, v116
	v_mul_f32_e32 v22, v22, v101
	v_max_f32_e32 v22, 0xda24260, v22
	v_mul_f32_e32 v18, v18, v100
	v_rcp_f32_e32 v100, v22
	v_mul_f32_e32 v18, v117, v18
	v_mul_f32_e32 v18, v18, v100
	v_bfe_u32 v100, v18, 16, 1
	v_add3_u32 v18, v18, v100, s10
	v_lshlrev_b32_e32 v100, 16, v164
	v_mul_f32_e32 v100, v22, v100
	v_bfe_u32 v101, v100, 16, 1
	v_add3_u32 v100, v100, v101, s10
	ds_write_b16_d16_hi v17, v100 offset:2880
	ds_write_b16_d16_hi v17, v18 offset:7488
	s_waitcnt vmcnt(36)
	v_lshlrev_b32_e32 v100, 16, v165
	v_max_f32_e32 v100, v100, v100
	v_med3_f32 v100, v100, s9, v244
	v_mul_f32_e32 v100, 0xbfb8aa3b, v100
	v_exp_f32_e32 v100, v100
	s_nop 0
	v_add_f32_e32 v101, 1.0, v100
	v_rcp_f32_e32 v101, v101
	s_nop 0
	v_fma_f32 v105, v117, v101, v116
	v_mul_f32_e32 v22, v22, v105
	v_max_f32_e32 v22, 0xda24260, v22
	v_mul_f32_e32 v100, v100, v101
	v_rcp_f32_e32 v101, v22
	v_mul_f32_e32 v100, v117, v100
	v_mul_f32_e32 v100, v100, v101
	v_bfe_u32 v101, v100, 16, 1
	v_add3_u32 v101, v100, v101, s10
	s_waitcnt vmcnt(35)
	v_lshlrev_b32_e32 v100, 16, v163
	v_mul_f32_e32 v100, v22, v100
	v_bfe_u32 v105, v100, 16, 1
	v_add3_u32 v100, v100, v105, s10
	ds_write_b16_d16_hi v17, v100 offset:2736
	ds_write_b16_d16_hi v17, v101 offset:7344
	s_waitcnt vmcnt(34)
	v_lshlrev_b32_e32 v100, 16, v160
	v_max_f32_e32 v100, v100, v100
	v_med3_f32 v100, v100, s9, v244
	v_mul_f32_e32 v100, 0xbfb8aa3b, v100
	v_exp_f32_e32 v100, v100
	s_nop 0
	v_add_f32_e32 v105, 1.0, v100
	v_rcp_f32_e32 v105, v105
	s_nop 0
	v_fma_f32 v160, v117, v105, v116
	v_mul_f32_e32 v22, v22, v160
	v_mul_f32_e32 v100, v100, v105
	v_max_f32_e32 v105, 0xda24260, v22
	v_rcp_f32_e32 v22, v105
	v_mul_f32_e32 v100, v117, v100
	v_mul_f32_e32 v22, v100, v22
	v_bfe_u32 v100, v22, 16, 1
	v_add3_u32 v22, v22, v100, s10
	v_lshlrev_b32_e32 v100, 16, v158
	v_mul_f32_e32 v100, v105, v100
	v_bfe_u32 v158, v100, 16, 1
	v_add3_u32 v100, v100, v158, s10
	ds_write_b16_d16_hi v17, v100 offset:2592
	ds_write_b16_d16_hi v17, v22 offset:7200
	v_lshlrev_b32_e32 v100, 16, v115
	v_max_f32_e32 v100, v100, v100
	v_med3_f32 v100, v100, s9, v244
	v_mul_f32_e32 v100, 0xbfb8aa3b, v100
	v_exp_f32_e32 v100, v100
	s_nop 0
	v_add_f32_e32 v115, 1.0, v100
	v_rcp_f32_e32 v115, v115
	s_nop 0
	v_fma_f32 v158, v117, v115, v116
	v_mul_f32_e32 v105, v105, v158
	v_mul_f32_e32 v100, v100, v115
	v_max_f32_e32 v115, 0xda24260, v105
	v_rcp_f32_e32 v105, v115
	v_mul_f32_e32 v100, v117, v100
	v_mul_f32_e32 v100, v100, v105
	v_bfe_u32 v105, v100, 16, 1
	v_add3_u32 v105, v100, v105, s10
	s_waitcnt vmcnt(23)
	v_lshlrev_b32_e32 v100, 16, v157
	v_mul_f32_e32 v100, v115, v100
	v_bfe_u32 v157, v100, 16, 1
	v_add3_u32 v100, v100, v157, s10
	ds_write_b16_d16_hi v17, v100 offset:2448
	ds_write_b16_d16_hi v17, v105 offset:7056
	v_lshlrev_b32_e32 v100, 16, v111
	v_max_f32_e32 v100, v100, v100
	v_med3_f32 v100, v100, s9, v244
	v_mul_f32_e32 v100, 0xbfb8aa3b, v100
	v_exp_f32_e32 v100, v100
	s_nop 0
	v_add_f32_e32 v111, 1.0, v100
	v_rcp_f32_e32 v111, v111
	s_nop 0
	v_fma_f32 v157, v117, v111, v116
	v_mul_f32_e32 v100, v100, v111
	v_mul_f32_e32 v111, v115, v157
	v_max_f32_e32 v111, 0xda24260, v111
	v_rcp_f32_e32 v115, v111
	v_mul_f32_e32 v100, v117, v100
	v_mul_f32_e32 v109, v111, v109
	v_mul_f32_e32 v100, v100, v115
	v_bfe_u32 v115, v100, 16, 1
	v_add3_u32 v100, v100, v115, s10
	v_bfe_u32 v115, v109, 16, 1
	v_add3_u32 v109, v109, v115, s10
	ds_write_b16_d16_hi v17, v109 offset:2304
	ds_write_b16_d16_hi v17, v100 offset:6912
	s_waitcnt vmcnt(15)
	v_lshlrev_b32_e32 v109, 16, v169
	v_max_f32_e32 v109, v109, v109
	v_med3_f32 v109, v109, s9, v244
	v_mul_f32_e32 v109, 0xbfb8aa3b, v109
	v_exp_f32_e32 v109, v109
	s_nop 0
	v_add_f32_e32 v115, 1.0, v109
	v_rcp_f32_e32 v115, v115
	s_nop 0
	v_fma_f32 v157, v117, v115, v116
	v_mul_f32_e32 v111, v111, v157
	v_max_f32_e32 v111, 0xda24260, v111
	v_mul_f32_e32 v109, v109, v115
	v_rcp_f32_e32 v115, v111
	v_mul_f32_e32 v109, v117, v109
	v_mul_f32_e32 v109, v109, v115
	v_bfe_u32 v115, v109, 16, 1
	v_add3_u32 v109, v109, v115, s10
	s_waitcnt vmcnt(14)
	v_lshlrev_b32_e32 v115, 16, v167
	v_mul_f32_e32 v115, v111, v115
	v_bfe_u32 v157, v115, 16, 1
	v_add3_u32 v115, v115, v157, s10
	ds_write_b16_d16_hi v17, v115 offset:2160
	ds_write_b16_d16_hi v17, v109 offset:6768
	s_waitcnt vmcnt(13)
	v_lshlrev_b32_e32 v115, 16, v166
	v_max_f32_e32 v115, v115, v115
	v_med3_f32 v115, v115, s9, v244
	v_mul_f32_e32 v115, 0xbfb8aa3b, v115
	v_exp_f32_e32 v115, v115
	global_load_ushort v175, v[10:11], off offset:3072
	global_load_ushort v173, v[10:11], off offset:1536
	global_load_ushort v174, v[6:7], off offset:2560
	global_load_ushort v171, v[6:7], off offset:1024
	global_load_ushort v172, v[12:13], off offset:2048
	global_load_ushort v169, v[12:13], off offset:512
	global_load_ushort v170, v[4:5], off offset:1536
	global_load_ushort v166, v[4:5], off
	global_load_ushort v168, v[14:15], off offset:1024
	v_add_co_u32_e32 v4, vcc, s11, v0
	v_add_f32_e32 v157, 1.0, v115
	v_rcp_f32_e32 v157, v157
	v_addc_co_u32_e32 v5, vcc, 0, v1, vcc
	v_fma_f32 v158, v117, v157, v116
	v_mul_f32_e32 v111, v111, v158
	v_max_f32_e32 v111, 0xda24260, v111
	v_mul_f32_e32 v115, v115, v157
	v_rcp_f32_e32 v157, v111
	v_mul_f32_e32 v115, v117, v115
	v_mul_f32_e32 v115, v115, v157
	v_bfe_u32 v157, v115, 16, 1
	v_add3_u32 v157, v115, v157, s10
	s_waitcnt vmcnt(21)
	v_lshlrev_b32_e32 v115, 16, v162
	v_mul_f32_e32 v115, v111, v115
	v_bfe_u32 v158, v115, 16, 1
	v_add3_u32 v115, v115, v158, s10
	global_load_ushort v165, v[4:5], off offset:3584
	global_load_ushort v167, v[4:5], off offset:512
	global_load_ushort v163, v[2:3], off offset:3072
	global_load_ushort v164, v[2:3], off
	global_load_ushort v160, v[8:9], off offset:2560
	global_load_ushort v162, v[0:1], off offset:3584
	global_load_ushort v158, v[0:1], off offset:2048
	s_waitcnt vmcnt(27)
	v_lshlrev_b32_e32 v0, 16, v159
	v_max_f32_e32 v0, v0, v0
	v_med3_f32 v0, v0, s9, v244
	v_mul_f32_e32 v0, 0xbfb8aa3b, v0
	v_exp_f32_e32 v0, v0
	ds_write_b16_d16_hi v17, v115 offset:2016
	ds_write_b16_d16_hi v17, v157 offset:6624
	v_add_f32_e32 v1, 1.0, v0
	v_rcp_f32_e32 v1, v1
	s_nop 0
	v_fma_f32 v2, v117, v1, v116
	v_mul_f32_e32 v0, v0, v1
	v_mul_f32_e32 v1, v111, v2
	v_max_f32_e32 v1, 0xda24260, v1
	v_rcp_f32_e32 v2, v1
	v_mul_f32_e32 v0, v117, v0
	v_mul_f32_e32 v0, v0, v2
	v_bfe_u32 v2, v0, 16, 1
	v_add3_u32 v0, v0, v2, s10
	s_waitcnt vmcnt(26)
	v_lshlrev_b32_e32 v2, 16, v113
	v_mul_f32_e32 v2, v1, v2
	v_bfe_u32 v3, v2, 16, 1
	v_add3_u32 v2, v2, v3, s10
	ds_write_b16_d16_hi v17, v2 offset:1872
	ds_write_b16_d16_hi v17, v0 offset:6480
	s_waitcnt vmcnt(25)
	v_lshlrev_b32_e32 v2, 16, v107
	v_max_f32_e32 v2, v2, v2
	v_med3_f32 v2, v2, s9, v244
	v_mul_f32_e32 v2, 0xbfb8aa3b, v2
	v_exp_f32_e32 v2, v2
	s_nop 0
	v_add_f32_e32 v3, 1.0, v2
	v_rcp_f32_e32 v3, v3
	s_nop 0
	v_fma_f32 v4, v117, v3, v116
	v_mul_f32_e32 v1, v1, v4
	v_max_f32_e32 v1, 0xda24260, v1
	v_mul_f32_e32 v2, v2, v3
	v_rcp_f32_e32 v3, v1
	v_mul_f32_e32 v2, v117, v2
	v_mul_f32_e32 v2, v2, v3
	v_bfe_u32 v3, v2, 16, 1
	v_add3_u32 v159, v2, v3, s10
	s_waitcnt vmcnt(24)
	v_lshlrev_b32_e32 v2, 16, v106
	v_mul_f32_e32 v2, v1, v2
	v_bfe_u32 v3, v2, 16, 1
	v_add3_u32 v2, v2, v3, s10
	ds_write_b16_d16_hi v17, v2 offset:1728
	ds_write_b16_d16_hi v17, v159 offset:6336
	s_waitcnt vmcnt(23)
	v_lshlrev_b32_e32 v2, 16, v104
	v_max_f32_e32 v2, v2, v2
	v_med3_f32 v2, v2, s9, v244
	v_mul_f32_e32 v2, 0xbfb8aa3b, v2
	v_exp_f32_e32 v2, v2
	s_nop 0
	v_add_f32_e32 v3, 1.0, v2
	v_rcp_f32_e32 v3, v3
	s_nop 0
	v_fma_f32 v4, v117, v3, v116
	v_mul_f32_e32 v1, v1, v4
	v_max_f32_e32 v1, 0xda24260, v1
	v_mul_f32_e32 v2, v2, v3
	v_rcp_f32_e32 v3, v1
	v_mul_f32_e32 v2, v117, v2
	v_mul_f32_e32 v2, v2, v3
	v_bfe_u32 v3, v2, 16, 1
	v_add3_u32 v2, v2, v3, s10
	s_waitcnt vmcnt(22)
	v_lshlrev_b32_e32 v3, 16, v103
	v_mul_f32_e32 v3, v1, v3
	v_bfe_u32 v4, v3, 16, 1
	v_add3_u32 v3, v3, v4, s10
	ds_write_b16_d16_hi v17, v3 offset:1584
	ds_write_b16_d16_hi v17, v2 offset:6192
	s_waitcnt vmcnt(21)
	v_lshlrev_b32_e32 v3, 16, v102
	v_max_f32_e32 v3, v3, v3
	v_med3_f32 v3, v3, s9, v244
	v_mul_f32_e32 v3, 0xbfb8aa3b, v3
	v_exp_f32_e32 v3, v3
	s_nop 0
	v_add_f32_e32 v4, 1.0, v3
	v_rcp_f32_e32 v4, v4
	s_nop 0
	v_fma_f32 v5, v117, v4, v116
	v_mul_f32_e32 v1, v1, v5
	v_max_f32_e32 v1, 0xda24260, v1
	v_mul_f32_e32 v3, v3, v4
	v_rcp_f32_e32 v4, v1
	v_mul_f32_e32 v3, v117, v3
	v_mul_f32_e32 v3, v3, v4
	v_bfe_u32 v4, v3, 16, 1
	v_add3_u32 v102, v3, v4, s10
	s_waitcnt vmcnt(20)
	v_lshlrev_b32_e32 v3, 16, v99
	v_mul_f32_e32 v3, v1, v3
	v_bfe_u32 v4, v3, 16, 1
	v_add3_u32 v3, v3, v4, s10
	ds_write_b16_d16_hi v17, v3 offset:1440
	ds_write_b16_d16_hi v17, v102 offset:6048
	s_waitcnt vmcnt(19)
	v_lshlrev_b32_e32 v3, 16, v98
	v_max_f32_e32 v3, v3, v3
	v_med3_f32 v3, v3, s9, v244
	v_mul_f32_e32 v3, 0xbfb8aa3b, v3
	v_exp_f32_e32 v3, v3
	s_nop 0
	v_add_f32_e32 v4, 1.0, v3
	v_rcp_f32_e32 v4, v4
	s_nop 0
	v_fma_f32 v5, v117, v4, v116
	v_mul_f32_e32 v1, v1, v5
	v_max_f32_e32 v1, 0xda24260, v1
	v_mul_f32_e32 v3, v3, v4
	v_rcp_f32_e32 v4, v1
	v_mul_f32_e32 v3, v117, v3
	v_mul_f32_e32 v3, v3, v4
	v_bfe_u32 v4, v3, 16, 1
	v_add3_u32 v3, v3, v4, s10
	s_waitcnt vmcnt(18)
	v_lshlrev_b32_e32 v4, 16, v21
	v_mul_f32_e32 v4, v1, v4
	v_bfe_u32 v5, v4, 16, 1
	v_add3_u32 v4, v4, v5, s10
	ds_write_b16_d16_hi v17, v4 offset:1296
	ds_write_b16_d16_hi v17, v3 offset:5904
	s_waitcnt vmcnt(17)
	v_lshlrev_b32_e32 v4, 16, v20
	v_max_f32_e32 v4, v4, v4
	v_med3_f32 v4, v4, s9, v244
	v_mul_f32_e32 v4, 0xbfb8aa3b, v4
	v_exp_f32_e32 v4, v4
	s_nop 0
	v_add_f32_e32 v5, 1.0, v4
	v_rcp_f32_e32 v5, v5
	s_nop 0
	v_fma_f32 v6, v117, v5, v116
	v_mul_f32_e32 v1, v1, v6
	v_max_f32_e32 v12, 0xda24260, v1
	v_rcp_f32_e32 v1, v12
	v_mul_f32_e32 v4, v4, v5
	v_mul_f32_e32 v4, v117, v4
	v_mul_f32_e32 v1, v4, v1
	v_bfe_u32 v4, v1, 16, 1
	v_add3_u32 v20, v1, v4, s10
	s_waitcnt vmcnt(16)
	v_lshlrev_b32_e32 v1, 16, v19
	v_mul_f32_e32 v1, v12, v1
	v_bfe_u32 v4, v1, 16, 1
	v_add3_u32 v1, v1, v4, s10
	ds_write_b16_d16_hi v17, v1 offset:1152
	ds_write_b16_d16_hi v17, v20 offset:5760
	s_waitcnt vmcnt(15)
	v_lshlrev_b32_e32 v8, 16, v175
	v_max_f32_e32 v8, v8, v8
	v_med3_f32 v8, v8, s9, v244
	v_mul_f32_e32 v8, 0xbfb8aa3b, v8
	v_exp_f32_e32 v98, v8
	v_and_b32_e32 v113, 0xffff0000, v2
	v_lshl_or_b32 v2, v108, 16, v124
	v_and_b32_e32 v115, 0xffff0000, v3
	v_add_f32_e32 v13, 1.0, v98
	v_rcp_f32_e32 v104, v13
	v_lshl_or_b32 v3, v110, 16, v112
	v_lshl_or_b32 v11, v151, 16, v129
	v_and_b32_e32 v19, 0xffff0000, v114
	v_fma_f32 v106, v117, v104, v116
	v_mul_f32_e32 v12, v12, v106
	v_max_f32_e32 v106, 0xda24260, v12
	v_rcp_f32_e32 v108, v106
	v_mul_f32_e32 v98, v98, v104
	v_mul_f32_e32 v98, v117, v98
	v_lshl_or_b32 v7, v133, 16, v127
	v_mul_f32_e32 v98, v98, v108
	v_bfe_u32 v104, v98, 16, 1
	v_add3_u32 v98, v98, v104, s10
	s_waitcnt vmcnt(13)
	v_lshlrev_b32_e32 v104, 16, v174
	v_max_f32_e32 v104, v104, v104
	v_med3_f32 v104, v104, s9, v244
	v_mul_f32_e32 v104, 0xbfb8aa3b, v104
	v_exp_f32_e32 v104, v104
	v_lshlrev_b32_e32 v108, 16, v173
	v_mul_f32_e32 v108, v106, v108
	v_bfe_u32 v112, v108, 16, 1
	v_add_f32_e32 v110, 1.0, v104
	v_rcp_f32_e32 v110, v110
	v_add3_u32 v108, v108, v112, s10
	ds_write_b16_d16_hi v17, v108 offset:1008
	v_and_b32_e32 v129, 0xffff0000, v98
	v_fma_f32 v108, v117, v110, v116
	v_mul_f32_e32 v106, v106, v108
	v_max_f32_e32 v106, 0xda24260, v106
	v_rcp_f32_e32 v108, v106
	ds_write_b16_d16_hi v17, v98 offset:5616
	v_mul_f32_e32 v98, v104, v110
	v_mul_f32_e32 v98, v117, v98
	v_mul_f32_e32 v98, v98, v108
	s_waitcnt vmcnt(11)
	v_lshlrev_b32_e32 v108, 16, v172
	v_max_f32_e32 v108, v108, v108
	v_med3_f32 v108, v108, s9, v244
	v_mul_f32_e32 v108, 0xbfb8aa3b, v108
	v_exp_f32_e32 v108, v108
	v_bfe_u32 v104, v98, 16, 1
	v_add3_u32 v98, v98, v104, s10
	v_lshlrev_b32_e32 v104, 16, v171
	v_add_f32_e32 v110, 1.0, v108
	v_rcp_f32_e32 v110, v110
	v_mul_f32_e32 v104, v106, v104
	v_bfe_u32 v112, v104, 16, 1
	v_add3_u32 v104, v104, v112, s10
	ds_write_b16_d16_hi v17, v104 offset:864
	v_fma_f32 v104, v117, v110, v116
	v_mul_f32_e32 v104, v106, v104
	v_max_f32_e32 v104, 0xda24260, v104
	v_rcp_f32_e32 v106, v104
	v_mul_f32_e32 v108, v108, v110
	v_mul_f32_e32 v108, v117, v108
	s_waitcnt vmcnt(10)
	v_lshlrev_b32_e32 v110, 16, v169
	v_mul_f32_e32 v106, v108, v106
	v_bfe_u32 v108, v106, 16, 1
	v_add3_u32 v106, v106, v108, s10
	s_waitcnt vmcnt(9)
	v_lshlrev_b32_e32 v108, 16, v170
	v_max_f32_e32 v108, v108, v108
	v_med3_f32 v108, v108, s9, v244
	v_mul_f32_e32 v108, 0xbfb8aa3b, v108
	v_exp_f32_e32 v108, v108
	v_mul_f32_e32 v110, v104, v110
	v_bfe_u32 v114, v110, 16, 1
	v_add3_u32 v110, v110, v114, s10
	v_add_f32_e32 v112, 1.0, v108
	v_rcp_f32_e32 v112, v112
	ds_write_b16_d16_hi v17, v110 offset:720
	v_and_b32_e32 v127, 0xffff0000, v106
	ds_write_b16_d16_hi v17, v106 offset:5328
	v_fma_f32 v110, v117, v112, v116
	v_mul_f32_e32 v104, v104, v110
	v_max_f32_e32 v104, 0xda24260, v104
	v_rcp_f32_e32 v110, v104
	v_mul_f32_e32 v106, v108, v112
	v_mul_f32_e32 v106, v117, v106
	v_lshl_or_b32 v1, v135, 16, v123
	v_mul_f32_e32 v106, v106, v110
	s_waitcnt vmcnt(7)
	v_lshlrev_b32_e32 v110, 16, v168
	v_max_f32_e32 v110, v110, v110
	v_med3_f32 v110, v110, s9, v244
	v_mul_f32_e32 v110, 0xbfb8aa3b, v110
	v_exp_f32_e32 v110, v110
	v_bfe_u32 v108, v106, 16, 1
	v_add3_u32 v106, v106, v108, s10
	v_lshlrev_b32_e32 v108, 16, v166
	v_add_f32_e32 v112, 1.0, v110
	v_rcp_f32_e32 v112, v112
	v_mul_f32_e32 v108, v104, v108
	v_bfe_u32 v114, v108, 16, 1
	v_add3_u32 v108, v108, v114, s10
	ds_write_b16_d16_hi v17, v108 offset:576
	v_fma_f32 v108, v117, v112, v116
	v_mul_f32_e32 v104, v104, v108
	v_max_f32_e32 v104, 0xda24260, v104
	v_rcp_f32_e32 v108, v104
	v_mul_f32_e32 v110, v110, v112
	v_mul_f32_e32 v110, v117, v110
	s_waitcnt vmcnt(6)
	v_lshlrev_b32_e32 v112, 16, v165
	v_mul_f32_e32 v108, v110, v108
	v_bfe_u32 v110, v108, 16, 1
	v_add3_u32 v108, v108, v110, s10
	s_waitcnt vmcnt(5)
	v_lshlrev_b32_e32 v110, 16, v167
	v_max_f32_e32 v110, v110, v110
	v_med3_f32 v110, v110, s9, v244
	v_mul_f32_e32 v110, 0xbfb8aa3b, v110
	v_exp_f32_e32 v110, v110
	v_mul_f32_e32 v112, v104, v112
	v_bfe_u32 v123, v112, 16, 1
	v_add3_u32 v112, v112, v123, s10
	v_add_f32_e32 v114, 1.0, v110
	v_rcp_f32_e32 v114, v114
	ds_write_b16_d16_hi v17, v112 offset:432
	v_lshl_or_b32 v5, v137, 16, v131
	v_and_b32_e32 v131, 0xffff0000, v108
	v_fma_f32 v112, v117, v114, v116
	v_mul_f32_e32 v104, v104, v112
	v_max_f32_e32 v104, 0xda24260, v104
	v_rcp_f32_e32 v112, v104
	ds_write_b16_d16_hi v17, v108 offset:5040
	v_mul_f32_e32 v108, v110, v114
	v_mul_f32_e32 v108, v117, v108
	v_mul_f32_e32 v108, v108, v112
	s_waitcnt vmcnt(3)
	v_lshlrev_b32_e32 v112, 16, v164
	v_max_f32_e32 v112, v112, v112
	v_med3_f32 v112, v112, s9, v244
	v_mul_f32_e32 v112, 0xbfb8aa3b, v112
	v_exp_f32_e32 v112, v112
	v_bfe_u32 v110, v108, 16, 1
	v_add3_u32 v108, v108, v110, s10
	v_lshlrev_b32_e32 v110, 16, v163
	v_add_f32_e32 v114, 1.0, v112
	v_rcp_f32_e32 v114, v114
	v_mul_f32_e32 v110, v104, v110
	v_bfe_u32 v123, v110, 16, 1
	v_add3_u32 v110, v110, v123, s10
	ds_write_b16_d16_hi v17, v110 offset:288
	v_fma_f32 v110, v117, v114, v116
	v_mul_f32_e32 v104, v104, v110
	v_max_f32_e32 v104, 0xda24260, v104
	v_rcp_f32_e32 v110, v104
	v_mul_f32_e32 v112, v112, v114
	v_mul_f32_e32 v112, v117, v112
	s_waitcnt vmcnt(2)
	v_lshlrev_b32_e32 v114, 16, v160
	v_mul_f32_e32 v110, v112, v110
	v_bfe_u32 v112, v110, 16, 1
	v_add3_u32 v110, v110, v112, s10
	s_waitcnt vmcnt(1)
	v_lshlrev_b32_e32 v112, 16, v162
	v_max_f32_e32 v112, v112, v112
	v_med3_f32 v112, v112, s9, v244
	v_mul_f32_e32 v112, 0xbfb8aa3b, v112
	v_exp_f32_e32 v112, v112
	v_mul_f32_e32 v114, v104, v114
	v_bfe_u32 v124, v114, 16, 1
	v_add3_u32 v114, v114, v124, s10
	v_add_f32_e32 v123, 1.0, v112
	v_rcp_f32_e32 v123, v123
	ds_write_b16_d16_hi v17, v114 offset:144
	v_lshl_or_b32 v12, v145, 16, v132
	v_lshl_or_b32 v6, v139, 16, v125
	v_fma_f32 v114, v117, v123, v116
	v_mul_f32_e32 v104, v104, v114
	v_max_f32_e32 v132, 0xda24260, v104
	v_rcp_f32_e32 v104, v132
	v_and_b32_e32 v125, 0xffff0000, v110
	ds_write_b16_d16_hi v17, v110 offset:4752
	v_mul_f32_e32 v110, v112, v123
	v_mul_f32_e32 v110, v117, v110
	v_mul_f32_e32 v104, v110, v104
	v_bfe_u32 v110, v104, 16, 1
	v_add3_u32 v104, v104, v110, s10
	s_waitcnt vmcnt(0)
	v_lshlrev_b32_e32 v110, 16, v158
	v_mul_f32_e32 v110, v132, v110
	v_bfe_u32 v112, v110, 16, 1
	v_add3_u32 v110, v110, v112, s10
	v_and_b32_e32 v111, 0xffff0000, v0
	v_and_b32_e32 v109, 0xffff0000, v109
	v_and_b32_e32 v107, 0xffff0000, v105
	v_and_b32_e32 v105, 0xffff0000, v101
	v_and_b32_e32 v103, 0xffff0000, v23
	v_and_b32_e32 v101, 0xffff0000, v156
	v_and_b32_e32 v99, 0xffff0000, v155
	v_and_b32_e32 v23, 0xffff0000, v154
	v_and_b32_e32 v21, 0xffff0000, v153
	v_lshl_or_b32 v0, v134, 16, v128
	v_lshl_or_b32 v4, v150, 16, v130
	v_lshl_or_b32 v10, v149, 16, v126
	v_lshl_or_b32 v9, v144, 16, v143
	v_lshl_or_b32 v8, v148, 16, v141
	v_lshl_or_b32 v15, v146, 16, v140
	v_lshl_or_b32 v14, v147, 16, v138
	v_lshl_or_b32 v13, v142, 16, v136
	ds_write_b16_d16_hi v17, v98 offset:5472
	ds_write_b16_d16_hi v17, v106 offset:5184
	ds_write_b16_d16_hi v17, v108 offset:4896
	ds_write_b16_d16_hi v17, v110
	ds_write_b16_d16_hi v17, v104 offset:4608
	v_and_b32_e32 v124, 0xffff0000, v104
	v_and_b32_e32 v130, 0xffff0000, v108
	v_and_b32_e32 v126, 0xffff0000, v106
	v_and_b32_e32 v128, 0xffff0000, v98
	s_movk_i32 s0, 0x50
	v_pk_mul_f32 v[124:125], v[132:133], v[124:125] op_sel_hi:[0,1]
	v_pk_mul_f32 v[130:131], v[132:133], v[130:131] op_sel_hi:[0,1]
	v_pk_mul_f32 v[126:127], v[132:133], v[126:127] op_sel_hi:[0,1]
	v_pk_mul_f32 v[128:129], v[132:133], v[128:129] op_sel_hi:[0,1]
	v_and_b32_e32 v114, 0xffff0000, v20
	v_and_b32_e32 v112, 0xffff0000, v102
	v_and_b32_e32 v110, 0xffff0000, v159
	v_and_b32_e32 v108, 0xffff0000, v157
	v_and_b32_e32 v106, 0xffff0000, v100
	v_and_b32_e32 v104, 0xffff0000, v22
	v_and_b32_e32 v102, 0xffff0000, v18
	v_and_b32_e32 v100, 0xffff0000, v152
	v_and_b32_e32 v98, 0xffff0000, v122
	v_and_b32_e32 v22, 0xffff0000, v121
	v_and_b32_e32 v20, 0xffff0000, v120
	v_and_b32_e32 v18, 0xffff0000, v88
	v_mad_u64_u32 v[134:135], s[2:3], v16, s0, v[92:93]
	v_cvt_pk_bf16_f32 v124, v124, v125
	v_cvt_pk_bf16_f32 v125, v130, v131
	v_cvt_pk_bf16_f32 v126, v126, v127
	v_cvt_pk_bf16_f32 v127, v128, v129
	v_pk_mul_f32 v[114:115], v[132:133], v[114:115] op_sel_hi:[0,1]
	v_pk_mul_f32 v[112:113], v[132:133], v[112:113] op_sel_hi:[0,1]
	v_pk_mul_f32 v[110:111], v[132:133], v[110:111] op_sel_hi:[0,1]
	v_pk_mul_f32 v[108:109], v[132:133], v[108:109] op_sel_hi:[0,1]
	v_pk_mul_f32 v[106:107], v[132:133], v[106:107] op_sel_hi:[0,1]
	v_pk_mul_f32 v[104:105], v[132:133], v[104:105] op_sel_hi:[0,1]
	v_pk_mul_f32 v[102:103], v[132:133], v[102:103] op_sel_hi:[0,1]
	v_pk_mul_f32 v[100:101], v[132:133], v[100:101] op_sel_hi:[0,1]
	v_pk_mul_f32 v[98:99], v[132:133], v[98:99] op_sel_hi:[0,1]
	v_pk_mul_f32 v[22:23], v[132:133], v[22:23] op_sel_hi:[0,1]
	v_pk_mul_f32 v[20:21], v[132:133], v[20:21] op_sel_hi:[0,1]
	v_pk_mul_f32 v[18:19], v[132:133], v[18:19] op_sel_hi:[0,1]
	ds_write_b128 v134, v[124:127] offset:9216
	v_cvt_pk_bf16_f32 v124, v114, v115
	v_cvt_pk_bf16_f32 v125, v112, v113
	v_cvt_pk_bf16_f32 v126, v110, v111
	v_cvt_pk_bf16_f32 v127, v108, v109
	v_cvt_pk_bf16_f32 v106, v106, v107
	v_cvt_pk_bf16_f32 v107, v104, v105
	v_cvt_pk_bf16_f32 v108, v102, v103
	v_cvt_pk_bf16_f32 v109, v100, v101
	v_cvt_pk_bf16_f32 v98, v98, v99
	v_cvt_pk_bf16_f32 v99, v22, v23
	v_cvt_pk_bf16_f32 v100, v20, v21
	v_cvt_pk_bf16_f32 v101, v18, v19
	v_lshl_add_u32 v16, v16, 2, v92
	ds_write_b128 v134, v[124:127] offset:9232
	ds_write_b128 v134, v[106:109] offset:9248
	ds_write_b128 v134, v[98:101] offset:9264
	ds_write_b32 v16, v132 offset:19456
	ds_write_b128 v134, v[12:15] offset:14336
	ds_write_b128 v134, v[8:11] offset:14352
	ds_write_b128 v134, v[4:7] offset:14368
	ds_write_b128 v134, v[0:3] offset:14384
	s_waitcnt lgkmcnt(0)
	v_or_b32_e32 v88, v95, v118
	v_lshlrev_b64 v[0:1], 11, v[88:89]
	v_lshlrev_b32_e32 v100, 2, v119
	v_lshl_add_u64 v[0:1], s[40:41], 0, v[0:1]
	v_ashrrev_i32_e32 v101, 31, v100
	v_mad_u32_u24 v106, v118, s48, v92
	v_lshlrev_b32_e32 v95, 4, v119
	v_lshl_add_u64 v[0:1], v[0:1], 0, v[90:91]
	v_lshlrev_b64 v[102:103], 1, v[100:101]
	v_add_u32_e32 v107, v106, v95
	v_lshl_add_u64 v[104:105], v[0:1], 0, v[102:103]
	ds_read_b128 v[0:3], v107 offset:4608
	ds_read_b128 v[4:7], v107
	ds_read_b128 v[16:19], v107 offset:32
	ds_read_b128 v[20:23], v107 offset:4640
	s_waitcnt lgkmcnt(2)
	v_mfma_f32_32x32x16_bf16 v[0:15], v[0:3], v[4:7], 0
	v_cmp_ge_i32_e32 vcc, v100, v118
	v_cvt_pk_bf16_f32 v120, v32, v33
	v_cvt_pk_bf16_f32 v121, v34, v35
	v_cvt_pk_bf16_f32 v122, v36, v37
	v_cvt_pk_bf16_f32 v123, v38, v39
	v_lshl_add_u64 v[98:99], v[104:105], 0, s[4:5]
	s_waitcnt lgkmcnt(0)
	v_mfma_f32_32x32x16_bf16 v[0:15], v[20:23], v[16:19], v[0:15]
	ds_read_b128 v[16:19], v107 offset:4672
	ds_read_b128 v[20:23], v107 offset:64
	s_waitcnt lgkmcnt(0)
	v_mfma_f32_32x32x16_bf16 v[0:15], v[16:19], v[20:23], v[0:15]
	ds_read_b128 v[16:19], v107 offset:4704
	ds_read_b128 v[20:23], v107 offset:96
	s_waitcnt lgkmcnt(0)
	v_mfma_f32_32x32x16_bf16 v[0:15], v[16:19], v[20:23], v[0:15]
	v_or_b32_e32 v16, 1, v100
	s_nop 10
	v_cndmask_b32_e32 v0, 0, v0, vcc
	v_cmp_ge_i32_e32 vcc, v16, v118
	v_or_b32_e32 v16, 2, v100
	s_nop 0
	v_cndmask_b32_e32 v1, 0, v1, vcc
	v_cmp_ge_i32_e32 vcc, v16, v118
	v_or_b32_e32 v16, 3, v100
	s_nop 0
	v_cndmask_b32_e32 v2, 0, v2, vcc
	v_cmp_ge_i32_e32 vcc, v16, v118
	v_add_u32_e32 v16, 8, v100
	s_nop 0
	v_cndmask_b32_e32 v3, 0, v3, vcc
	v_cmp_ge_i32_e32 vcc, v16, v118
	v_add_u32_e32 v16, 9, v100
	v_cvt_pk_bf16_f32 v17, v2, v3
	v_cndmask_b32_e32 v4, 0, v4, vcc
	v_cmp_ge_i32_e32 vcc, v16, v118
	v_add_u32_e32 v16, 10, v100
	s_nop 0
	v_cndmask_b32_e32 v5, 0, v5, vcc
	v_cmp_ge_i32_e32 vcc, v16, v118
	v_add_u32_e32 v16, 11, v100
	v_cvt_pk_bf16_f32 v18, v4, v5
	v_cndmask_b32_e32 v6, 0, v6, vcc
	v_cmp_ge_i32_e32 vcc, v16, v118
	v_add_u32_e32 v16, 16, v100
	s_nop 0
	v_cndmask_b32_e32 v7, 0, v7, vcc
	v_cmp_ge_i32_e32 vcc, v16, v118
	v_add_u32_e32 v16, 17, v100
	v_cvt_pk_bf16_f32 v19, v6, v7
	v_cndmask_b32_e32 v8, 0, v8, vcc
	v_cmp_ge_i32_e32 vcc, v16, v118
	v_add_u32_e32 v16, 18, v100
	s_nop 0
	v_cndmask_b32_e32 v9, 0, v9, vcc
	v_cmp_ge_i32_e32 vcc, v16, v118
	v_add_u32_e32 v16, 19, v100
	v_cvt_pk_bf16_f32 v20, v8, v9
	v_cndmask_b32_e32 v10, 0, v10, vcc
	v_cmp_ge_i32_e32 vcc, v16, v118
	v_add_u32_e32 v16, 24, v100
	s_nop 0
	v_cndmask_b32_e32 v11, 0, v11, vcc
	v_cmp_ge_i32_e32 vcc, v16, v118
	v_add_u32_e32 v16, 25, v100
	v_cvt_pk_bf16_f32 v21, v10, v11
	v_cndmask_b32_e32 v12, 0, v12, vcc
	v_cmp_ge_i32_e32 vcc, v16, v118
	v_add_u32_e32 v16, 26, v100
	s_nop 0
	v_cndmask_b32_e32 v13, 0, v13, vcc
	v_cmp_ge_i32_e32 vcc, v16, v118
	v_add_u32_e32 v16, 27, v100
	v_cvt_pk_bf16_f32 v22, v12, v13
	v_cndmask_b32_e32 v14, 0, v14, vcc
	v_cmp_ge_i32_e32 vcc, v16, v118
	v_cvt_pk_bf16_f32 v16, v0, v1
	v_lshlrev_b32_e32 v0, 3, v119
	v_mul_u32_u24_e32 v1, 0x50, v118
	v_add3_u32 v107, v92, v0, v1
	v_add_u32_e32 v4, 0x3800, v107
	v_add_u32_e32 v106, v106, v0
	ds_read2_b64 v[0:3], v4 offset1:2
	ds_read2_b64 v[108:111], v4 offset0:4 offset1:6
	v_cndmask_b32_e32 v15, 0, v15, vcc
	v_cvt_pk_bf16_f32 v23, v14, v15
	s_waitcnt lgkmcnt(1)
	v_mfma_f32_32x32x16_bf16 v[0:15], v[0:3], v[16:19], 0
	v_add_co_u32_e32 v104, vcc, s6, v104
	s_nop 1
	v_addc_co_u32_e32 v105, vcc, 0, v105, vcc
	s_waitcnt lgkmcnt(0)
	v_mfma_f32_32x32x16_bf16 v[0:15], v[108:111], v[20:23], v[0:15]
	ds_read2_b64 v[108:111], v106 offset1:2
	ds_read2_b64 v[112:115], v106 offset0:4 offset1:6
	s_waitcnt lgkmcnt(1)
	v_mfma_f32_32x32x16_bf16 v[0:15], v[120:123], v[108:111], v[0:15]
	v_cvt_pk_bf16_f32 v108, v40, v41
	v_cvt_pk_bf16_f32 v109, v42, v43
	v_cvt_pk_bf16_f32 v110, v44, v45
	v_cvt_pk_bf16_f32 v111, v46, v47
	s_waitcnt lgkmcnt(0)
	s_nop 0
	v_mfma_f32_32x32x16_bf16 v[0:15], v[108:111], v[112:115], v[0:15]
	ds_read2_b64 v[108:111], v106 offset0:8 offset1:10
	v_cvt_pk_bf16_f32 v112, v54, v55
	v_cvt_pk_bf16_f32 v113, v50, v51
	v_cvt_pk_bf16_f32 v114, v52, v53
	v_cvt_pk_bf16_f32 v115, v82, v83
	s_waitcnt lgkmcnt(0)
	s_nop 0
	v_mfma_f32_32x32x16_bf16 v[0:15], v[112:115], v[108:111], v[0:15]
	ds_read2_b64 v[108:111], v106 offset0:12 offset1:14
	v_cvt_pk_bf16_f32 v112, v56, v57
	v_cvt_pk_bf16_f32 v113, v58, v59
	v_cvt_pk_bf16_f32 v114, v60, v61
	v_cvt_pk_bf16_f32 v115, v62, v63
	s_waitcnt lgkmcnt(0)
	s_nop 0
	v_mfma_f32_32x32x16_bf16 v[0:15], v[112:115], v[108:111], v[0:15]
	global_load_dwordx2 v[108:109], v[104:105], off offset:1536
	s_waitcnt vmcnt(0)
	v_lshlrev_b32_e32 v110, 16, v108
	v_and_b32_e32 v111, 0xffff0000, v108
	s_nop 7
	v_pk_add_f32 v[0:1], v[0:1], v[110:111]
	v_lshlrev_b32_e32 v108, 16, v109
	v_and_b32_e32 v109, 0xffff0000, v109
	v_pk_add_f32 v[2:3], v[2:3], v[108:109]
	v_mul_f32_e32 v108, v1, v1
	v_pk_fma_f32 v[108:109], v[0:1], v[0:1], v[108:109] op_sel_hi:[1,1,0]
	v_cvt_pk_bf16_f32 v0, v0, v1
	v_cvt_pk_bf16_f32 v1, v2, v3
	global_store_dwordx2 v[104:105], v[0:1], off offset:1536
	global_load_dwordx2 v[0:1], v[98:99], off offset:16
	v_mul_f32_e32 v110, v3, v3
	v_pk_fma_f32 v[110:111], v[2:3], v[2:3], v[110:111] op_sel_hi:[1,1,0]
	s_waitcnt vmcnt(0)
	v_lshlrev_b32_e32 v2, 16, v0
	v_and_b32_e32 v3, 0xffff0000, v0
	v_lshlrev_b32_e32 v0, 16, v1
	v_and_b32_e32 v1, 0xffff0000, v1
	v_pk_add_f32 v[2:3], v[4:5], v[2:3]
	v_pk_add_f32 v[0:1], v[6:7], v[0:1]
	v_mul_f32_e32 v4, v3, v3
	v_mul_f32_e32 v6, v1, v1
	v_pk_fma_f32 v[4:5], v[2:3], v[2:3], v[4:5] op_sel_hi:[1,1,0]
	v_pk_fma_f32 v[6:7], v[0:1], v[0:1], v[6:7] op_sel_hi:[1,1,0]
	v_cvt_pk_bf16_f32 v2, v2, v3
	v_cvt_pk_bf16_f32 v3, v0, v1
	global_load_dwordx2 v[0:1], v[98:99], off offset:32
	v_pk_add_f32 v[4:5], v[4:5], v[6:7]
	global_store_dwordx2 v[98:99], v[2:3], off offset:16
	v_pk_add_f32 v[108:109], v[108:109], v[110:111]
	s_waitcnt vmcnt(1)
	v_lshlrev_b32_e32 v2, 16, v0
	v_and_b32_e32 v3, 0xffff0000, v0
	v_pk_add_f32 v[2:3], v[8:9], v[2:3]
	v_lshlrev_b32_e32 v0, 16, v1
	v_and_b32_e32 v1, 0xffff0000, v1
	v_pk_add_f32 v[6:7], v[10:11], v[0:1]
	v_mul_f32_e32 v0, v3, v3
	v_pk_fma_f32 v[0:1], v[2:3], v[2:3], v[0:1] op_sel_hi:[1,1,0]
	v_cvt_pk_bf16_f32 v2, v2, v3
	v_cvt_pk_bf16_f32 v3, v6, v7
	global_store_dwordx2 v[98:99], v[2:3], off offset:32
	global_load_dwordx2 v[2:3], v[98:99], off offset:48
	v_mul_f32_e32 v8, v7, v7
	v_pk_fma_f32 v[8:9], v[6:7], v[6:7], v[8:9] op_sel_hi:[1,1,0]
	v_pk_add_f32 v[4:5], v[108:109], v[4:5]
	v_pk_add_f32 v[0:1], v[0:1], v[8:9]
	s_nop 0
	v_pk_add_f32 v[0:1], v[4:5], v[0:1]
	s_waitcnt vmcnt(0)
	v_lshlrev_b32_e32 v4, 16, v2
	v_and_b32_e32 v5, 0xffff0000, v2
	v_lshlrev_b32_e32 v2, 16, v3
	v_and_b32_e32 v3, 0xffff0000, v3
	v_pk_add_f32 v[4:5], v[12:13], v[4:5]
	v_pk_add_f32 v[2:3], v[14:15], v[2:3]
	v_mul_f32_e32 v6, v5, v5
	v_mul_f32_e32 v8, v3, v3
	v_pk_fma_f32 v[6:7], v[4:5], v[4:5], v[6:7] op_sel_hi:[1,1,0]
	v_pk_fma_f32 v[8:9], v[2:3], v[2:3], v[8:9] op_sel_hi:[1,1,0]
	s_nop 0
	v_pk_add_f32 v[6:7], v[6:7], v[8:9]
	s_nop 0
	v_pk_add_f32 v[112:113], v[0:1], v[6:7]
	v_cvt_pk_bf16_f32 v0, v4, v5
	v_cvt_pk_bf16_f32 v1, v2, v3
	global_store_dwordx2 v[98:99], v[0:1], off offset:48
	v_add_u32_e32 v4, 0x4000, v107
	ds_read2_b64 v[0:3], v4 offset0:64 offset1:66
	ds_read2_b64 v[108:111], v4 offset0:68 offset1:70
	s_waitcnt lgkmcnt(1)
	v_mfma_f32_32x32x16_bf16 v[0:15], v[0:3], v[16:19], 0
	s_waitcnt lgkmcnt(0)
	v_mfma_f32_32x32x16_bf16 v[0:15], v[108:111], v[20:23], v[0:15]
	v_cvt_pk_bf16_f32 v108, v26, v27
	v_cvt_pk_bf16_f32 v109, v28, v29
	v_cvt_pk_bf16_f32 v110, v30, v31
	v_cvt_pk_bf16_f32 v111, v48, v49
	ds_read2_b64 v[16:19], v106 offset1:2
	ds_read2_b64 v[20:23], v106 offset0:4 offset1:6
	s_waitcnt lgkmcnt(1)
	v_mfma_f32_32x32x16_bf16 v[0:15], v[108:111], v[16:19], v[0:15]
	v_cvt_pk_bf16_f32 v16, v24, v25
	v_cvt_pk_bf16_f32 v17, v84, v85
	v_cvt_pk_bf16_f32 v18, v86, v87
	v_cvt_pk_bf16_f32 v19, v96, v97
	s_waitcnt lgkmcnt(0)
	s_nop 0
	v_mfma_f32_32x32x16_bf16 v[0:15], v[16:19], v[20:23], v[0:15]
	ds_read2_b64 v[16:19], v106 offset0:8 offset1:10
	v_cvt_pk_bf16_f32 v20, v66, v67
	v_cvt_pk_bf16_f32 v21, v68, v69
	v_cvt_pk_bf16_f32 v22, v70, v71
	v_cvt_pk_bf16_f32 v23, v72, v73
	s_waitcnt lgkmcnt(0)
	s_nop 0
	v_mfma_f32_32x32x16_bf16 v[0:15], v[20:23], v[16:19], v[0:15]
	ds_read2_b64 v[16:19], v106 offset0:12 offset1:14
	v_cvt_pk_bf16_f32 v20, v74, v75
	v_cvt_pk_bf16_f32 v21, v76, v77
	v_cvt_pk_bf16_f32 v22, v78, v79
	v_cvt_pk_bf16_f32 v23, v80, v81
	s_waitcnt lgkmcnt(0)
	s_nop 0
	v_mfma_f32_32x32x16_bf16 v[0:15], v[20:23], v[16:19], v[0:15]
	global_load_dwordx2 v[16:17], v[98:99], off offset:64
	s_waitcnt vmcnt(0)
	v_lshlrev_b32_e32 v18, 16, v16
	v_and_b32_e32 v19, 0xffff0000, v16
	s_nop 7
	v_pk_add_f32 v[0:1], v[0:1], v[18:19]
	v_lshlrev_b32_e32 v16, 16, v17
	v_and_b32_e32 v17, 0xffff0000, v17
	v_pk_add_f32 v[2:3], v[2:3], v[16:17]
	v_mul_f32_e32 v16, v1, v1
	v_pk_fma_f32 v[16:17], v[0:1], v[0:1], v[16:17] op_sel_hi:[1,1,0]
	v_cvt_pk_bf16_f32 v0, v0, v1
	v_cvt_pk_bf16_f32 v1, v2, v3
	global_store_dwordx2 v[98:99], v[0:1], off offset:64
	global_load_dwordx2 v[0:1], v[98:99], off offset:80
	v_mul_f32_e32 v18, v3, v3
	v_pk_fma_f32 v[18:19], v[2:3], v[2:3], v[18:19] op_sel_hi:[1,1,0]
	s_waitcnt vmcnt(0)
	v_lshlrev_b32_e32 v2, 16, v0
	v_and_b32_e32 v3, 0xffff0000, v0
	v_lshlrev_b32_e32 v0, 16, v1
	v_and_b32_e32 v1, 0xffff0000, v1
	v_pk_add_f32 v[2:3], v[4:5], v[2:3]
	v_pk_add_f32 v[0:1], v[6:7], v[0:1]
	v_mul_f32_e32 v4, v3, v3
	v_mul_f32_e32 v6, v1, v1
	v_pk_fma_f32 v[4:5], v[2:3], v[2:3], v[4:5] op_sel_hi:[1,1,0]
	v_pk_fma_f32 v[6:7], v[0:1], v[0:1], v[6:7] op_sel_hi:[1,1,0]
	v_cvt_pk_bf16_f32 v2, v2, v3
	v_cvt_pk_bf16_f32 v3, v0, v1
	global_load_dwordx2 v[0:1], v[98:99], off offset:96
	v_pk_add_f32 v[4:5], v[4:5], v[6:7]
	global_store_dwordx2 v[98:99], v[2:3], off offset:80
	v_pk_add_f32 v[16:17], v[16:17], v[18:19]
	s_waitcnt vmcnt(1)
	v_lshlrev_b32_e32 v2, 16, v0
	v_and_b32_e32 v3, 0xffff0000, v0
	v_lshlrev_b32_e32 v0, 16, v1
	v_and_b32_e32 v1, 0xffff0000, v1
	v_pk_add_f32 v[2:3], v[8:9], v[2:3]
	v_pk_add_f32 v[6:7], v[10:11], v[0:1]
	v_mov_b32_e32 v0, v2
	v_mov_b32_e32 v8, v3
	v_cvt_pk_bf16_f32 v2, v2, v3
	v_cvt_pk_bf16_f32 v3, v6, v7
	global_store_dwordx2 v[98:99], v[2:3], off offset:96
	global_load_dwordx2 v[2:3], v[98:99], off offset:112
	v_mov_b32_e32 v9, v7
	v_mov_b32_e32 v1, v6
	v_pk_mul_f32 v[8:9], v[8:9], v[8:9]
	v_pk_add_f32 v[16:17], v[112:113], v[16:17]
	v_pk_fma_f32 v[0:1], v[0:1], v[0:1], v[8:9]
	v_pk_add_f32 v[4:5], v[16:17], v[4:5]
	v_pk_add_f32 v[0:1], v[0:1], v[0:1] op_sel:[0,1] op_sel_hi:[1,0]
	s_nop 0
	v_pk_add_f32 v[0:1], v[4:5], v[0:1]
	s_waitcnt vmcnt(0)
	v_lshlrev_b32_e32 v4, 16, v2
	v_and_b32_e32 v5, 0xffff0000, v2
	v_lshlrev_b32_e32 v2, 16, v3
	v_and_b32_e32 v3, 0xffff0000, v3
	v_pk_add_f32 v[4:5], v[12:13], v[4:5]
	v_pk_add_f32 v[2:3], v[14:15], v[2:3]
	v_mov_b32_e32 v8, v5
	v_mov_b32_e32 v9, v3
	v_mov_b32_e32 v6, v4
	v_mov_b32_e32 v7, v2
	v_pk_mul_f32 v[8:9], v[8:9], v[8:9]
	s_nop 0
	v_pk_fma_f32 v[6:7], v[6:7], v[6:7], v[8:9]
	s_nop 0
	v_pk_add_f32 v[6:7], v[6:7], v[6:7] op_sel:[0,1] op_sel_hi:[1,0]
	s_nop 0
	v_pk_add_f32 v[114:115], v[0:1], v[6:7]
	v_cvt_pk_bf16_f32 v0, v4, v5
	v_cvt_pk_bf16_f32 v1, v2, v3
	global_store_dwordx2 v[98:99], v[0:1], off offset:112
	v_add_u32_e32 v95, v92, v95
	v_mad_u32_u24 v115, v118, s0, v95
	ds_read_b128 v[0:3], v95 offset:19456
	ds_read_b128 v[4:7], v95 offset:19488
	ds_read_b128 v[8:11], v95 offset:19520
	ds_read_b128 v[12:15], v95 offset:19552
	ds_read_b128 v[16:19], v115 offset:9216
	ds_read_b128 v[20:23], v115 offset:14336
	ds_read_b128 v[106:109], v115 offset:9248
	ds_read_b128 v[110:113], v115 offset:14368
	ds_read_b128 v[118:121], v115 offset:16896
	s_waitcnt lgkmcnt(8)
	v_pk_mul_f32 v[34:35], v[2:3], v[34:35]
	v_pk_mul_f32 v[32:33], v[0:1], v[32:33]
	s_waitcnt lgkmcnt(7)
	v_pk_mul_f32 v[38:39], v[6:7], v[38:39]
	v_pk_mul_f32 v[36:37], v[4:5], v[36:37]
	s_waitcnt lgkmcnt(6)
	v_pk_mul_f32 v[42:43], v[10:11], v[42:43]
	v_pk_mul_f32 v[40:41], v[8:9], v[40:41]
	s_waitcnt lgkmcnt(5)
	v_pk_mul_f32 v[46:47], v[14:15], v[46:47]
	v_pk_mul_f32 v[44:45], v[12:13], v[44:45]
	v_pk_mul_f32 v[0:1], v[0:1], v[26:27]
	v_pk_mul_f32 v[2:3], v[2:3], v[28:29]
	v_pk_mul_f32 v[4:5], v[4:5], v[30:31]
	v_pk_mul_f32 v[6:7], v[6:7], v[48:49]
	v_pk_mul_f32 v[8:9], v[8:9], v[24:25]
	v_pk_mul_f32 v[10:11], v[10:11], v[84:85]
	v_pk_mul_f32 v[12:13], v[12:13], v[86:87]
	v_pk_mul_f32 v[14:15], v[14:15], v[96:97]
	s_waitcnt lgkmcnt(3)
	v_mfma_f32_32x32x16_bf16 v[32:47], v[16:19], v[20:23], v[32:47]
	ds_read_b128 v[84:87], v115 offset:16928
	s_movk_i32 s4, 0x50
	s_waitcnt lgkmcnt(1)
	v_mfma_f32_32x32x16_bf16 v[0:15], v[16:19], v[118:121], v[0:15]
	v_mfma_f32_32x32x16_bf16 v[32:47], v[106:109], v[110:113], v[32:47]
	s_waitcnt lgkmcnt(0)
	v_mfma_f32_32x32x16_bf16 v[0:15], v[106:109], v[84:87], v[0:15]
	ds_read_b128 v[16:19], v95 offset:19584
	ds_read_b128 v[24:27], v95 offset:19616
	ds_read_b128 v[28:31], v95 offset:19648
	ds_read_b128 v[106:109], v95 offset:19680
	ds_read_b128 v[122:125], v115 offset:11776
	s_waitcnt lgkmcnt(4)
	v_pk_mul_f32 v[50:51], v[18:19], v[50:51]
	v_pk_mul_f32 v[48:49], v[16:17], v[54:55]
	s_waitcnt lgkmcnt(3)
	v_pk_mul_f32 v[54:55], v[26:27], v[82:83]
	v_pk_mul_f32 v[52:53], v[24:25], v[52:53]
	s_waitcnt lgkmcnt(2)
	v_pk_mul_f32 v[58:59], v[30:31], v[58:59]
	v_pk_mul_f32 v[56:57], v[28:29], v[56:57]
	s_waitcnt lgkmcnt(1)
	v_pk_mul_f32 v[62:63], v[108:109], v[62:63]
	v_pk_mul_f32 v[60:61], v[106:107], v[60:61]
	ds_read_b128 v[126:129], v115 offset:11808
	v_pk_mul_f32 v[16:17], v[16:17], v[66:67]
	s_waitcnt lgkmcnt(1)
	v_mfma_f32_32x32x16_bf16 v[48:63], v[122:125], v[20:23], v[48:63]
	v_mul_f32_e64 v18, v18, v68
	v_mul_f32_e64 v19, v19, v69
	v_mul_f32_e64 v20, v24, v70
	v_mul_f32_e64 v21, v25, v71
	v_mul_f32_e64 v22, v26, v72
	v_mul_f32_e64 v23, v27, v73
	v_pk_mul_f32 v[24:25], v[28:29], v[74:75]
	v_pk_mul_f32 v[26:27], v[30:31], v[76:77]
	v_pk_mul_f32 v[28:29], v[106:107], v[78:79]
	v_pk_mul_f32 v[30:31], v[108:109], v[80:81]
	s_waitcnt lgkmcnt(0)
	s_waitcnt lgkmcnt(0)
	v_mfma_f32_32x32x16_bf16 v[48:63], v[126:129], v[110:113], v[48:63]
	v_mfma_f32_32x32x16_bf16 v[16:31], v[122:125], v[118:121], v[16:31]
	v_mfma_f32_32x32x16_bf16 v[16:31], v[126:129], v[84:87], v[16:31]
	v_mad_i64_i32 v[64:65], s[2:3], v88, s1, v[64:65]
	v_lshl_add_u64 v[64:65], v[64:65], 0, v[90:91]
	v_lshl_add_u64 v[64:65], v[64:65], 0, v[102:103]
	s_mov_b64 s[48:49], 0x1000
	s_movk_i32 s5, 0x1000
	v_lshl_add_u64 v[72:73], v[64:65], 0, s[48:49]
	v_add_co_u32_e32 v64, vcc, s5, v64
	global_load_dwordx2 v[74:75], v[104:105], off offset:1536
	s_nop 0
	v_addc_co_u32_e32 v65, vcc, 0, v65, vcc
	global_load_dwordx2 v[76:77], v[64:65], off
	v_readlane_b32 s0, v255, 18
	v_readlane_b32 s1, v255, 19
	s_add_u32 s2, s40, s0
	v_mov_b32_e32 v66, v114
	s_addc_u32 s3, s41, s1
	s_nop 0
	v_permlane32_swap_b32_e32 v114, v66
	v_lshl_add_u64 v[64:65], v[100:101], 2, s[2:3]
	s_mov_b64 s[2:3], 0x4800
	v_add_f32_e32 v66, v114, v66
	v_lshl_add_u64 v[70:71], v[64:65], 0, s[2:3]
	v_add_co_u32_e32 v64, vcc, s7, v64
	v_fmamk_f32 v66, v66, 0x3c800000, v237
	s_nop 0
	v_addc_co_u32_e32 v65, vcc, 0, v65, vcc
	v_rsq_f32_e32 v68, v66
	global_load_dwordx4 v[64:67], v[64:65], off offset:2048
	s_movk_i32 s6, 0x1200
	s_waitcnt vmcnt(2)
	v_lshlrev_b32_e32 v82, 16, v74
	v_and_b32_e32 v83, 0xffff0000, v74
	v_lshlrev_b32_e32 v74, 16, v75
	s_waitcnt vmcnt(1)
	v_lshlrev_b32_e32 v78, 16, v76
	v_mul_f32_e32 v69, 0xbfb8aa3b, v78
	v_exp_f32_e32 v69, v69
	v_and_b32_e32 v79, 0xffff0000, v76
	v_lshlrev_b32_e32 v76, 16, v77
	v_and_b32_e32 v77, 0xffff0000, v77
	v_add_f32_e32 v69, 1.0, v69
	v_rcp_f32_e32 v80, v69
	v_mul_f32_e32 v69, 0xbfb8aa3b, v79
	v_exp_f32_e32 v69, v69
	v_and_b32_e32 v75, 0xffff0000, v75
	v_add_f32_e32 v69, 1.0, v69
	v_rcp_f32_e32 v81, v69
	v_pk_mul_f32 v[82:83], v[68:69], v[82:83] op_sel_hi:[0,1]
	v_pk_mul_f32 v[74:75], v[68:69], v[74:75] op_sel_hi:[0,1]
	s_waitcnt vmcnt(0)
	v_pk_mul_f32 v[64:65], v[64:65], v[82:83]
	v_pk_mul_f32 v[78:79], v[80:81], v[78:79]
	v_pk_mul_f32 v[66:67], v[66:67], v[74:75]
	v_pk_mul_f32 v[64:65], v[64:65], v[78:79]
	s_nop 0
	v_cvt_pk_bf16_f32 v64, v64, v65
	v_mul_f32_e32 v65, 0xbfb8aa3b, v76
	v_exp_f32_e32 v65, v65
	s_nop 0
	v_add_f32_e32 v65, 1.0, v65
	v_rcp_f32_e32 v78, v65
	v_mul_f32_e32 v65, 0xbfb8aa3b, v77
	v_exp_f32_e32 v65, v65
	s_nop 0
	v_add_f32_e32 v65, 1.0, v65
	v_rcp_f32_e32 v79, v65
	s_nop 0
	v_pk_mul_f32 v[74:75], v[78:79], v[76:77]
	s_nop 0
	v_pk_mul_f32 v[66:67], v[66:67], v[74:75]
	s_nop 0
	v_cvt_pk_bf16_f32 v65, v66, v67
	global_store_dwordx2 v[104:105], v[64:65], off offset:1536
	global_load_dwordx4 v[64:67], v[70:71], off offset:32
	s_nop 0
	global_load_dwordx2 v[74:75], v[72:73], off offset:16
	global_load_dwordx2 v[76:77], v[98:99], off offset:16
	s_waitcnt vmcnt(1)
	v_lshlrev_b32_e32 v78, 16, v74
	v_mul_f32_e32 v69, 0xbfb8aa3b, v78
	v_exp_f32_e32 v69, v69
	v_and_b32_e32 v79, 0xffff0000, v74
	s_waitcnt vmcnt(0)
	v_lshlrev_b32_e32 v82, 16, v76
	v_and_b32_e32 v83, 0xffff0000, v76
	v_add_f32_e32 v69, 1.0, v69
	v_rcp_f32_e32 v80, v69
	v_mul_f32_e32 v69, 0xbfb8aa3b, v79
	v_exp_f32_e32 v69, v69
	v_lshlrev_b32_e32 v74, 16, v75
	v_and_b32_e32 v75, 0xffff0000, v75
	v_lshlrev_b32_e32 v76, 16, v77
	v_add_f32_e32 v69, 1.0, v69
	v_rcp_f32_e32 v81, v69
	v_pk_mul_f32 v[82:83], v[68:69], v[82:83] op_sel_hi:[0,1]
	v_pk_mul_f32 v[64:65], v[64:65], v[82:83]
	v_and_b32_e32 v77, 0xffff0000, v77
	v_pk_mul_f32 v[78:79], v[80:81], v[78:79]
	v_pk_mul_f32 v[76:77], v[68:69], v[76:77] op_sel_hi:[0,1]
	v_pk_mul_f32 v[64:65], v[64:65], v[78:79]
	v_pk_mul_f32 v[66:67], v[66:67], v[76:77]
	v_cvt_pk_bf16_f32 v64, v64, v65
	v_mul_f32_e32 v65, 0xbfb8aa3b, v74
	v_exp_f32_e32 v65, v65
	s_nop 0
	v_add_f32_e32 v65, 1.0, v65
	v_rcp_f32_e32 v78, v65
	v_mul_f32_e32 v65, 0xbfb8aa3b, v75
	v_exp_f32_e32 v65, v65
	s_nop 0
	v_add_f32_e32 v65, 1.0, v65
	v_rcp_f32_e32 v79, v65
	s_nop 0
	v_pk_mul_f32 v[74:75], v[78:79], v[74:75]
	s_nop 0
	v_pk_mul_f32 v[66:67], v[66:67], v[74:75]
	s_nop 0
	v_cvt_pk_bf16_f32 v65, v66, v67
	global_store_dwordx2 v[98:99], v[64:65], off offset:16
	global_load_dwordx4 v[64:67], v[70:71], off offset:64
	s_nop 0
	global_load_dwordx2 v[74:75], v[72:73], off offset:32
	global_load_dwordx2 v[76:77], v[98:99], off offset:32
	s_waitcnt vmcnt(1)
	v_lshlrev_b32_e32 v78, 16, v74
	v_mul_f32_e32 v69, 0xbfb8aa3b, v78
	v_exp_f32_e32 v69, v69
	v_and_b32_e32 v79, 0xffff0000, v74
	s_waitcnt vmcnt(0)
	v_lshlrev_b32_e32 v82, 16, v76
	v_and_b32_e32 v83, 0xffff0000, v76
	v_add_f32_e32 v69, 1.0, v69
	v_rcp_f32_e32 v80, v69
	v_mul_f32_e32 v69, 0xbfb8aa3b, v79
	v_exp_f32_e32 v69, v69
	v_lshlrev_b32_e32 v74, 16, v75
	v_and_b32_e32 v75, 0xffff0000, v75
	v_lshlrev_b32_e32 v76, 16, v77
	v_add_f32_e32 v69, 1.0, v69
	v_rcp_f32_e32 v81, v69
	v_pk_mul_f32 v[82:83], v[68:69], v[82:83] op_sel_hi:[0,1]
	v_pk_mul_f32 v[64:65], v[64:65], v[82:83]
	v_and_b32_e32 v77, 0xffff0000, v77
	v_pk_mul_f32 v[78:79], v[80:81], v[78:79]
	v_pk_mul_f32 v[76:77], v[68:69], v[76:77] op_sel_hi:[0,1]
	v_pk_mul_f32 v[64:65], v[64:65], v[78:79]
	v_pk_mul_f32 v[66:67], v[66:67], v[76:77]
	v_cvt_pk_bf16_f32 v64, v64, v65
	v_mul_f32_e32 v65, 0xbfb8aa3b, v74
	v_exp_f32_e32 v65, v65
	s_nop 0
	v_add_f32_e32 v65, 1.0, v65
	v_rcp_f32_e32 v78, v65
	v_mul_f32_e32 v65, 0xbfb8aa3b, v75
	v_exp_f32_e32 v65, v65
	s_nop 0
	v_add_f32_e32 v65, 1.0, v65
	v_rcp_f32_e32 v79, v65
	s_nop 0
	v_pk_mul_f32 v[74:75], v[78:79], v[74:75]
	s_nop 0
	v_pk_mul_f32 v[66:67], v[66:67], v[74:75]
	s_nop 0
	v_cvt_pk_bf16_f32 v65, v66, v67
	global_store_dwordx2 v[98:99], v[64:65], off offset:32
	global_load_dwordx4 v[64:67], v[70:71], off offset:96
	s_nop 0
	global_load_dwordx2 v[74:75], v[72:73], off offset:48
	global_load_dwordx2 v[76:77], v[98:99], off offset:48
	s_waitcnt vmcnt(1)
	v_lshlrev_b32_e32 v78, 16, v74
	v_mul_f32_e32 v69, 0xbfb8aa3b, v78
	v_exp_f32_e32 v69, v69
	v_and_b32_e32 v79, 0xffff0000, v74
	s_waitcnt vmcnt(0)
	v_lshlrev_b32_e32 v82, 16, v76
	v_and_b32_e32 v83, 0xffff0000, v76
	v_add_f32_e32 v69, 1.0, v69
	v_rcp_f32_e32 v80, v69
	v_mul_f32_e32 v69, 0xbfb8aa3b, v79
	v_exp_f32_e32 v69, v69
	v_lshlrev_b32_e32 v74, 16, v75
	v_and_b32_e32 v75, 0xffff0000, v75
	v_lshlrev_b32_e32 v76, 16, v77
	v_add_f32_e32 v69, 1.0, v69
	v_rcp_f32_e32 v81, v69
	v_pk_mul_f32 v[82:83], v[68:69], v[82:83] op_sel_hi:[0,1]
	v_pk_mul_f32 v[64:65], v[64:65], v[82:83]
	v_and_b32_e32 v77, 0xffff0000, v77
	v_pk_mul_f32 v[78:79], v[80:81], v[78:79]
	v_pk_mul_f32 v[76:77], v[68:69], v[76:77] op_sel_hi:[0,1]
	v_pk_mul_f32 v[64:65], v[64:65], v[78:79]
	v_pk_mul_f32 v[66:67], v[66:67], v[76:77]
	v_cvt_pk_bf16_f32 v64, v64, v65
	v_mul_f32_e32 v65, 0xbfb8aa3b, v74
	v_exp_f32_e32 v65, v65
	s_nop 0
	v_add_f32_e32 v65, 1.0, v65
	v_rcp_f32_e32 v78, v65
	v_mul_f32_e32 v65, 0xbfb8aa3b, v75
	v_exp_f32_e32 v65, v65
	s_nop 0
	v_add_f32_e32 v65, 1.0, v65
	v_rcp_f32_e32 v79, v65
	s_nop 0
	v_pk_mul_f32 v[74:75], v[78:79], v[74:75]
	s_nop 0
	v_pk_mul_f32 v[66:67], v[66:67], v[74:75]
	s_nop 0
	v_cvt_pk_bf16_f32 v65, v66, v67
	global_store_dwordx2 v[98:99], v[64:65], off offset:48
	global_load_dwordx2 v[74:75], v[98:99], off offset:64
	global_load_dwordx2 v[76:77], v[72:73], off offset:64
	global_load_dwordx4 v[64:67], v[70:71], off offset:128
	s_waitcnt vmcnt(2)
	v_lshlrev_b32_e32 v82, 16, v74
	s_waitcnt vmcnt(1)
	v_lshlrev_b32_e32 v78, 16, v76
	v_mul_f32_e32 v69, 0xbfb8aa3b, v78
	v_exp_f32_e32 v69, v69
	v_and_b32_e32 v79, 0xffff0000, v76
	v_and_b32_e32 v83, 0xffff0000, v74
	v_lshlrev_b32_e32 v76, 16, v77
	v_add_f32_e32 v69, 1.0, v69
	v_rcp_f32_e32 v80, v69
	v_mul_f32_e32 v69, 0xbfb8aa3b, v79
	v_exp_f32_e32 v69, v69
	v_and_b32_e32 v77, 0xffff0000, v77
	v_lshlrev_b32_e32 v74, 16, v75
	v_and_b32_e32 v75, 0xffff0000, v75
	v_add_f32_e32 v69, 1.0, v69
	v_rcp_f32_e32 v81, v69
	v_pk_mul_f32 v[82:83], v[68:69], v[82:83] op_sel_hi:[0,1]
	s_waitcnt vmcnt(0)
	v_pk_mul_f32 v[64:65], v[64:65], v[82:83]
	v_pk_mul_f32 v[74:75], v[68:69], v[74:75] op_sel_hi:[0,1]
	v_pk_mul_f32 v[78:79], v[80:81], v[78:79]
	v_pk_mul_f32 v[66:67], v[66:67], v[74:75]
	v_pk_mul_f32 v[64:65], v[64:65], v[78:79]
	s_nop 0
	v_cvt_pk_bf16_f32 v64, v64, v65
	v_mul_f32_e32 v65, 0xbfb8aa3b, v76
	v_exp_f32_e32 v65, v65
	s_nop 0
	v_add_f32_e32 v65, 1.0, v65
	v_rcp_f32_e32 v78, v65
	v_mul_f32_e32 v65, 0xbfb8aa3b, v77
	v_exp_f32_e32 v65, v65
	s_nop 0
	v_add_f32_e32 v65, 1.0, v65
	v_rcp_f32_e32 v79, v65
	s_nop 0
	v_pk_mul_f32 v[74:75], v[78:79], v[76:77]
	s_nop 0
	v_pk_mul_f32 v[66:67], v[66:67], v[74:75]
	s_nop 0
	v_cvt_pk_bf16_f32 v65, v66, v67
	global_store_dwordx2 v[98:99], v[64:65], off offset:64
	global_load_dwordx2 v[74:75], v[98:99], off offset:80
	global_load_dwordx2 v[76:77], v[72:73], off offset:80
	s_nop 0
	global_load_dwordx4 v[64:67], v[70:71], off offset:160
	s_waitcnt vmcnt(2)
	v_lshlrev_b32_e32 v82, 16, v74
	s_waitcnt vmcnt(1)
	v_lshlrev_b32_e32 v78, 16, v76
	v_mul_f32_e32 v69, 0xbfb8aa3b, v78
	v_exp_f32_e32 v69, v69
	v_and_b32_e32 v79, 0xffff0000, v76
	v_and_b32_e32 v83, 0xffff0000, v74
	v_lshlrev_b32_e32 v76, 16, v77
	v_add_f32_e32 v69, 1.0, v69
	v_rcp_f32_e32 v80, v69
	v_mul_f32_e32 v69, 0xbfb8aa3b, v79
	v_exp_f32_e32 v69, v69
	v_and_b32_e32 v77, 0xffff0000, v77
	v_lshlrev_b32_e32 v74, 16, v75
	v_and_b32_e32 v75, 0xffff0000, v75
	v_add_f32_e32 v69, 1.0, v69
	v_rcp_f32_e32 v81, v69
	v_pk_mul_f32 v[82:83], v[68:69], v[82:83] op_sel_hi:[0,1]
	s_waitcnt vmcnt(0)
	v_pk_mul_f32 v[64:65], v[64:65], v[82:83]
	v_pk_mul_f32 v[74:75], v[68:69], v[74:75] op_sel_hi:[0,1]
	v_pk_mul_f32 v[78:79], v[80:81], v[78:79]
	v_pk_mul_f32 v[66:67], v[66:67], v[74:75]
	v_pk_mul_f32 v[64:65], v[64:65], v[78:79]
	s_nop 0
	v_cvt_pk_bf16_f32 v64, v64, v65
	v_mul_f32_e32 v65, 0xbfb8aa3b, v76
	v_exp_f32_e32 v65, v65
	s_nop 0
	v_add_f32_e32 v65, 1.0, v65
	v_rcp_f32_e32 v78, v65
	v_mul_f32_e32 v65, 0xbfb8aa3b, v77
	v_exp_f32_e32 v65, v65
	s_nop 0
	v_add_f32_e32 v65, 1.0, v65
	v_rcp_f32_e32 v79, v65
	s_nop 0
	v_pk_mul_f32 v[74:75], v[78:79], v[76:77]
	s_nop 0
	v_pk_mul_f32 v[66:67], v[66:67], v[74:75]
	s_nop 0
	v_cvt_pk_bf16_f32 v65, v66, v67
	global_store_dwordx2 v[98:99], v[64:65], off offset:80
	global_load_dwordx2 v[74:75], v[98:99], off offset:96
	global_load_dwordx2 v[76:77], v[72:73], off offset:96
	s_nop 0
	global_load_dwordx4 v[64:67], v[70:71], off offset:192
	s_waitcnt vmcnt(2)
	v_lshlrev_b32_e32 v82, 16, v74
	s_waitcnt vmcnt(1)
	v_lshlrev_b32_e32 v78, 16, v76
	v_mul_f32_e32 v69, 0xbfb8aa3b, v78
	v_exp_f32_e32 v69, v69
	v_and_b32_e32 v79, 0xffff0000, v76
	v_and_b32_e32 v83, 0xffff0000, v74
	v_lshlrev_b32_e32 v76, 16, v77
	v_add_f32_e32 v69, 1.0, v69
	v_rcp_f32_e32 v80, v69
	v_mul_f32_e32 v69, 0xbfb8aa3b, v79
	v_exp_f32_e32 v69, v69
	v_and_b32_e32 v77, 0xffff0000, v77
	v_lshlrev_b32_e32 v74, 16, v75
	v_and_b32_e32 v75, 0xffff0000, v75
	v_add_f32_e32 v69, 1.0, v69
	v_rcp_f32_e32 v81, v69
	v_pk_mul_f32 v[82:83], v[68:69], v[82:83] op_sel_hi:[0,1]
	s_waitcnt vmcnt(0)
	v_pk_mul_f32 v[64:65], v[64:65], v[82:83]
	v_pk_mul_f32 v[74:75], v[68:69], v[74:75] op_sel_hi:[0,1]
	v_pk_mul_f32 v[78:79], v[80:81], v[78:79]
	v_pk_mul_f32 v[66:67], v[66:67], v[74:75]
	v_pk_mul_f32 v[64:65], v[64:65], v[78:79]
	s_nop 0
	v_cvt_pk_bf16_f32 v64, v64, v65
	v_mul_f32_e32 v65, 0xbfb8aa3b, v76
	v_exp_f32_e32 v65, v65
	s_nop 0
	v_add_f32_e32 v65, 1.0, v65
	v_rcp_f32_e32 v78, v65
	v_mul_f32_e32 v65, 0xbfb8aa3b, v77
	v_exp_f32_e32 v65, v65
	s_nop 0
	v_add_f32_e32 v65, 1.0, v65
	v_rcp_f32_e32 v79, v65
	s_nop 0
	v_pk_mul_f32 v[74:75], v[78:79], v[76:77]
	s_nop 0
	v_pk_mul_f32 v[66:67], v[66:67], v[74:75]
	s_nop 0
	v_cvt_pk_bf16_f32 v65, v66, v67
	global_store_dwordx2 v[98:99], v[64:65], off offset:96
	global_load_dwordx2 v[64:65], v[98:99], off offset:112
	s_nop 0
	global_load_dwordx2 v[66:67], v[72:73], off offset:112
	s_nop 0
	global_load_dwordx4 v[70:73], v[70:71], off offset:224
	s_waitcnt vmcnt(2)
	v_lshlrev_b32_e32 v78, 16, v64
	s_waitcnt vmcnt(1)
	v_lshlrev_b32_e32 v74, 16, v66
	v_mul_f32_e32 v69, 0xbfb8aa3b, v74
	v_exp_f32_e32 v69, v69
	v_and_b32_e32 v75, 0xffff0000, v66
	v_lshlrev_b32_e32 v66, 16, v67
	v_and_b32_e32 v79, 0xffff0000, v64
	v_add_f32_e32 v69, 1.0, v69
	v_rcp_f32_e32 v76, v69
	v_mul_f32_e32 v69, 0xbfb8aa3b, v75
	v_exp_f32_e32 v69, v69
	v_and_b32_e32 v67, 0xffff0000, v67
	v_add_f32_e32 v69, 1.0, v69
	v_rcp_f32_e32 v77, v69
	v_pk_mul_f32 v[78:79], v[68:69], v[78:79] op_sel_hi:[0,1]
	v_mul_f32_e32 v69, 0xbfb8aa3b, v66
	v_exp_f32_e32 v69, v69
	s_waitcnt vmcnt(0)
	v_pk_mul_f32 v[70:71], v[70:71], v[78:79]
	v_pk_mul_f32 v[74:75], v[76:77], v[74:75]
	v_add_f32_e32 v69, 1.0, v69
	v_pk_mul_f32 v[70:71], v[70:71], v[74:75]
	v_lshlrev_b32_e32 v74, 16, v65
	v_cvt_pk_bf16_f32 v64, v70, v71
	v_rcp_f32_e32 v70, v69
	v_mul_f32_e32 v69, 0xbfb8aa3b, v67
	v_exp_f32_e32 v69, v69
	v_and_b32_e32 v75, 0xffff0000, v65
	v_add_f32_e32 v69, 1.0, v69
	v_rcp_f32_e32 v71, v69
	v_pk_mul_f32 v[68:69], v[68:69], v[74:75] op_sel_hi:[0,1]
	v_pk_mul_f32 v[68:69], v[72:73], v[68:69]
	v_pk_mul_f32 v[66:67], v[70:71], v[66:67]
	s_nop 0
	v_pk_mul_f32 v[66:67], v[68:69], v[66:67]
	s_nop 0
	v_cvt_pk_bf16_f32 v65, v66, v67
	global_store_dwordx2 v[98:99], v[64:65], off offset:112
	s_add_u32 s2, s12, 0xb200000
	v_and_b32_e32 v114, 31, v94
	v_ashrrev_i32_e32 v115, 5, v94
	s_addc_u32 s3, s13, 0
	v_mov_b64_e32 v[96:97], s[2:3]
	v_mad_i64_i32 v[64:65], s[2:3], v93, s6, v[96:97]
	v_ashrrev_i32_e32 v95, 31, v94
	v_lshl_add_u64 v[64:65], v[64:65], 0, v[90:91]
	v_lshl_add_u64 v[64:65], v[94:95], 1, v[64:65]
	v_add_co_u32_e32 v76, vcc, s37, v64
	s_movk_i32 s2, 0x5000
	s_nop 0
	v_addc_co_u32_e32 v77, vcc, 0, v65, vcc
	global_load_ushort v95, v[76:77], off offset:3072
	global_load_ushort v107, v[76:77], off offset:1536
	v_add_co_u32_e32 v66, vcc, s20, v64
	v_lshl_add_u32 v88, v94, 1, v92
	s_nop 0
	v_addc_co_u32_e32 v67, vcc, 0, v65, vcc
	v_add_co_u32_e32 v68, vcc, s2, v64
	s_movk_i32 s2, 0x7000
	s_nop 0
	v_addc_co_u32_e32 v69, vcc, 0, v65, vcc
	v_add_co_u32_e32 v70, vcc, s2, v64
	s_mov_b32 s2, 0x10000
	s_nop 0
	v_addc_co_u32_e32 v71, vcc, 0, v65, vcc
	v_add_co_u32_e32 v80, vcc, s28, v64
	s_waitcnt vmcnt(0)
	v_lshlrev_b32_e32 v107, 16, v107
	v_addc_co_u32_e32 v81, vcc, 0, v65, vcc
	v_add_co_u32_e32 v82, vcc, s29, v64
	v_readlane_b32 s28, v255, 28
	s_nop 0
	v_addc_co_u32_e32 v83, vcc, 0, v65, vcc
	v_add_co_u32_e32 v84, vcc, s18, v64
	v_readlane_b32 s29, v255, 29
	s_nop 0
	v_addc_co_u32_e32 v85, vcc, 0, v65, vcc
	v_add_co_u32_e32 v86, vcc, s2, v64
	s_mov_b32 s2, 0x14000
	s_nop 0
	v_addc_co_u32_e32 v87, vcc, 0, v65, vcc
	v_add_co_u32_e32 v72, vcc, s51, v64
	s_nop 1
	v_addc_co_u32_e32 v73, vcc, 0, v65, vcc
	v_add_co_u32_e32 v74, vcc, s2, v64
	s_mov_b32 s2, 0x1a000
	s_nop 0
	v_addc_co_u32_e32 v75, vcc, 0, v65, vcc
	v_add_co_u32_e32 v78, vcc, s30, v64
	s_nop 1
	v_addc_co_u32_e32 v79, vcc, 0, v65, vcc
	v_add_co_u32_e32 v98, vcc, s31, v64
	s_mov_b64 s[30:31], 0x4800
	s_nop 0
	v_addc_co_u32_e32 v99, vcc, 0, v65, vcc
	v_add_co_u32_e32 v100, vcc, s34, v64
	s_nop 1
	v_addc_co_u32_e32 v101, vcc, 0, v65, vcc
	v_add_co_u32_e32 v102, vcc, s35, v64
	s_mov_b64 s[34:35], 0x1200
	s_nop 0
	v_addc_co_u32_e32 v103, vcc, 0, v65, vcc
	v_add_co_u32_e32 v104, vcc, s19, v64
	v_readlane_b32 s18, v255, 26
	s_nop 0
	v_addc_co_u32_e32 v105, vcc, 0, v65, vcc
	v_add_co_u32_e32 v118, vcc, s36, v64
	v_readlane_b32 s36, v255, 30
	s_nop 0
	v_addc_co_u32_e32 v119, vcc, 0, v65, vcc
	v_add_co_u32_e32 v108, vcc, s21, v64
	v_readlane_b32 s19, v255, 27
	s_nop 0
	v_addc_co_u32_e32 v109, vcc, 0, v65, vcc
	global_load_ushort v111, v[108:109], off offset:512
	global_load_ushort v106, v[108:109], off offset:1024
	global_load_ushort v113, v[108:109], off offset:2048
	s_nop 0
	global_load_ushort v108, v[76:77], off offset:2048
	global_load_ushort v110, v[118:119], off offset:1536
	global_load_ushort v120, v[118:119], off offset:2560
	global_load_ushort v121, v[102:103], off offset:3584
	global_load_ushort v122, v[104:105], off offset:512
	global_load_ushort v152, v[118:119], off offset:1024
	global_load_ushort v153, v[104:105], off offset:1536
	global_load_ushort v154, v[104:105], off
	global_load_ushort v158, v[102:103], off offset:3072
	global_load_ushort v160, v[102:103], off
	global_load_ushort v165, v[100:101], off offset:3584
	v_lshlrev_b32_e32 v76, 16, v95
	v_max_f32_e32 v76, v76, v76
	v_med3_f32 v76, v76, s9, v244
	v_mul_f32_e32 v76, 0xbfb8aa3b, v76
	v_exp_f32_e32 v95, v76
	v_add_co_u32_e32 v76, vcc, s42, v64
	global_load_ushort v123, v[78:79], off offset:512
	global_load_ushort v124, v[98:99], off offset:1536
	global_load_ushort v126, v[100:101], off offset:2560
	global_load_ushort v166, v[100:101], off offset:2048
	global_load_ushort v168, v[98:99], off offset:2560
	global_load_ushort v171, v[98:99], off offset:1024
	global_load_ushort v167, v[78:79], off offset:1536
	global_load_ushort v163, v[78:79], off
	v_add_f32_e32 v109, 1.0, v95
	v_addc_co_u32_e32 v77, vcc, 0, v65, vcc
	v_rcp_f32_e32 v109, v109
	v_add_co_u32_e32 v134, vcc, s17, v64
	v_readlane_b32 s37, v255, 31
	s_nop 0
	v_addc_co_u32_e32 v135, vcc, 0, v65, vcc
	v_add_co_u32_e32 v132, vcc, s16, v64
	v_fma_f32 v112, v117, v109, v116
	s_nop 0
	v_addc_co_u32_e32 v133, vcc, 0, v65, vcc
	v_max_f32_e32 v150, 0xda24260, v112
	v_add_co_u32_e32 v118, vcc, s2, v64
	v_mul_f32_e32 v95, v95, v109
	v_rcp_f32_e32 v109, v150
	v_addc_co_u32_e32 v119, vcc, 0, v65, vcc
	s_mov_b32 s2, 0x18000
	v_add_co_u32_e32 v136, vcc, s2, v64
	s_mov_b32 s2, 0x16000
	s_nop 0
	v_addc_co_u32_e32 v137, vcc, 0, v65, vcc
	v_mul_f32_e32 v95, v117, v95
	v_mul_f32_e32 v107, v150, v107
	v_add_co_u32_e32 v78, vcc, s2, v64
	v_bfe_u32 v112, v107, 16, 1
	v_mul_f32_e32 v95, v95, v109
	v_addc_co_u32_e32 v79, vcc, 0, v65, vcc
	v_add3_u32 v151, v107, v112, s10
	v_bfe_u32 v107, v95, 16, 1
	v_add_co_u32_e32 v138, vcc, s43, v64
	v_add3_u32 v112, v95, v107, s10
	s_nop 0
	v_addc_co_u32_e32 v139, vcc, 0, v65, vcc
	global_load_ushort v125, v[84:85], off offset:512
	global_load_ushort v127, v[86:87], off offset:1536
	global_load_ushort v128, v[72:73], off offset:2560
	global_load_ushort v129, v[74:75], off offset:3584
	global_load_ushort v157, v[74:75], off offset:3072
	global_load_ushort v155, v[74:75], off
	global_load_ushort v109, v[72:73], off offset:3584
	global_load_ushort v107, v[72:73], off offset:2048
	global_load_ushort v172, v[76:77], off offset:1024
	global_load_ushort v173, v[134:135], off offset:3584
	global_load_ushort v174, v[132:133], off offset:2560
	global_load_ushort v175, v[118:119], off offset:1536
	global_load_ushort v131, v[118:119], off offset:2048
	s_nop 0
	global_load_ushort v132, v[132:133], off offset:3072
	s_nop 0
	global_load_ushort v176, v[134:135], off offset:512
	global_load_ushort v133, v[76:77], off
	global_load_ushort v177, v[118:119], off offset:3072
	global_load_ushort v170, v[136:137], off offset:2048
	global_load_ushort v169, v[136:137], off offset:512
	global_load_ushort v164, v[78:79], off offset:1024
	global_load_ushort v162, v[138:139], off offset:3584
	global_load_ushort v159, v[138:139], off offset:512
	global_load_ushort v135, v[78:79], off
	s_nop 0
	global_load_ushort v137, v[136:137], off offset:1024
	v_add_co_u32_e32 v144, vcc, s44, v64
	global_load_ushort v130, v[64:65], off offset:2560
	global_load_ushort v134, v[66:67], off offset:3584
	global_load_ushort v136, v[68:69], off offset:512
	global_load_ushort v138, v[70:71], off offset:1536
	global_load_ushort v139, v[80:81], off offset:2560
	global_load_ushort v141, v[82:83], off offset:3584
	global_load_ushort v142, v[84:85], off offset:-4096
	global_load_ushort v140, v[68:69], off offset:-4096
	v_addc_co_u32_e32 v145, vcc, 0, v65, vcc
	v_add_co_u32_e32 v100, vcc, s45, v64
	v_readlane_b32 s42, v255, 32
	s_nop 0
	v_addc_co_u32_e32 v101, vcc, 0, v65, vcc
	v_add_co_u32_e32 v102, vcc, s46, v64
	v_readlane_b32 s43, v255, 33
	s_nop 0
	v_addc_co_u32_e32 v103, vcc, 0, v65, vcc
	v_add_co_u32_e32 v104, vcc, s47, v64
	v_readlane_b32 s46, v255, 38
	s_nop 0
	v_addc_co_u32_e32 v105, vcc, 0, v65, vcc
	v_add_co_u32_e32 v98, vcc, s15, v64
	s_waitcnt vmcnt(53)
	v_lshlrev_b32_e32 v111, 16, v111
	v_addc_co_u32_e32 v99, vcc, 0, v65, vcc
	s_waitcnt vmcnt(51)
	v_lshlrev_b32_e32 v113, 16, v113
	s_waitcnt vmcnt(48)
	v_lshlrev_b32_e32 v72, 16, v120
	v_max_f32_e32 v72, v72, v72
	v_med3_f32 v72, v72, s9, v244
	v_mul_f32_e32 v72, 0xbfb8aa3b, v72
	v_exp_f32_e32 v95, v72
	v_add_co_u32_e32 v74, vcc, s14, v64
	v_max_f32_e32 v113, v113, v113
	v_add_f32_e32 v118, 1.0, v95
	v_rcp_f32_e32 v118, v118
	v_addc_co_u32_e32 v75, vcc, 0, v65, vcc
	v_med3_f32 v113, v113, s9, v244
	v_fma_f32 v119, v117, v118, v116
	v_mul_f32_e32 v119, v150, v119
	v_max_f32_e32 v119, 0xda24260, v119
	v_add_co_u32_e32 v76, vcc, s27, v64
	v_rcp_f32_e32 v120, v119
	v_mul_f32_e32 v113, 0xbfb8aa3b, v113
	v_addc_co_u32_e32 v77, vcc, 0, v65, vcc
	v_exp_f32_e32 v113, v113
	v_add_co_u32_e32 v78, vcc, s7, v64
	v_mul_f32_e32 v95, v95, v118
	s_nop 0
	v_addc_co_u32_e32 v79, vcc, 0, v65, vcc
	v_mul_f32_e32 v95, v117, v95
	v_add_co_u32_e32 v72, vcc, s5, v64
	v_mul_f32_e32 v95, v95, v120
	s_nop 0
	v_addc_co_u32_e32 v73, vcc, 0, v65, vcc
	global_load_ushort v156, v[144:145], off offset:2560
	global_load_ushort v148, v[144:145], off offset:3072
	global_load_ushort v149, v[100:101], off offset:2048
	global_load_ushort v147, v[102:103], off offset:1024
	global_load_ushort v146, v[98:99], off offset:3072
	s_nop 0
	global_load_ushort v144, v[74:75], off offset:2048
	global_load_ushort v145, v[76:77], off offset:1024
	global_load_ushort v143, v[72:73], off offset:3072
	v_bfe_u32 v118, v95, 16, 1
	v_add_f32_e32 v120, 1.0, v113
	v_add3_u32 v95, v95, v118, s10
	s_waitcnt vmcnt(53)
	v_lshlrev_b32_e32 v118, 16, v152
	v_rcp_f32_e32 v120, v120
	v_mul_f32_e32 v118, v119, v118
	v_bfe_u32 v150, v118, 16, 1
	v_add3_u32 v118, v118, v150, s10
	ds_write_b16_d16_hi v88, v118 offset:4320
	v_fma_f32 v118, v117, v120, v116
	v_mul_f32_e32 v118, v119, v118
	v_mul_f32_e32 v113, v113, v120
	s_waitcnt vmcnt(52)
	v_lshlrev_b32_e32 v120, 16, v153
	v_max_f32_e32 v118, 0xda24260, v118
	v_max_f32_e32 v120, v120, v120
	v_rcp_f32_e32 v119, v118
	v_med3_f32 v120, v120, s9, v244
	v_mul_f32_e32 v120, 0xbfb8aa3b, v120
	v_exp_f32_e32 v120, v120
	v_mul_f32_e32 v113, v117, v113
	v_mul_f32_e32 v113, v113, v119
	v_bfe_u32 v119, v113, 16, 1
	ds_write_b16_d16_hi v88, v151 offset:4464
	v_add3_u32 v151, v113, v119, s10
	v_add_f32_e32 v113, 1.0, v120
	v_rcp_f32_e32 v113, v113
	v_mul_f32_e32 v111, v118, v111
	v_bfe_u32 v119, v111, 16, 1
	v_add3_u32 v111, v111, v119, s10
	ds_write_b16_d16_hi v88, v111 offset:4176
	v_fma_f32 v111, v117, v113, v116
	s_waitcnt vmcnt(31)
	v_lshlrev_b32_e32 v119, 16, v172
	v_mul_f32_e32 v111, v118, v111
	v_max_f32_e32 v119, v119, v119
	v_max_f32_e32 v111, 0xda24260, v111
	v_med3_f32 v119, v119, s9, v244
	v_rcp_f32_e32 v118, v111
	v_mul_f32_e32 v119, 0xbfb8aa3b, v119
	v_exp_f32_e32 v119, v119
	v_mul_f32_e32 v113, v120, v113
	v_mul_f32_e32 v113, v117, v113
	v_mul_f32_e32 v113, v113, v118
	v_bfe_u32 v118, v113, 16, 1
	v_add_f32_e32 v120, 1.0, v119
	v_add3_u32 v118, v113, v118, s10
	v_lshlrev_b32_e32 v113, 16, v154
	v_rcp_f32_e32 v120, v120
	v_mul_f32_e32 v113, v111, v113
	v_bfe_u32 v150, v113, 16, 1
	v_add3_u32 v113, v113, v150, s10
	ds_write_b16_d16_hi v88, v113 offset:4032
	v_fma_f32 v113, v117, v120, v116
	v_mul_f32_e32 v111, v111, v113
	v_mul_f32_e32 v119, v119, v120
	s_waitcnt vmcnt(25)
	v_lshlrev_b32_e32 v120, 16, v176
	v_max_f32_e32 v111, 0xda24260, v111
	v_max_f32_e32 v120, v120, v120
	v_rcp_f32_e32 v113, v111
	v_med3_f32 v120, v120, s9, v244
	v_mul_f32_e32 v120, 0xbfb8aa3b, v120
	v_exp_f32_e32 v120, v120
	v_mul_f32_e32 v119, v117, v119
	v_mul_f32_e32 v113, v119, v113
	v_bfe_u32 v119, v113, 16, 1
	v_add3_u32 v152, v113, v119, s10
	v_add_f32_e32 v119, 1.0, v120
	v_lshlrev_b32_e32 v113, 16, v173
	v_rcp_f32_e32 v119, v119
	v_mul_f32_e32 v113, v111, v113
	v_bfe_u32 v150, v113, 16, 1
	v_add3_u32 v113, v113, v150, s10
	ds_write_b16_d16_hi v88, v113 offset:3888
	v_fma_f32 v113, v117, v119, v116
	v_mul_f32_e32 v119, v120, v119
	v_lshlrev_b32_e32 v120, 16, v160
	v_mul_f32_e32 v111, v111, v113
	v_max_f32_e32 v120, v120, v120
	v_max_f32_e32 v111, 0xda24260, v111
	v_med3_f32 v120, v120, s9, v244
	v_rcp_f32_e32 v113, v111
	v_mul_f32_e32 v120, 0xbfb8aa3b, v120
	v_exp_f32_e32 v120, v120
	v_mul_f32_e32 v119, v117, v119
	v_mul_f32_e32 v113, v119, v113
	v_bfe_u32 v119, v113, 16, 1
	v_add_f32_e32 v150, 1.0, v120
	v_add3_u32 v119, v113, v119, s10
	v_lshlrev_b32_e32 v113, 16, v158
	v_rcp_f32_e32 v150, v150
	v_mul_f32_e32 v113, v111, v113
	v_bfe_u32 v153, v113, 16, 1
	v_add3_u32 v113, v113, v153, s10
	ds_write_b16_d16_hi v88, v113 offset:3744
	v_fma_f32 v113, v117, v150, v116
	v_mul_f32_e32 v111, v111, v113
	v_mul_f32_e32 v120, v120, v150
	v_lshlrev_b32_e32 v150, 16, v165
	v_max_f32_e32 v111, 0xda24260, v111
	v_max_f32_e32 v150, v150, v150
	v_rcp_f32_e32 v113, v111
	v_med3_f32 v150, v150, s9, v244
	v_mul_f32_e32 v150, 0xbfb8aa3b, v150
	v_exp_f32_e32 v150, v150
	v_mul_f32_e32 v120, v117, v120
	v_mul_f32_e32 v113, v120, v113
	v_bfe_u32 v120, v113, 16, 1
	v_add3_u32 v153, v113, v120, s10
	v_add_f32_e32 v120, 1.0, v150
	v_lshlrev_b32_e32 v113, 16, v174
	v_rcp_f32_e32 v120, v120
	v_mul_f32_e32 v113, v111, v113
	v_bfe_u32 v154, v113, 16, 1
	v_add3_u32 v113, v113, v154, s10
	ds_write_b16_d16_hi v88, v113 offset:3600
	v_fma_f32 v113, v117, v120, v116
	v_mul_f32_e32 v111, v111, v113
	v_max_f32_e32 v111, 0xda24260, v111
	v_rcp_f32_e32 v113, v111
	v_mul_f32_e32 v120, v150, v120
	v_mul_f32_e32 v120, v117, v120
	v_readlane_b32 s47, v255, 39
	v_mul_f32_e32 v113, v120, v113
	v_bfe_u32 v120, v113, 16, 1
	v_add3_u32 v120, v113, v120, s10
	v_lshlrev_b32_e32 v113, 16, v166
	v_mul_f32_e32 v113, v111, v113
	v_bfe_u32 v150, v113, 16, 1
	v_add3_u32 v113, v113, v150, s10
	ds_write_b16_d16_hi v88, v112 offset:9072
	ds_write_b16_d16_hi v88, v95 offset:8928
	ds_write_b16_d16_hi v88, v151 offset:8784
	ds_write_b16_d16_hi v88, v118 offset:8640
	ds_write_b16_d16_hi v88, v152 offset:8496
	ds_write_b16_d16_hi v88, v119 offset:8352
	ds_write_b16_d16_hi v88, v153 offset:8208
	ds_write_b16_d16_hi v88, v113 offset:3456
	ds_write_b16_d16_hi v88, v120 offset:8064
	s_waitcnt vmcnt(23)
	v_lshlrev_b32_e32 v113, 16, v177
	v_max_f32_e32 v113, v113, v113
	v_med3_f32 v113, v113, s9, v244
	v_mul_f32_e32 v113, 0xbfb8aa3b, v113
	v_exp_f32_e32 v113, v113
	v_lshlrev_b32_e32 v107, 16, v107
	v_add_f32_e32 v150, 1.0, v113
	v_rcp_f32_e32 v150, v150
	s_nop 0
	v_fma_f32 v154, v117, v150, v116
	v_mul_f32_e32 v111, v111, v154
	v_max_f32_e32 v111, 0xda24260, v111
	v_mul_f32_e32 v113, v113, v150
	v_rcp_f32_e32 v150, v111
	v_mul_f32_e32 v113, v117, v113
	v_mul_f32_e32 v113, v113, v150
	v_bfe_u32 v150, v113, 16, 1
	v_add3_u32 v154, v113, v150, s10
	v_lshlrev_b32_e32 v113, 16, v175
	v_mul_f32_e32 v113, v111, v113
	v_bfe_u32 v150, v113, 16, 1
	v_add3_u32 v113, v113, v150, s10
	ds_write_b16_d16_hi v88, v113 offset:3312
	ds_write_b16_d16_hi v88, v154 offset:7920
	v_lshlrev_b32_e32 v113, 16, v168
	v_max_f32_e32 v113, v113, v113
	v_med3_f32 v113, v113, s9, v244
	v_mul_f32_e32 v113, 0xbfb8aa3b, v113
	v_exp_f32_e32 v113, v113
	s_nop 0
	v_add_f32_e32 v150, 1.0, v113
	v_rcp_f32_e32 v150, v150
	s_nop 0
	v_fma_f32 v158, v117, v150, v116
	v_mul_f32_e32 v111, v111, v158
	v_max_f32_e32 v172, 0xda24260, v111
	v_rcp_f32_e32 v111, v172
	v_mul_f32_e32 v113, v113, v150
	v_mul_f32_e32 v113, v117, v113
	v_mul_f32_e32 v111, v113, v111
	v_bfe_u32 v113, v111, 16, 1
	v_add3_u32 v150, v111, v113, s10
	v_lshlrev_b32_e32 v111, 16, v171
	v_mul_f32_e32 v111, v172, v111
	v_bfe_u32 v113, v111, 16, 1
	v_add3_u32 v171, v111, v113, s10
	global_load_ushort v168, v[100:101], off offset:3072
	global_load_ushort v166, v[100:101], off offset:1536
	global_load_ushort v165, v[86:87], off offset:2560
	global_load_ushort v160, v[86:87], off offset:1024
	global_load_ushort v158, v[102:103], off offset:2048
	global_load_ushort v113, v[102:103], off offset:512
	global_load_ushort v111, v[84:85], off offset:1536
	s_nop 0
	global_load_ushort v103, v[84:85], off
	global_load_ushort v102, v[104:105], off offset:1024
	v_add_co_u32_e32 v84, vcc, s50, v64
	s_nop 1
	v_addc_co_u32_e32 v85, vcc, 0, v65, vcc
	global_load_ushort v101, v[84:85], off offset:3584
	global_load_ushort v100, v[84:85], off offset:512
	global_load_ushort v87, v[82:83], off offset:3072
	global_load_ushort v86, v[82:83], off
	s_nop 0
	global_load_ushort v83, v[98:99], off offset:2560
	global_load_ushort v82, v[80:81], off offset:3584
	s_nop 0
	global_load_ushort v81, v[80:81], off offset:2048
	s_waitcnt vmcnt(38)
	v_lshlrev_b32_e32 v80, 16, v170
	v_max_f32_e32 v80, v80, v80
	v_med3_f32 v80, v80, s9, v244
	v_mul_f32_e32 v80, 0xbfb8aa3b, v80
	v_exp_f32_e32 v80, v80
	ds_write_b16_d16_hi v88, v171 offset:3168
	ds_write_b16_d16_hi v88, v150 offset:7776
	v_add_f32_e32 v84, 1.0, v80
	v_rcp_f32_e32 v84, v84
	s_nop 0
	v_fma_f32 v85, v117, v84, v116
	v_mul_f32_e32 v80, v80, v84
	v_mul_f32_e32 v84, v172, v85
	v_max_f32_e32 v84, 0xda24260, v84
	v_rcp_f32_e32 v85, v84
	v_mul_f32_e32 v80, v117, v80
	v_mul_f32_e32 v80, v80, v85
	v_bfe_u32 v85, v80, 16, 1
	v_add3_u32 v85, v80, v85, s10
	s_waitcnt vmcnt(37)
	v_lshlrev_b32_e32 v80, 16, v169
	v_mul_f32_e32 v80, v84, v80
	v_bfe_u32 v98, v80, 16, 1
	v_add3_u32 v80, v80, v98, s10
	ds_write_b16_d16_hi v88, v80 offset:3024
	ds_write_b16_d16_hi v88, v85 offset:7632
	v_lshlrev_b32_e32 v80, 16, v167
	v_max_f32_e32 v80, v80, v80
	v_med3_f32 v80, v80, s9, v244
	v_mul_f32_e32 v80, 0xbfb8aa3b, v80
	v_exp_f32_e32 v80, v80
	s_nop 0
	v_add_f32_e32 v98, 1.0, v80
	v_rcp_f32_e32 v98, v98
	s_nop 0
	v_fma_f32 v99, v117, v98, v116
	v_mul_f32_e32 v84, v84, v99
	v_max_f32_e32 v84, 0xda24260, v84
	v_mul_f32_e32 v80, v80, v98
	v_rcp_f32_e32 v98, v84
	v_mul_f32_e32 v80, v117, v80
	v_mul_f32_e32 v80, v80, v98
	v_bfe_u32 v98, v80, 16, 1
	v_add3_u32 v80, v80, v98, s10
	v_lshlrev_b32_e32 v98, 16, v163
	v_mul_f32_e32 v98, v84, v98
	v_bfe_u32 v99, v98, 16, 1
	v_add3_u32 v98, v98, v99, s10
	ds_write_b16_d16_hi v88, v98 offset:2880
	ds_write_b16_d16_hi v88, v80 offset:7488
	s_waitcnt vmcnt(36)
	v_lshlrev_b32_e32 v98, 16, v164
	v_max_f32_e32 v98, v98, v98
	v_med3_f32 v98, v98, s9, v244
	v_mul_f32_e32 v98, 0xbfb8aa3b, v98
	v_exp_f32_e32 v98, v98
	s_nop 0
	v_add_f32_e32 v99, 1.0, v98
	v_rcp_f32_e32 v99, v99
	s_nop 0
	v_fma_f32 v104, v117, v99, v116
	v_mul_f32_e32 v84, v84, v104
	v_max_f32_e32 v84, 0xda24260, v84
	v_mul_f32_e32 v98, v98, v99
	v_rcp_f32_e32 v99, v84
	v_mul_f32_e32 v98, v117, v98
	v_mul_f32_e32 v98, v98, v99
	v_bfe_u32 v99, v98, 16, 1
	v_add3_u32 v99, v98, v99, s10
	s_waitcnt vmcnt(35)
	v_lshlrev_b32_e32 v98, 16, v162
	v_mul_f32_e32 v98, v84, v98
	v_bfe_u32 v104, v98, 16, 1
	v_add3_u32 v98, v98, v104, s10
	ds_write_b16_d16_hi v88, v98 offset:2736
	ds_write_b16_d16_hi v88, v99 offset:7344
	s_waitcnt vmcnt(34)
	v_lshlrev_b32_e32 v98, 16, v159
	v_max_f32_e32 v98, v98, v98
	v_med3_f32 v98, v98, s9, v244
	v_mul_f32_e32 v98, 0xbfb8aa3b, v98
	v_exp_f32_e32 v98, v98
	s_nop 0
	v_add_f32_e32 v104, 1.0, v98
	v_rcp_f32_e32 v104, v104
	s_nop 0
	v_fma_f32 v105, v117, v104, v116
	v_mul_f32_e32 v84, v84, v105
	v_mul_f32_e32 v98, v98, v104
	v_max_f32_e32 v104, 0xda24260, v84
	v_rcp_f32_e32 v84, v104
	v_mul_f32_e32 v98, v117, v98
	v_mul_f32_e32 v84, v98, v84
	v_bfe_u32 v98, v84, 16, 1
	v_add3_u32 v84, v84, v98, s10
	v_lshlrev_b32_e32 v98, 16, v157
	v_mul_f32_e32 v98, v104, v98
	v_bfe_u32 v105, v98, 16, 1
	v_add3_u32 v98, v98, v105, s10
	ds_write_b16_d16_hi v88, v98 offset:2592
	ds_write_b16_d16_hi v88, v84 offset:7200
	v_lshlrev_b32_e32 v98, 16, v155
	v_max_f32_e32 v98, v98, v98
	v_med3_f32 v98, v98, s9, v244
	v_mul_f32_e32 v98, 0xbfb8aa3b, v98
	v_exp_f32_e32 v98, v98
	s_nop 0
	v_add_f32_e32 v105, 1.0, v98
	v_rcp_f32_e32 v105, v105
	s_nop 0
	v_fma_f32 v155, v117, v105, v116
	v_mul_f32_e32 v104, v104, v155
	v_max_f32_e32 v104, 0xda24260, v104
	v_mul_f32_e32 v98, v98, v105
	v_rcp_f32_e32 v105, v104
	v_mul_f32_e32 v98, v117, v98
	v_mul_f32_e32 v98, v98, v105
	v_bfe_u32 v105, v98, 16, 1
	v_add3_u32 v105, v98, v105, s10
	s_waitcnt vmcnt(23)
	v_lshlrev_b32_e32 v98, 16, v156
	v_mul_f32_e32 v98, v104, v98
	v_bfe_u32 v155, v98, 16, 1
	v_add3_u32 v98, v98, v155, s10
	ds_write_b16_d16_hi v88, v98 offset:2448
	ds_write_b16_d16_hi v88, v105 offset:7056
	v_lshlrev_b32_e32 v98, 16, v109
	v_max_f32_e32 v98, v98, v98
	v_med3_f32 v98, v98, s9, v244
	v_mul_f32_e32 v98, 0xbfb8aa3b, v98
	v_exp_f32_e32 v98, v98
	s_nop 0
	v_add_f32_e32 v109, 1.0, v98
	v_rcp_f32_e32 v109, v109
	s_nop 0
	v_fma_f32 v155, v117, v109, v116
	v_mul_f32_e32 v104, v104, v155
	v_max_f32_e32 v104, 0xda24260, v104
	v_mul_f32_e32 v98, v98, v109
	v_rcp_f32_e32 v109, v104
	v_mul_f32_e32 v98, v117, v98
	v_mul_f32_e32 v107, v104, v107
	v_mul_f32_e32 v98, v98, v109
	v_bfe_u32 v109, v98, 16, 1
	v_add3_u32 v98, v98, v109, s10
	v_bfe_u32 v109, v107, 16, 1
	v_add3_u32 v107, v107, v109, s10
	ds_write_b16_d16_hi v88, v107 offset:2304
	ds_write_b16_d16_hi v88, v98 offset:6912
	s_waitcnt vmcnt(15)
	v_lshlrev_b32_e32 v107, 16, v168
	v_max_f32_e32 v107, v107, v107
	v_med3_f32 v107, v107, s9, v244
	v_mul_f32_e32 v107, 0xbfb8aa3b, v107
	v_exp_f32_e32 v107, v107
	s_nop 0
	v_add_f32_e32 v109, 1.0, v107
	v_rcp_f32_e32 v109, v109
	s_nop 0
	v_fma_f32 v155, v117, v109, v116
	v_mul_f32_e32 v104, v104, v155
	v_max_f32_e32 v104, 0xda24260, v104
	v_mul_f32_e32 v107, v107, v109
	v_rcp_f32_e32 v109, v104
	v_mul_f32_e32 v107, v117, v107
	v_mul_f32_e32 v107, v107, v109
	v_bfe_u32 v109, v107, 16, 1
	v_add3_u32 v107, v107, v109, s10
	s_waitcnt vmcnt(14)
	v_lshlrev_b32_e32 v109, 16, v166
	v_mul_f32_e32 v109, v104, v109
	v_bfe_u32 v155, v109, 16, 1
	v_add3_u32 v109, v109, v155, s10
	ds_write_b16_d16_hi v88, v109 offset:2160
	ds_write_b16_d16_hi v88, v107 offset:6768
	s_waitcnt vmcnt(13)
	v_lshlrev_b32_e32 v109, 16, v165
	v_max_f32_e32 v109, v109, v109
	v_med3_f32 v109, v109, s9, v244
	v_mul_f32_e32 v109, 0xbfb8aa3b, v109
	v_exp_f32_e32 v109, v109
	global_load_ushort v172, v[74:75], off offset:3072
	global_load_ushort v170, v[74:75], off offset:1536
	global_load_ushort v171, v[70:71], off offset:2560
	global_load_ushort v168, v[70:71], off offset:1024
	global_load_ushort v169, v[76:77], off offset:2048
	global_load_ushort v166, v[76:77], off offset:512
	global_load_ushort v167, v[68:69], off offset:1536
	global_load_ushort v162, v[68:69], off
	global_load_ushort v164, v[78:79], off offset:1024
	v_add_co_u32_e32 v68, vcc, s11, v64
	v_add_f32_e32 v155, 1.0, v109
	v_rcp_f32_e32 v155, v155
	v_addc_co_u32_e32 v69, vcc, 0, v65, vcc
	v_fma_f32 v156, v117, v155, v116
	v_mul_f32_e32 v104, v104, v156
	v_max_f32_e32 v173, 0xda24260, v104
	v_rcp_f32_e32 v104, v173
	v_mul_f32_e32 v109, v109, v155
	v_mul_f32_e32 v109, v117, v109
	v_mul_f32_e32 v104, v109, v104
	v_bfe_u32 v109, v104, 16, 1
	v_add3_u32 v104, v104, v109, s10
	s_waitcnt vmcnt(21)
	v_lshlrev_b32_e32 v109, 16, v160
	v_mul_f32_e32 v109, v173, v109
	v_bfe_u32 v155, v109, 16, 1
	v_add3_u32 v109, v109, v155, s10
	global_load_ushort v163, v[68:69], off offset:3584
	global_load_ushort v165, v[68:69], off offset:512
	global_load_ushort v159, v[66:67], off offset:3072
	global_load_ushort v160, v[66:67], off
	global_load_ushort v156, v[72:73], off offset:2560
	global_load_ushort v157, v[64:65], off offset:3584
	global_load_ushort v155, v[64:65], off offset:2048
	s_waitcnt vmcnt(27)
	v_lshlrev_b32_e32 v64, 16, v158
	v_max_f32_e32 v64, v64, v64
	v_med3_f32 v64, v64, s9, v244
	v_mul_f32_e32 v64, 0xbfb8aa3b, v64
	v_exp_f32_e32 v64, v64
	ds_write_b16_d16_hi v88, v109 offset:2016
	ds_write_b16_d16_hi v88, v104 offset:6624
	v_add_f32_e32 v65, 1.0, v64
	v_rcp_f32_e32 v65, v65
	s_nop 0
	v_fma_f32 v66, v117, v65, v116
	v_mul_f32_e32 v64, v64, v65
	v_mul_f32_e32 v65, v173, v66
	v_max_f32_e32 v65, 0xda24260, v65
	v_rcp_f32_e32 v66, v65
	v_mul_f32_e32 v64, v117, v64
	v_mul_f32_e32 v64, v64, v66
	v_bfe_u32 v66, v64, 16, 1
	v_add3_u32 v64, v64, v66, s10
	s_waitcnt vmcnt(26)
	v_lshlrev_b32_e32 v66, 16, v113
	v_mul_f32_e32 v66, v65, v66
	v_bfe_u32 v67, v66, 16, 1
	v_add3_u32 v66, v66, v67, s10
	ds_write_b16_d16_hi v88, v66 offset:1872
	ds_write_b16_d16_hi v88, v64 offset:6480
	s_waitcnt vmcnt(25)
	v_lshlrev_b32_e32 v66, 16, v111
	v_max_f32_e32 v66, v66, v66
	v_med3_f32 v66, v66, s9, v244
	v_mul_f32_e32 v66, 0xbfb8aa3b, v66
	v_exp_f32_e32 v66, v66
	s_nop 0
	v_add_f32_e32 v67, 1.0, v66
	v_rcp_f32_e32 v67, v67
	s_nop 0
	v_fma_f32 v68, v117, v67, v116
	v_mul_f32_e32 v65, v65, v68
	v_max_f32_e32 v65, 0xda24260, v65
	v_mul_f32_e32 v66, v66, v67
	v_rcp_f32_e32 v67, v65
	v_mul_f32_e32 v66, v117, v66
	v_mul_f32_e32 v66, v66, v67
	v_bfe_u32 v67, v66, 16, 1
	v_add3_u32 v158, v66, v67, s10
	s_waitcnt vmcnt(24)
	v_lshlrev_b32_e32 v66, 16, v103
	v_mul_f32_e32 v66, v65, v66
	v_bfe_u32 v67, v66, 16, 1
	v_add3_u32 v66, v66, v67, s10
	ds_write_b16_d16_hi v88, v66 offset:1728
	ds_write_b16_d16_hi v88, v158 offset:6336
	s_waitcnt vmcnt(23)
	v_lshlrev_b32_e32 v66, 16, v102
	v_max_f32_e32 v66, v66, v66
	v_med3_f32 v66, v66, s9, v244
	v_mul_f32_e32 v66, 0xbfb8aa3b, v66
	v_exp_f32_e32 v66, v66
	s_nop 0
	v_add_f32_e32 v67, 1.0, v66
	v_rcp_f32_e32 v67, v67
	s_nop 0
	v_fma_f32 v68, v117, v67, v116
	v_mul_f32_e32 v65, v65, v68
	v_max_f32_e32 v65, 0xda24260, v65
	v_mul_f32_e32 v66, v66, v67
	v_rcp_f32_e32 v67, v65
	v_mul_f32_e32 v66, v117, v66
	v_mul_f32_e32 v66, v66, v67
	v_bfe_u32 v67, v66, 16, 1
	v_add3_u32 v66, v66, v67, s10
	s_waitcnt vmcnt(22)
	v_lshlrev_b32_e32 v67, 16, v101
	v_mul_f32_e32 v67, v65, v67
	v_bfe_u32 v68, v67, 16, 1
	v_add3_u32 v67, v67, v68, s10
	ds_write_b16_d16_hi v88, v67 offset:1584
	ds_write_b16_d16_hi v88, v66 offset:6192
	s_waitcnt vmcnt(21)
	v_lshlrev_b32_e32 v67, 16, v100
	v_max_f32_e32 v67, v67, v67
	v_med3_f32 v67, v67, s9, v244
	v_mul_f32_e32 v67, 0xbfb8aa3b, v67
	v_exp_f32_e32 v67, v67
	s_nop 0
	v_add_f32_e32 v68, 1.0, v67
	v_rcp_f32_e32 v68, v68
	s_nop 0
	v_fma_f32 v69, v117, v68, v116
	v_mul_f32_e32 v65, v65, v69
	v_max_f32_e32 v65, 0xda24260, v65
	v_mul_f32_e32 v67, v67, v68
	v_rcp_f32_e32 v68, v65
	v_mul_f32_e32 v67, v117, v67
	v_mul_f32_e32 v67, v67, v68
	v_bfe_u32 v68, v67, 16, 1
	v_add3_u32 v100, v67, v68, s10
	s_waitcnt vmcnt(20)
	v_lshlrev_b32_e32 v67, 16, v87
	v_mul_f32_e32 v67, v65, v67
	v_bfe_u32 v68, v67, 16, 1
	v_add3_u32 v67, v67, v68, s10
	ds_write_b16_d16_hi v88, v67 offset:1440
	ds_write_b16_d16_hi v88, v100 offset:6048
	s_waitcnt vmcnt(19)
	v_lshlrev_b32_e32 v67, 16, v86
	v_max_f32_e32 v67, v67, v67
	v_med3_f32 v67, v67, s9, v244
	v_mul_f32_e32 v67, 0xbfb8aa3b, v67
	v_exp_f32_e32 v67, v67
	s_nop 0
	v_add_f32_e32 v68, 1.0, v67
	v_rcp_f32_e32 v68, v68
	s_nop 0
	v_fma_f32 v69, v117, v68, v116
	v_mul_f32_e32 v65, v65, v69
	v_max_f32_e32 v65, 0xda24260, v65
	v_mul_f32_e32 v67, v67, v68
	v_rcp_f32_e32 v68, v65
	v_mul_f32_e32 v67, v117, v67
	v_mul_f32_e32 v67, v67, v68
	v_bfe_u32 v68, v67, 16, 1
	v_add3_u32 v67, v67, v68, s10
	s_waitcnt vmcnt(18)
	v_lshlrev_b32_e32 v68, 16, v83
	v_mul_f32_e32 v68, v65, v68
	v_bfe_u32 v69, v68, 16, 1
	v_add3_u32 v68, v68, v69, s10
	ds_write_b16_d16_hi v88, v68 offset:1296
	ds_write_b16_d16_hi v88, v67 offset:5904
	s_waitcnt vmcnt(17)
	v_lshlrev_b32_e32 v68, 16, v82
	v_max_f32_e32 v68, v68, v68
	v_med3_f32 v68, v68, s9, v244
	v_mul_f32_e32 v68, 0xbfb8aa3b, v68
	v_exp_f32_e32 v68, v68
	s_nop 0
	v_add_f32_e32 v69, 1.0, v68
	v_rcp_f32_e32 v69, v69
	s_nop 0
	v_fma_f32 v70, v117, v69, v116
	v_mul_f32_e32 v65, v65, v70
	v_max_f32_e32 v76, 0xda24260, v65
	v_rcp_f32_e32 v65, v76
	v_mul_f32_e32 v68, v68, v69
	v_mul_f32_e32 v68, v117, v68
	v_mul_f32_e32 v65, v68, v65
	v_bfe_u32 v68, v65, 16, 1
	v_add3_u32 v82, v65, v68, s10
	s_waitcnt vmcnt(16)
	v_lshlrev_b32_e32 v65, 16, v81
	v_mul_f32_e32 v65, v76, v65
	v_bfe_u32 v68, v65, 16, 1
	v_add3_u32 v65, v65, v68, s10
	ds_write_b16_d16_hi v88, v65 offset:1152
	ds_write_b16_d16_hi v88, v82 offset:5760
	s_waitcnt vmcnt(15)
	v_lshlrev_b32_e32 v72, 16, v172
	v_max_f32_e32 v72, v72, v72
	v_med3_f32 v72, v72, s9, v244
	v_mul_f32_e32 v72, 0xbfb8aa3b, v72
	v_exp_f32_e32 v86, v72
	v_and_b32_e32 v111, 0xffff0000, v66
	v_lshl_or_b32 v66, v106, 16, v122
	v_and_b32_e32 v113, 0xffff0000, v67
	v_add_f32_e32 v77, 1.0, v86
	v_rcp_f32_e32 v102, v77
	v_lshl_or_b32 v67, v108, 16, v110
	v_and_b32_e32 v81, 0xffff0000, v112
	v_lshl_or_b32 v75, v149, 16, v127
	v_fma_f32 v106, v117, v102, v116
	v_mul_f32_e32 v76, v76, v106
	v_max_f32_e32 v106, 0xda24260, v76
	v_rcp_f32_e32 v108, v106
	v_mul_f32_e32 v86, v86, v102
	v_mul_f32_e32 v86, v117, v86
	v_lshl_or_b32 v65, v133, 16, v121
	v_mul_f32_e32 v86, v86, v108
	v_bfe_u32 v102, v86, 16, 1
	v_add3_u32 v86, v86, v102, s10
	s_waitcnt vmcnt(13)
	v_lshlrev_b32_e32 v102, 16, v171
	v_max_f32_e32 v102, v102, v102
	v_med3_f32 v102, v102, s9, v244
	v_mul_f32_e32 v102, 0xbfb8aa3b, v102
	v_exp_f32_e32 v102, v102
	v_lshlrev_b32_e32 v108, 16, v170
	v_mul_f32_e32 v108, v106, v108
	v_bfe_u32 v112, v108, 16, 1
	v_add_f32_e32 v110, 1.0, v102
	v_rcp_f32_e32 v110, v110
	v_add3_u32 v108, v108, v112, s10
	ds_write_b16_d16_hi v88, v108 offset:1008
	v_and_b32_e32 v127, 0xffff0000, v86
	v_fma_f32 v108, v117, v110, v116
	v_mul_f32_e32 v106, v106, v108
	v_max_f32_e32 v106, 0xda24260, v106
	v_rcp_f32_e32 v108, v106
	ds_write_b16_d16_hi v88, v86 offset:5616
	v_mul_f32_e32 v86, v102, v110
	v_mul_f32_e32 v86, v117, v86
	v_mul_f32_e32 v86, v86, v108
	s_waitcnt vmcnt(11)
	v_lshlrev_b32_e32 v108, 16, v169
	v_max_f32_e32 v108, v108, v108
	v_med3_f32 v108, v108, s9, v244
	v_mul_f32_e32 v108, 0xbfb8aa3b, v108
	v_exp_f32_e32 v108, v108
	v_bfe_u32 v102, v86, 16, 1
	v_add3_u32 v86, v86, v102, s10
	v_lshlrev_b32_e32 v102, 16, v168
	v_add_f32_e32 v110, 1.0, v108
	v_rcp_f32_e32 v110, v110
	v_mul_f32_e32 v102, v106, v102
	v_bfe_u32 v112, v102, 16, 1
	v_add3_u32 v102, v102, v112, s10
	ds_write_b16_d16_hi v88, v102 offset:864
	v_fma_f32 v102, v117, v110, v116
	v_mul_f32_e32 v102, v106, v102
	v_max_f32_e32 v102, 0xda24260, v102
	v_rcp_f32_e32 v106, v102
	v_mul_f32_e32 v108, v108, v110
	v_mul_f32_e32 v108, v117, v108
	s_waitcnt vmcnt(10)
	v_lshlrev_b32_e32 v110, 16, v166
	v_mul_f32_e32 v106, v108, v106
	v_bfe_u32 v108, v106, 16, 1
	v_add3_u32 v106, v106, v108, s10
	s_waitcnt vmcnt(9)
	v_lshlrev_b32_e32 v108, 16, v167
	v_max_f32_e32 v108, v108, v108
	v_med3_f32 v108, v108, s9, v244
	v_mul_f32_e32 v108, 0xbfb8aa3b, v108
	v_exp_f32_e32 v108, v108
	v_mul_f32_e32 v110, v102, v110
	v_bfe_u32 v121, v110, 16, 1
	v_add3_u32 v110, v110, v121, s10
	v_add_f32_e32 v112, 1.0, v108
	v_rcp_f32_e32 v112, v112
	ds_write_b16_d16_hi v88, v110 offset:720
	v_lshl_or_b32 v74, v147, 16, v125
	v_and_b32_e32 v125, 0xffff0000, v106
	v_fma_f32 v110, v117, v112, v116
	v_mul_f32_e32 v102, v102, v110
	v_max_f32_e32 v102, 0xda24260, v102
	v_rcp_f32_e32 v110, v102
	ds_write_b16_d16_hi v88, v106 offset:5328
	v_mul_f32_e32 v106, v108, v112
	v_mul_f32_e32 v106, v117, v106
	v_mul_f32_e32 v106, v106, v110
	s_waitcnt vmcnt(7)
	v_lshlrev_b32_e32 v110, 16, v164
	v_max_f32_e32 v110, v110, v110
	v_med3_f32 v110, v110, s9, v244
	v_mul_f32_e32 v110, 0xbfb8aa3b, v110
	v_exp_f32_e32 v110, v110
	v_bfe_u32 v108, v106, 16, 1
	v_add3_u32 v106, v106, v108, s10
	v_lshlrev_b32_e32 v108, 16, v162
	v_add_f32_e32 v112, 1.0, v110
	v_rcp_f32_e32 v112, v112
	v_mul_f32_e32 v108, v102, v108
	v_bfe_u32 v121, v108, 16, 1
	v_add3_u32 v108, v108, v121, s10
	ds_write_b16_d16_hi v88, v108 offset:576
	v_fma_f32 v108, v117, v112, v116
	v_mul_f32_e32 v102, v102, v108
	v_max_f32_e32 v102, 0xda24260, v102
	v_rcp_f32_e32 v108, v102
	v_mul_f32_e32 v110, v110, v112
	v_mul_f32_e32 v110, v117, v110
	s_waitcnt vmcnt(6)
	v_lshlrev_b32_e32 v112, 16, v163
	v_mul_f32_e32 v108, v110, v108
	v_bfe_u32 v110, v108, 16, 1
	v_add3_u32 v108, v108, v110, s10
	s_waitcnt vmcnt(5)
	v_lshlrev_b32_e32 v110, 16, v165
	v_max_f32_e32 v110, v110, v110
	v_med3_f32 v110, v110, s9, v244
	v_mul_f32_e32 v110, 0xbfb8aa3b, v110
	v_exp_f32_e32 v110, v110
	v_mul_f32_e32 v112, v102, v112
	v_bfe_u32 v122, v112, 16, 1
	v_add3_u32 v112, v112, v122, s10
	v_add_f32_e32 v121, 1.0, v110
	v_rcp_f32_e32 v121, v121
	ds_write_b16_d16_hi v88, v112 offset:432
	v_lshl_or_b32 v69, v135, 16, v129
	v_and_b32_e32 v129, 0xffff0000, v108
	v_fma_f32 v112, v117, v121, v116
	v_mul_f32_e32 v102, v102, v112
	v_max_f32_e32 v102, 0xda24260, v102
	v_rcp_f32_e32 v112, v102
	ds_write_b16_d16_hi v88, v108 offset:5040
	v_mul_f32_e32 v108, v110, v121
	v_mul_f32_e32 v108, v117, v108
	v_mul_f32_e32 v108, v108, v112
	s_waitcnt vmcnt(3)
	v_lshlrev_b32_e32 v112, 16, v160
	v_max_f32_e32 v112, v112, v112
	v_med3_f32 v112, v112, s9, v244
	v_mul_f32_e32 v112, 0xbfb8aa3b, v112
	v_exp_f32_e32 v112, v112
	v_bfe_u32 v110, v108, 16, 1
	v_add3_u32 v108, v108, v110, s10
	v_lshlrev_b32_e32 v110, 16, v159
	v_add_f32_e32 v121, 1.0, v112
	v_rcp_f32_e32 v121, v121
	v_mul_f32_e32 v110, v102, v110
	v_bfe_u32 v122, v110, 16, 1
	v_add3_u32 v110, v110, v122, s10
	ds_write_b16_d16_hi v88, v110 offset:288
	v_fma_f32 v110, v117, v121, v116
	v_mul_f32_e32 v102, v102, v110
	v_max_f32_e32 v102, 0xda24260, v102
	v_rcp_f32_e32 v110, v102
	v_mul_f32_e32 v112, v112, v121
	v_mul_f32_e32 v112, v117, v112
	s_waitcnt vmcnt(2)
	v_lshlrev_b32_e32 v121, 16, v156
	v_mul_f32_e32 v110, v112, v110
	v_bfe_u32 v112, v110, 16, 1
	v_add3_u32 v110, v110, v112, s10
	s_waitcnt vmcnt(1)
	v_lshlrev_b32_e32 v112, 16, v157
	v_max_f32_e32 v112, v112, v112
	v_med3_f32 v112, v112, s9, v244
	v_mul_f32_e32 v112, 0xbfb8aa3b, v112
	v_exp_f32_e32 v112, v112
	v_mul_f32_e32 v121, v102, v121
	v_lshl_or_b32 v70, v137, 16, v123
	v_and_b32_e32 v123, 0xffff0000, v110
	v_add_f32_e32 v122, 1.0, v112
	v_rcp_f32_e32 v122, v122
	ds_write_b16_d16_hi v88, v110 offset:4752
	v_lshl_or_b32 v71, v131, 16, v124
	v_bfe_u32 v124, v121, 16, 1
	v_fmac_f32_e32 v116, v117, v122
	v_mul_f32_e32 v102, v102, v116
	v_max_f32_e32 v116, 0xda24260, v102
	v_rcp_f32_e32 v102, v116
	v_mul_f32_e32 v110, v112, v122
	v_mul_f32_e32 v110, v117, v110
	v_readlane_b32 s9, v255, 34
	v_mul_f32_e32 v102, v110, v102
	v_bfe_u32 v110, v102, 16, 1
	v_add3_u32 v102, v102, v110, s10
	s_waitcnt vmcnt(0)
	v_lshlrev_b32_e32 v110, 16, v155
	v_mul_f32_e32 v110, v116, v110
	v_bfe_u32 v112, v110, 16, 1
	v_add3_u32 v121, v121, v124, s10
	v_add3_u32 v110, v110, v112, s10
	v_readlane_b32 s10, v255, 36
	v_and_b32_e32 v109, 0xffff0000, v64
	v_and_b32_e32 v107, 0xffff0000, v107
	v_and_b32_e32 v105, 0xffff0000, v105
	v_and_b32_e32 v103, 0xffff0000, v99
	v_and_b32_e32 v101, 0xffff0000, v85
	v_and_b32_e32 v99, 0xffff0000, v154
	v_and_b32_e32 v87, 0xffff0000, v153
	v_and_b32_e32 v85, 0xffff0000, v152
	v_and_b32_e32 v83, 0xffff0000, v151
	v_lshl_or_b32 v64, v132, 16, v126
	v_lshl_or_b32 v68, v148, 16, v128
	v_lshl_or_b32 v73, v142, 16, v141
	v_lshl_or_b32 v72, v146, 16, v139
	v_lshl_or_b32 v79, v144, 16, v138
	v_lshl_or_b32 v78, v145, 16, v136
	v_lshl_or_b32 v77, v140, 16, v134
	v_lshl_or_b32 v76, v143, 16, v130
	ds_write_b16_d16_hi v88, v86 offset:5472
	ds_write_b16_d16_hi v88, v106 offset:5184
	ds_write_b16_d16_hi v88, v108 offset:4896
	ds_write_b16_d16_hi v88, v121 offset:144
	ds_write_b16_d16_hi v88, v110
	ds_write_b16_d16_hi v88, v102 offset:4608
	v_and_b32_e32 v122, 0xffff0000, v102
	v_and_b32_e32 v128, 0xffff0000, v108
	v_and_b32_e32 v124, 0xffff0000, v106
	v_and_b32_e32 v126, 0xffff0000, v86
	v_pk_mul_f32 v[122:123], v[116:117], v[122:123] op_sel_hi:[0,1]
	v_pk_mul_f32 v[128:129], v[116:117], v[128:129] op_sel_hi:[0,1]
	v_pk_mul_f32 v[124:125], v[116:117], v[124:125] op_sel_hi:[0,1]
	v_pk_mul_f32 v[126:127], v[116:117], v[126:127] op_sel_hi:[0,1]
	v_and_b32_e32 v112, 0xffff0000, v82
	v_and_b32_e32 v110, 0xffff0000, v100
	v_and_b32_e32 v108, 0xffff0000, v158
	v_and_b32_e32 v106, 0xffff0000, v104
	v_and_b32_e32 v104, 0xffff0000, v98
	v_and_b32_e32 v102, 0xffff0000, v84
	v_and_b32_e32 v100, 0xffff0000, v80
	v_and_b32_e32 v98, 0xffff0000, v150
	v_and_b32_e32 v86, 0xffff0000, v120
	v_and_b32_e32 v84, 0xffff0000, v119
	v_and_b32_e32 v82, 0xffff0000, v118
	v_and_b32_e32 v80, 0xffff0000, v95
	v_mad_u64_u32 v[130:131], s[2:3], v94, s4, v[92:93]
	v_cvt_pk_bf16_f32 v122, v122, v123
	v_cvt_pk_bf16_f32 v123, v128, v129
	v_cvt_pk_bf16_f32 v124, v124, v125
	v_cvt_pk_bf16_f32 v125, v126, v127
	v_pk_mul_f32 v[112:113], v[116:117], v[112:113] op_sel_hi:[0,1]
	v_pk_mul_f32 v[110:111], v[116:117], v[110:111] op_sel_hi:[0,1]
	v_pk_mul_f32 v[108:109], v[116:117], v[108:109] op_sel_hi:[0,1]
	v_pk_mul_f32 v[106:107], v[116:117], v[106:107] op_sel_hi:[0,1]
	v_pk_mul_f32 v[104:105], v[116:117], v[104:105] op_sel_hi:[0,1]
	v_pk_mul_f32 v[102:103], v[116:117], v[102:103] op_sel_hi:[0,1]
	v_pk_mul_f32 v[100:101], v[116:117], v[100:101] op_sel_hi:[0,1]
	v_pk_mul_f32 v[98:99], v[116:117], v[98:99] op_sel_hi:[0,1]
	v_pk_mul_f32 v[86:87], v[116:117], v[86:87] op_sel_hi:[0,1]
	v_pk_mul_f32 v[84:85], v[116:117], v[84:85] op_sel_hi:[0,1]
	v_pk_mul_f32 v[82:83], v[116:117], v[82:83] op_sel_hi:[0,1]
	v_pk_mul_f32 v[80:81], v[116:117], v[80:81] op_sel_hi:[0,1]
	ds_write_b128 v130, v[122:125] offset:9216
	v_cvt_pk_bf16_f32 v122, v112, v113
	v_cvt_pk_bf16_f32 v123, v110, v111
	v_cvt_pk_bf16_f32 v124, v108, v109
	v_cvt_pk_bf16_f32 v125, v106, v107
	v_cvt_pk_bf16_f32 v104, v104, v105
	v_cvt_pk_bf16_f32 v105, v102, v103
	v_cvt_pk_bf16_f32 v106, v100, v101
	v_cvt_pk_bf16_f32 v107, v98, v99
	v_cvt_pk_bf16_f32 v98, v86, v87
	v_cvt_pk_bf16_f32 v99, v84, v85
	v_cvt_pk_bf16_f32 v100, v82, v83
	v_cvt_pk_bf16_f32 v101, v80, v81
	v_lshl_add_u32 v80, v94, 2, v92
	ds_write_b128 v130, v[122:125] offset:9232
	ds_write_b128 v130, v[104:107] offset:9248
	ds_write_b128 v130, v[98:101] offset:9264
	ds_write_b32 v80, v116 offset:19456
	ds_write_b128 v130, v[76:79] offset:14336
	ds_write_b128 v130, v[72:75] offset:14352
	ds_write_b128 v130, v[68:71] offset:14368
	ds_write_b128 v130, v[64:67] offset:14384
	s_waitcnt lgkmcnt(0)
	v_or_b32_e32 v88, v93, v114
	v_lshlrev_b64 v[64:65], 11, v[88:89]
	v_lshlrev_b32_e32 v98, 2, v115
	v_lshl_add_u64 v[64:65], s[12:13], 0, v[64:65]
	v_ashrrev_i32_e32 v99, 31, v98
	v_lshl_add_u64 v[64:65], v[64:65], 0, v[90:91]
	v_lshlrev_b64 v[100:101], 1, v[98:99]
	v_lshl_add_u64 v[102:103], v[64:65], 0, v[100:101]
	s_mov_b64 s[2:3], 0x16f00600
	v_lshl_add_u64 v[94:95], v[102:103], 0, s[2:3]
	s_movk_i32 s2, 0x90
	v_mad_u32_u24 v89, v114, s2, v92
	v_lshl_add_u32 v93, v115, 4, v89
	ds_read_b128 v[64:67], v93 offset:4608
	ds_read_b128 v[68:71], v93
	ds_read_b128 v[80:83], v93 offset:32
	ds_read_b128 v[84:87], v93 offset:4640
	s_waitcnt lgkmcnt(2)
	v_mfma_f32_32x32x16_bf16 v[64:79], v[64:67], v[68:71], 0
	v_cmp_ge_i32_e32 vcc, v98, v114
	v_cvt_pk_bf16_f32 v32, v32, v33
	v_cvt_pk_bf16_f32 v33, v34, v35
	v_cvt_pk_bf16_f32 v34, v36, v37
	v_cvt_pk_bf16_f32 v35, v38, v39
	v_cvt_pk_bf16_f32 v36, v48, v49
	v_cvt_pk_bf16_f32 v37, v50, v51
	s_waitcnt lgkmcnt(0)
	v_mfma_f32_32x32x16_bf16 v[64:79], v[84:87], v[80:83], v[64:79]
	ds_read_b128 v[80:83], v93 offset:4672
	ds_read_b128 v[84:87], v93 offset:64
	v_cvt_pk_bf16_f32 v38, v52, v53
	v_cvt_pk_bf16_f32 v39, v54, v55
	s_mov_b32 s2, 0x16f00000
	s_waitcnt lgkmcnt(0)
	v_mfma_f32_32x32x16_bf16 v[64:79], v[80:83], v[84:87], v[64:79]
	ds_read_b128 v[80:83], v93 offset:4704
	ds_read_b128 v[84:87], v93 offset:96
	s_waitcnt lgkmcnt(0)
	v_mfma_f32_32x32x16_bf16 v[64:79], v[80:83], v[84:87], v[64:79]
	v_or_b32_e32 v80, 1, v98
	s_nop 10
	v_cndmask_b32_e32 v64, 0, v64, vcc
	v_cmp_ge_i32_e32 vcc, v80, v114
	v_or_b32_e32 v80, 2, v98
	s_nop 0
	v_cndmask_b32_e32 v65, 0, v65, vcc
	v_cmp_ge_i32_e32 vcc, v80, v114
	v_or_b32_e32 v80, 3, v98
	s_nop 0
	v_cndmask_b32_e32 v66, 0, v66, vcc
	v_cmp_ge_i32_e32 vcc, v80, v114
	v_add_u32_e32 v80, 8, v98
	s_nop 0
	v_cndmask_b32_e32 v67, 0, v67, vcc
	v_cmp_ge_i32_e32 vcc, v80, v114
	v_add_u32_e32 v80, 9, v98
	v_cvt_pk_bf16_f32 v81, v66, v67
	v_cndmask_b32_e32 v68, 0, v68, vcc
	v_cmp_ge_i32_e32 vcc, v80, v114
	v_add_u32_e32 v80, 10, v98
	s_nop 0
	v_cndmask_b32_e32 v69, 0, v69, vcc
	v_cmp_ge_i32_e32 vcc, v80, v114
	v_add_u32_e32 v80, 11, v98
	v_cvt_pk_bf16_f32 v82, v68, v69
	v_cndmask_b32_e32 v70, 0, v70, vcc
	v_cmp_ge_i32_e32 vcc, v80, v114
	v_add_u32_e32 v80, 16, v98
	s_nop 0
	v_cndmask_b32_e32 v71, 0, v71, vcc
	v_cmp_ge_i32_e32 vcc, v80, v114
	v_add_u32_e32 v80, 17, v98
	v_cvt_pk_bf16_f32 v83, v70, v71
	v_cndmask_b32_e32 v72, 0, v72, vcc
	v_cmp_ge_i32_e32 vcc, v80, v114
	v_add_u32_e32 v80, 18, v98
	s_nop 0
	v_cndmask_b32_e32 v73, 0, v73, vcc
	v_cmp_ge_i32_e32 vcc, v80, v114
	v_add_u32_e32 v80, 19, v98
	v_cvt_pk_bf16_f32 v84, v72, v73
	v_cndmask_b32_e32 v74, 0, v74, vcc
	v_cmp_ge_i32_e32 vcc, v80, v114
	v_add_u32_e32 v80, 24, v98
	s_nop 0
	v_cndmask_b32_e32 v75, 0, v75, vcc
	v_cmp_ge_i32_e32 vcc, v80, v114
	v_add_u32_e32 v80, 25, v98
	v_cvt_pk_bf16_f32 v85, v74, v75
	v_cndmask_b32_e32 v76, 0, v76, vcc
	v_cmp_ge_i32_e32 vcc, v80, v114
	v_add_u32_e32 v80, 26, v98
	s_nop 0
	v_cndmask_b32_e32 v77, 0, v77, vcc
	v_cmp_ge_i32_e32 vcc, v80, v114
	v_add_u32_e32 v80, 27, v98
	v_cvt_pk_bf16_f32 v86, v76, v77
	v_cndmask_b32_e32 v78, 0, v78, vcc
	v_cmp_ge_i32_e32 vcc, v80, v114
	v_cvt_pk_bf16_f32 v80, v64, v65
	v_lshlrev_b32_e32 v64, 3, v115
	v_mul_u32_u24_e32 v65, 0x50, v114
	v_add3_u32 v92, v92, v64, v65
	v_add_u32_e32 v68, 0x3800, v92
	v_add_u32_e32 v89, v89, v64
	ds_read2_b64 v[64:67], v68 offset1:2
	ds_read2_b64 v[104:107], v68 offset0:4 offset1:6
	v_cndmask_b32_e32 v79, 0, v79, vcc
	v_cvt_pk_bf16_f32 v87, v78, v79
	s_waitcnt lgkmcnt(1)
	v_mfma_f32_32x32x16_bf16 v[64:79], v[64:67], v[80:83], 0
	v_add_co_u32_e32 v48, vcc, s2, v102
	s_nop 1
	v_addc_co_u32_e32 v49, vcc, 0, v103, vcc
	s_waitcnt lgkmcnt(0)
	v_mfma_f32_32x32x16_bf16 v[64:79], v[104:107], v[84:87], v[64:79]
	ds_read2_b64 v[104:107], v89 offset1:2
	ds_read2_b64 v[108:111], v89 offset0:4 offset1:6
	s_waitcnt lgkmcnt(1)
	v_mfma_f32_32x32x16_bf16 v[64:79], v[32:35], v[104:107], v[64:79]
	v_cvt_pk_bf16_f32 v32, v40, v41
	v_cvt_pk_bf16_f32 v33, v42, v43
	v_cvt_pk_bf16_f32 v34, v44, v45
	v_cvt_pk_bf16_f32 v35, v46, v47
	s_waitcnt lgkmcnt(0)
	s_nop 0
	v_mfma_f32_32x32x16_bf16 v[64:79], v[32:35], v[108:111], v[64:79]
	ds_read2_b64 v[32:35], v89 offset0:8 offset1:10
	s_waitcnt lgkmcnt(0)
	v_mfma_f32_32x32x16_bf16 v[64:79], v[36:39], v[32:35], v[64:79]
	ds_read2_b64 v[32:35], v89 offset0:12 offset1:14
	v_cvt_pk_bf16_f32 v36, v56, v57
	v_cvt_pk_bf16_f32 v37, v58, v59
	v_cvt_pk_bf16_f32 v38, v60, v61
	v_cvt_pk_bf16_f32 v39, v62, v63
	s_waitcnt lgkmcnt(0)
	s_nop 0
	v_mfma_f32_32x32x16_bf16 v[64:79], v[36:39], v[32:35], v[64:79]
	global_load_dwordx2 v[32:33], v[48:49], off offset:1536
	s_waitcnt vmcnt(0)
	v_lshlrev_b32_e32 v34, 16, v32
	v_and_b32_e32 v35, 0xffff0000, v32
	v_lshlrev_b32_e32 v32, 16, v33
	v_and_b32_e32 v33, 0xffff0000, v33
	s_nop 5
	v_pk_add_f32 v[34:35], v[64:65], v[34:35]
	v_pk_add_f32 v[32:33], v[66:67], v[32:33]
	v_mul_f32_e32 v36, v35, v35
	v_mul_f32_e32 v38, v33, v33
	v_pk_fma_f32 v[36:37], v[34:35], v[34:35], v[36:37] op_sel_hi:[1,1,0]
	v_pk_fma_f32 v[38:39], v[32:33], v[32:33], v[38:39] op_sel_hi:[1,1,0]
	v_cvt_pk_bf16_f32 v34, v34, v35
	v_cvt_pk_bf16_f32 v35, v32, v33
	global_load_dwordx2 v[32:33], v[94:95], off offset:16
	v_pk_add_f32 v[36:37], v[36:37], v[38:39]
	global_store_dwordx2 v[48:49], v[34:35], off offset:1536
	s_waitcnt vmcnt(1)
	v_lshlrev_b32_e32 v34, 16, v32
	v_and_b32_e32 v35, 0xffff0000, v32
	v_lshlrev_b32_e32 v32, 16, v33
	v_and_b32_e32 v33, 0xffff0000, v33
	v_pk_add_f32 v[34:35], v[68:69], v[34:35]
	v_pk_add_f32 v[32:33], v[70:71], v[32:33]
	v_mul_f32_e32 v38, v35, v35
	v_mul_f32_e32 v40, v33, v33
	v_pk_fma_f32 v[38:39], v[34:35], v[34:35], v[38:39] op_sel_hi:[1,1,0]
	v_pk_fma_f32 v[40:41], v[32:33], v[32:33], v[40:41] op_sel_hi:[1,1,0]
	v_cvt_pk_bf16_f32 v34, v34, v35
	v_cvt_pk_bf16_f32 v35, v32, v33
	global_load_dwordx2 v[32:33], v[94:95], off offset:32
	v_pk_add_f32 v[38:39], v[38:39], v[40:41]
	global_store_dwordx2 v[94:95], v[34:35], off offset:16
	v_pk_add_f32 v[36:37], v[36:37], v[38:39]
	s_waitcnt vmcnt(1)
	v_lshlrev_b32_e32 v34, 16, v32
	v_and_b32_e32 v35, 0xffff0000, v32
	v_pk_add_f32 v[34:35], v[72:73], v[34:35]
	v_lshlrev_b32_e32 v32, 16, v33
	v_and_b32_e32 v33, 0xffff0000, v33
	v_pk_add_f32 v[38:39], v[74:75], v[32:33]
	v_mul_f32_e32 v32, v35, v35
	v_pk_fma_f32 v[32:33], v[34:35], v[34:35], v[32:33] op_sel_hi:[1,1,0]
	v_cvt_pk_bf16_f32 v34, v34, v35
	v_cvt_pk_bf16_f32 v35, v38, v39
	global_store_dwordx2 v[94:95], v[34:35], off offset:32
	global_load_dwordx2 v[34:35], v[94:95], off offset:48
	v_mul_f32_e32 v40, v39, v39
	v_pk_fma_f32 v[40:41], v[38:39], v[38:39], v[40:41] op_sel_hi:[1,1,0]
	s_nop 0
	v_pk_add_f32 v[32:33], v[32:33], v[40:41]
	s_nop 0
	v_pk_add_f32 v[32:33], v[36:37], v[32:33]
	s_waitcnt vmcnt(0)
	v_lshlrev_b32_e32 v36, 16, v34
	v_and_b32_e32 v37, 0xffff0000, v34
	v_lshlrev_b32_e32 v34, 16, v35
	v_and_b32_e32 v35, 0xffff0000, v35
	v_pk_add_f32 v[36:37], v[76:77], v[36:37]
	v_pk_add_f32 v[34:35], v[78:79], v[34:35]
	v_mul_f32_e32 v38, v37, v37
	v_mul_f32_e32 v40, v35, v35
	v_pk_fma_f32 v[38:39], v[36:37], v[36:37], v[38:39] op_sel_hi:[1,1,0]
	v_pk_fma_f32 v[40:41], v[34:35], v[34:35], v[40:41] op_sel_hi:[1,1,0]
	s_nop 0
	v_pk_add_f32 v[38:39], v[38:39], v[40:41]
	s_nop 0
	v_pk_add_f32 v[58:59], v[32:33], v[38:39]
	v_cvt_pk_bf16_f32 v32, v36, v37
	v_cvt_pk_bf16_f32 v33, v34, v35
	global_store_dwordx2 v[94:95], v[32:33], off offset:48
	v_add_u32_e32 v36, 0x4000, v92
	ds_read2_b64 v[32:35], v36 offset0:64 offset1:66
	ds_read2_b64 v[50:53], v36 offset0:68 offset1:70
	v_cvt_pk_bf16_f32 v0, v0, v1
	v_cvt_pk_bf16_f32 v1, v2, v3
	v_cvt_pk_bf16_f32 v2, v4, v5
	s_waitcnt lgkmcnt(1)
	v_mfma_f32_32x32x16_bf16 v[32:47], v[32:35], v[80:83], 0
	v_cvt_pk_bf16_f32 v3, v6, v7
	v_cvt_pk_bf16_f32 v4, v16, v17
	v_cvt_pk_bf16_f32 v5, v18, v19
	v_cvt_pk_bf16_f32 v6, v20, v21
	v_cvt_pk_bf16_f32 v7, v22, v23
	s_waitcnt lgkmcnt(0)
	v_mfma_f32_32x32x16_bf16 v[32:47], v[50:53], v[84:87], v[32:47]
	ds_read2_b64 v[50:53], v89 offset1:2
	ds_read2_b64 v[54:57], v89 offset0:4 offset1:6
	s_waitcnt lgkmcnt(1)
	v_mfma_f32_32x32x16_bf16 v[32:47], v[0:3], v[50:53], v[32:47]
	v_cvt_pk_bf16_f32 v0, v8, v9
	v_cvt_pk_bf16_f32 v1, v10, v11
	v_cvt_pk_bf16_f32 v2, v12, v13
	v_cvt_pk_bf16_f32 v3, v14, v15
	s_waitcnt lgkmcnt(0)
	s_nop 0
	v_mfma_f32_32x32x16_bf16 v[32:47], v[0:3], v[54:57], v[32:47]
	ds_read2_b64 v[0:3], v89 offset0:8 offset1:10
	s_waitcnt lgkmcnt(0)
	v_mfma_f32_32x32x16_bf16 v[32:47], v[4:7], v[0:3], v[32:47]
	ds_read2_b64 v[0:3], v89 offset0:12 offset1:14
	v_cvt_pk_bf16_f32 v4, v24, v25
	v_cvt_pk_bf16_f32 v5, v26, v27
	v_cvt_pk_bf16_f32 v6, v28, v29
	v_cvt_pk_bf16_f32 v7, v30, v31
	s_waitcnt lgkmcnt(0)
	s_nop 0
	v_mfma_f32_32x32x16_bf16 v[32:47], v[4:7], v[0:3], v[32:47]
	global_load_dwordx2 v[0:1], v[94:95], off offset:64
	s_waitcnt vmcnt(0)
	v_lshlrev_b32_e32 v2, 16, v0
	v_and_b32_e32 v3, 0xffff0000, v0
	v_lshlrev_b32_e32 v0, 16, v1
	v_and_b32_e32 v1, 0xffff0000, v1
	s_nop 5
	v_pk_add_f32 v[2:3], v[32:33], v[2:3]
	v_pk_add_f32 v[0:1], v[34:35], v[0:1]
	v_mul_f32_e32 v4, v3, v3
	v_mul_f32_e32 v6, v1, v1
	v_pk_fma_f32 v[4:5], v[2:3], v[2:3], v[4:5] op_sel_hi:[1,1,0]
	v_pk_fma_f32 v[6:7], v[0:1], v[0:1], v[6:7] op_sel_hi:[1,1,0]
	v_cvt_pk_bf16_f32 v2, v2, v3
	v_cvt_pk_bf16_f32 v3, v0, v1
	global_load_dwordx2 v[0:1], v[94:95], off offset:80
	v_pk_add_f32 v[4:5], v[4:5], v[6:7]
	global_store_dwordx2 v[94:95], v[2:3], off offset:64
	v_pk_add_f32 v[4:5], v[58:59], v[4:5]
	s_waitcnt vmcnt(1)
	v_lshlrev_b32_e32 v2, 16, v0
	v_and_b32_e32 v3, 0xffff0000, v0
	v_lshlrev_b32_e32 v0, 16, v1
	v_and_b32_e32 v1, 0xffff0000, v1
	v_pk_add_f32 v[2:3], v[36:37], v[2:3]
	v_pk_add_f32 v[0:1], v[38:39], v[0:1]
	v_mul_f32_e32 v6, v3, v3
	v_mul_f32_e32 v8, v1, v1
	v_pk_fma_f32 v[6:7], v[2:3], v[2:3], v[6:7] op_sel_hi:[1,1,0]
	v_pk_fma_f32 v[8:9], v[0:1], v[0:1], v[8:9] op_sel_hi:[1,1,0]
	v_cvt_pk_bf16_f32 v2, v2, v3
	v_cvt_pk_bf16_f32 v3, v0, v1
	global_load_dwordx2 v[0:1], v[94:95], off offset:96
	v_pk_add_f32 v[6:7], v[6:7], v[8:9]
	global_store_dwordx2 v[94:95], v[2:3], off offset:80
	v_pk_add_f32 v[4:5], v[4:5], v[6:7]
	s_waitcnt vmcnt(1)
	v_lshlrev_b32_e32 v2, 16, v0
	v_and_b32_e32 v3, 0xffff0000, v0
	v_lshlrev_b32_e32 v0, 16, v1
	v_and_b32_e32 v1, 0xffff0000, v1
	v_pk_add_f32 v[2:3], v[40:41], v[2:3]
	v_pk_add_f32 v[6:7], v[42:43], v[0:1]
	v_mov_b32_e32 v0, v2
	v_mov_b32_e32 v8, v3
	v_cvt_pk_bf16_f32 v2, v2, v3
	v_cvt_pk_bf16_f32 v3, v6, v7
	global_store_dwordx2 v[94:95], v[2:3], off offset:96
	global_load_dwordx2 v[2:3], v[94:95], off offset:112
	v_mov_b32_e32 v9, v7
	v_mov_b32_e32 v1, v6
	v_pk_mul_f32 v[8:9], v[8:9], v[8:9]
	s_nop 0
	v_pk_fma_f32 v[0:1], v[0:1], v[0:1], v[8:9]
	s_nop 0
	v_pk_add_f32 v[0:1], v[0:1], v[0:1] op_sel:[0,1] op_sel_hi:[1,0]
	s_nop 0
	v_pk_add_f32 v[0:1], v[4:5], v[0:1]
	s_waitcnt vmcnt(0)
	v_lshlrev_b32_e32 v4, 16, v2
	v_and_b32_e32 v5, 0xffff0000, v2
	v_lshlrev_b32_e32 v2, 16, v3
	v_and_b32_e32 v3, 0xffff0000, v3
	v_pk_add_f32 v[4:5], v[44:45], v[4:5]
	v_pk_add_f32 v[2:3], v[46:47], v[2:3]
	v_mov_b32_e32 v8, v5
	v_mov_b32_e32 v9, v3
	v_mov_b32_e32 v6, v4
	v_mov_b32_e32 v7, v2
	v_pk_mul_f32 v[8:9], v[8:9], v[8:9]
	v_cvt_pk_bf16_f32 v4, v4, v5
	v_pk_fma_f32 v[6:7], v[6:7], v[6:7], v[8:9]
	v_cvt_pk_bf16_f32 v5, v2, v3
	v_pk_add_f32 v[6:7], v[6:7], v[6:7] op_sel:[0,1] op_sel_hi:[1,0]
	global_store_dwordx2 v[94:95], v[4:5], off offset:112
	v_pk_add_f32 v[0:1], v[0:1], v[6:7]
	s_waitcnt lgkmcnt(0)
	s_nop 0
	v_mov_b32_e32 v1, v0
	s_nop 1
	v_permlane32_swap_b32_e32 v0, v1
	v_add_f32_e32 v0, v0, v1
	v_fmamk_f32 v0, v0, 0x3c800000, v237
	v_rsq_f32_e32 v4, v0
	v_mad_i64_i32 v[0:1], s[2:3], v88, s6, v[96:97]
	v_lshl_add_u64 v[0:1], v[0:1], 0, v[90:91]
	v_lshl_add_u64 v[0:1], v[0:1], 0, v[100:101]
	v_lshl_add_u64 v[8:9], v[0:1], 0, s[48:49]
	v_add_co_u32_e32 v0, vcc, s5, v0
	global_load_dwordx2 v[10:11], v[48:49], off offset:1536
	s_nop 0
	v_addc_co_u32_e32 v1, vcc, 0, v1, vcc
	global_load_dwordx2 v[12:13], v[0:1], off
	s_add_u32 s2, s12, s0
	s_addc_u32 s3, s13, s1
	v_lshl_add_u64 v[0:1], v[98:99], 2, s[2:3]
	v_lshl_add_u64 v[6:7], v[0:1], 0, s[30:31]
	v_add_co_u32_e32 v0, vcc, s7, v0
	v_readlane_b32 s48, v254, 11
	s_nop 0
	v_addc_co_u32_e32 v1, vcc, 0, v1, vcc
	global_load_dwordx4 v[0:3], v[0:1], off offset:2048
	v_readlane_b32 s49, v254, 12
	s_waitcnt vmcnt(2)
	v_lshlrev_b32_e32 v18, 16, v10
	v_and_b32_e32 v19, 0xffff0000, v10
	v_lshlrev_b32_e32 v10, 16, v11
	s_waitcnt vmcnt(1)
	v_lshlrev_b32_e32 v14, 16, v12
	v_mul_f32_e32 v5, 0xbfb8aa3b, v14
	v_exp_f32_e32 v5, v5
	v_and_b32_e32 v15, 0xffff0000, v12
	v_lshlrev_b32_e32 v12, 16, v13
	v_and_b32_e32 v13, 0xffff0000, v13
	v_add_f32_e32 v5, 1.0, v5
	v_rcp_f32_e32 v16, v5
	v_mul_f32_e32 v5, 0xbfb8aa3b, v15
	v_exp_f32_e32 v5, v5
	v_and_b32_e32 v11, 0xffff0000, v11
	v_add_f32_e32 v5, 1.0, v5
	v_rcp_f32_e32 v17, v5
	v_pk_mul_f32 v[18:19], v[4:5], v[18:19] op_sel_hi:[0,1]
	s_waitcnt vmcnt(0)
	v_pk_mul_f32 v[0:1], v[0:1], v[18:19]
	v_pk_mul_f32 v[10:11], v[4:5], v[10:11] op_sel_hi:[0,1]
	v_pk_mul_f32 v[14:15], v[16:17], v[14:15]
	v_pk_mul_f32 v[2:3], v[2:3], v[10:11]
	v_pk_mul_f32 v[0:1], v[0:1], v[14:15]
	s_nop 0
	v_cvt_pk_bf16_f32 v0, v0, v1
	v_mul_f32_e32 v1, 0xbfb8aa3b, v12
	v_exp_f32_e32 v1, v1
	s_nop 0
	v_add_f32_e32 v1, 1.0, v1
	v_rcp_f32_e32 v14, v1
	v_mul_f32_e32 v1, 0xbfb8aa3b, v13
	v_exp_f32_e32 v1, v1
	s_nop 0
	v_add_f32_e32 v1, 1.0, v1
	v_rcp_f32_e32 v15, v1
	s_nop 0
	v_pk_mul_f32 v[10:11], v[14:15], v[12:13]
	s_nop 0
	v_pk_mul_f32 v[2:3], v[2:3], v[10:11]
	s_nop 0
	v_cvt_pk_bf16_f32 v1, v2, v3
	global_store_dwordx2 v[48:49], v[0:1], off offset:1536
	global_load_dwordx4 v[0:3], v[6:7], off offset:32
	s_nop 0
	global_load_dwordx2 v[10:11], v[8:9], off offset:16
	global_load_dwordx2 v[12:13], v[94:95], off offset:16
	s_waitcnt vmcnt(1)
	v_lshlrev_b32_e32 v14, 16, v10
	v_mul_f32_e32 v5, 0xbfb8aa3b, v14
	v_exp_f32_e32 v5, v5
	v_and_b32_e32 v15, 0xffff0000, v10
	s_waitcnt vmcnt(0)
	v_lshlrev_b32_e32 v18, 16, v12
	v_and_b32_e32 v19, 0xffff0000, v12
	v_add_f32_e32 v5, 1.0, v5
	v_rcp_f32_e32 v16, v5
	v_mul_f32_e32 v5, 0xbfb8aa3b, v15
	v_exp_f32_e32 v5, v5
	v_lshlrev_b32_e32 v10, 16, v11
	v_and_b32_e32 v11, 0xffff0000, v11
	v_lshlrev_b32_e32 v12, 16, v13
	v_add_f32_e32 v5, 1.0, v5
	v_rcp_f32_e32 v17, v5
	v_pk_mul_f32 v[18:19], v[4:5], v[18:19] op_sel_hi:[0,1]
	v_pk_mul_f32 v[0:1], v[0:1], v[18:19]
	v_and_b32_e32 v13, 0xffff0000, v13
	v_pk_mul_f32 v[14:15], v[16:17], v[14:15]
	v_pk_mul_f32 v[12:13], v[4:5], v[12:13] op_sel_hi:[0,1]
	v_pk_mul_f32 v[0:1], v[0:1], v[14:15]
	v_pk_mul_f32 v[2:3], v[2:3], v[12:13]
	v_cvt_pk_bf16_f32 v0, v0, v1
	v_mul_f32_e32 v1, 0xbfb8aa3b, v10
	v_exp_f32_e32 v1, v1
	s_nop 0
	v_add_f32_e32 v1, 1.0, v1
	v_rcp_f32_e32 v14, v1
	v_mul_f32_e32 v1, 0xbfb8aa3b, v11
	v_exp_f32_e32 v1, v1
	s_nop 0
	v_add_f32_e32 v1, 1.0, v1
	v_rcp_f32_e32 v15, v1
	s_nop 0
	v_pk_mul_f32 v[10:11], v[14:15], v[10:11]
	s_nop 0
	v_pk_mul_f32 v[2:3], v[2:3], v[10:11]
	s_nop 0
	v_cvt_pk_bf16_f32 v1, v2, v3
	global_store_dwordx2 v[94:95], v[0:1], off offset:16
	global_load_dwordx4 v[0:3], v[6:7], off offset:64
	s_nop 0
	global_load_dwordx2 v[10:11], v[8:9], off offset:32
	global_load_dwordx2 v[12:13], v[94:95], off offset:32
	s_waitcnt vmcnt(1)
	v_lshlrev_b32_e32 v14, 16, v10
	v_mul_f32_e32 v5, 0xbfb8aa3b, v14
	v_exp_f32_e32 v5, v5
	v_and_b32_e32 v15, 0xffff0000, v10
	s_waitcnt vmcnt(0)
	v_lshlrev_b32_e32 v18, 16, v12
	v_and_b32_e32 v19, 0xffff0000, v12
	v_add_f32_e32 v5, 1.0, v5
	v_rcp_f32_e32 v16, v5
	v_mul_f32_e32 v5, 0xbfb8aa3b, v15
	v_exp_f32_e32 v5, v5
	v_lshlrev_b32_e32 v10, 16, v11
	v_and_b32_e32 v11, 0xffff0000, v11
	v_lshlrev_b32_e32 v12, 16, v13
	v_add_f32_e32 v5, 1.0, v5
	v_rcp_f32_e32 v17, v5
	v_pk_mul_f32 v[18:19], v[4:5], v[18:19] op_sel_hi:[0,1]
	v_pk_mul_f32 v[0:1], v[0:1], v[18:19]
	v_and_b32_e32 v13, 0xffff0000, v13
	v_pk_mul_f32 v[14:15], v[16:17], v[14:15]
	v_pk_mul_f32 v[12:13], v[4:5], v[12:13] op_sel_hi:[0,1]
	v_pk_mul_f32 v[0:1], v[0:1], v[14:15]
	v_pk_mul_f32 v[2:3], v[2:3], v[12:13]
	v_cvt_pk_bf16_f32 v0, v0, v1
	v_mul_f32_e32 v1, 0xbfb8aa3b, v10
	v_exp_f32_e32 v1, v1
	s_nop 0
	v_add_f32_e32 v1, 1.0, v1
	v_rcp_f32_e32 v14, v1
	v_mul_f32_e32 v1, 0xbfb8aa3b, v11
	v_exp_f32_e32 v1, v1
	s_nop 0
	v_add_f32_e32 v1, 1.0, v1
	v_rcp_f32_e32 v15, v1
	s_nop 0
	v_pk_mul_f32 v[10:11], v[14:15], v[10:11]
	s_nop 0
	v_pk_mul_f32 v[2:3], v[2:3], v[10:11]
	s_nop 0
	v_cvt_pk_bf16_f32 v1, v2, v3
	global_store_dwordx2 v[94:95], v[0:1], off offset:32
	global_load_dwordx4 v[0:3], v[6:7], off offset:96
	s_nop 0
	global_load_dwordx2 v[10:11], v[8:9], off offset:48
	global_load_dwordx2 v[12:13], v[94:95], off offset:48
	s_waitcnt vmcnt(1)
	v_lshlrev_b32_e32 v14, 16, v10
	v_mul_f32_e32 v5, 0xbfb8aa3b, v14
	v_exp_f32_e32 v5, v5
	v_and_b32_e32 v15, 0xffff0000, v10
	s_waitcnt vmcnt(0)
	v_lshlrev_b32_e32 v18, 16, v12
	v_and_b32_e32 v19, 0xffff0000, v12
	v_add_f32_e32 v5, 1.0, v5
	v_rcp_f32_e32 v16, v5
	v_mul_f32_e32 v5, 0xbfb8aa3b, v15
	v_exp_f32_e32 v5, v5
	v_lshlrev_b32_e32 v10, 16, v11
	v_and_b32_e32 v11, 0xffff0000, v11
	v_lshlrev_b32_e32 v12, 16, v13
	v_add_f32_e32 v5, 1.0, v5
	v_rcp_f32_e32 v17, v5
	v_pk_mul_f32 v[18:19], v[4:5], v[18:19] op_sel_hi:[0,1]
	v_pk_mul_f32 v[0:1], v[0:1], v[18:19]
	v_and_b32_e32 v13, 0xffff0000, v13
	v_pk_mul_f32 v[14:15], v[16:17], v[14:15]
	v_pk_mul_f32 v[12:13], v[4:5], v[12:13] op_sel_hi:[0,1]
	v_pk_mul_f32 v[0:1], v[0:1], v[14:15]
	v_pk_mul_f32 v[2:3], v[2:3], v[12:13]
	v_cvt_pk_bf16_f32 v0, v0, v1
	v_mul_f32_e32 v1, 0xbfb8aa3b, v10
	v_exp_f32_e32 v1, v1
	s_nop 0
	v_add_f32_e32 v1, 1.0, v1
	v_rcp_f32_e32 v14, v1
	v_mul_f32_e32 v1, 0xbfb8aa3b, v11
	v_exp_f32_e32 v1, v1
	s_nop 0
	v_add_f32_e32 v1, 1.0, v1
	v_rcp_f32_e32 v15, v1
	s_nop 0
	v_pk_mul_f32 v[10:11], v[14:15], v[10:11]
	s_nop 0
	v_pk_mul_f32 v[2:3], v[2:3], v[10:11]
	s_nop 0
	v_cvt_pk_bf16_f32 v1, v2, v3
	global_store_dwordx2 v[94:95], v[0:1], off offset:48
	global_load_dwordx2 v[10:11], v[94:95], off offset:64
	global_load_dwordx2 v[12:13], v[8:9], off offset:64
	global_load_dwordx4 v[0:3], v[6:7], off offset:128
	s_waitcnt vmcnt(2)
	v_lshlrev_b32_e32 v18, 16, v10
	s_waitcnt vmcnt(1)
	v_lshlrev_b32_e32 v14, 16, v12
	v_mul_f32_e32 v5, 0xbfb8aa3b, v14
	v_exp_f32_e32 v5, v5
	v_and_b32_e32 v15, 0xffff0000, v12
	v_and_b32_e32 v19, 0xffff0000, v10
	v_lshlrev_b32_e32 v12, 16, v13
	v_add_f32_e32 v5, 1.0, v5
	v_rcp_f32_e32 v16, v5
	v_mul_f32_e32 v5, 0xbfb8aa3b, v15
	v_exp_f32_e32 v5, v5
	v_and_b32_e32 v13, 0xffff0000, v13
	v_lshlrev_b32_e32 v10, 16, v11
	v_and_b32_e32 v11, 0xffff0000, v11
	v_add_f32_e32 v5, 1.0, v5
	v_rcp_f32_e32 v17, v5
	v_pk_mul_f32 v[18:19], v[4:5], v[18:19] op_sel_hi:[0,1]
	s_waitcnt vmcnt(0)
	v_pk_mul_f32 v[0:1], v[0:1], v[18:19]
	v_pk_mul_f32 v[10:11], v[4:5], v[10:11] op_sel_hi:[0,1]
	v_pk_mul_f32 v[14:15], v[16:17], v[14:15]
	v_pk_mul_f32 v[2:3], v[2:3], v[10:11]
	v_pk_mul_f32 v[0:1], v[0:1], v[14:15]
	s_nop 0
	v_cvt_pk_bf16_f32 v0, v0, v1
	v_mul_f32_e32 v1, 0xbfb8aa3b, v12
	v_exp_f32_e32 v1, v1
	s_nop 0
	v_add_f32_e32 v1, 1.0, v1
	v_rcp_f32_e32 v14, v1
	v_mul_f32_e32 v1, 0xbfb8aa3b, v13
	v_exp_f32_e32 v1, v1
	s_nop 0
	v_add_f32_e32 v1, 1.0, v1
	v_rcp_f32_e32 v15, v1
	s_nop 0
	v_pk_mul_f32 v[10:11], v[14:15], v[12:13]
	s_nop 0
	v_pk_mul_f32 v[2:3], v[2:3], v[10:11]
	s_nop 0
	v_cvt_pk_bf16_f32 v1, v2, v3
	global_store_dwordx2 v[94:95], v[0:1], off offset:64
	global_load_dwordx2 v[10:11], v[94:95], off offset:80
	global_load_dwordx2 v[12:13], v[8:9], off offset:80
	s_nop 0
	global_load_dwordx4 v[0:3], v[6:7], off offset:160
	s_waitcnt vmcnt(2)
	v_lshlrev_b32_e32 v18, 16, v10
	s_waitcnt vmcnt(1)
	v_lshlrev_b32_e32 v14, 16, v12
	v_mul_f32_e32 v5, 0xbfb8aa3b, v14
	v_exp_f32_e32 v5, v5
	v_and_b32_e32 v15, 0xffff0000, v12
	v_and_b32_e32 v19, 0xffff0000, v10
	v_lshlrev_b32_e32 v12, 16, v13
	v_add_f32_e32 v5, 1.0, v5
	v_rcp_f32_e32 v16, v5
	v_mul_f32_e32 v5, 0xbfb8aa3b, v15
	v_exp_f32_e32 v5, v5
	v_and_b32_e32 v13, 0xffff0000, v13
	v_lshlrev_b32_e32 v10, 16, v11
	v_and_b32_e32 v11, 0xffff0000, v11
	v_add_f32_e32 v5, 1.0, v5
	v_rcp_f32_e32 v17, v5
	v_pk_mul_f32 v[18:19], v[4:5], v[18:19] op_sel_hi:[0,1]
	s_waitcnt vmcnt(0)
	v_pk_mul_f32 v[0:1], v[0:1], v[18:19]
	v_pk_mul_f32 v[10:11], v[4:5], v[10:11] op_sel_hi:[0,1]
	v_pk_mul_f32 v[14:15], v[16:17], v[14:15]
	v_pk_mul_f32 v[2:3], v[2:3], v[10:11]
	v_pk_mul_f32 v[0:1], v[0:1], v[14:15]
	s_nop 0
	v_cvt_pk_bf16_f32 v0, v0, v1
	v_mul_f32_e32 v1, 0xbfb8aa3b, v12
	v_exp_f32_e32 v1, v1
	s_nop 0
	v_add_f32_e32 v1, 1.0, v1
	v_rcp_f32_e32 v14, v1
	v_mul_f32_e32 v1, 0xbfb8aa3b, v13
	v_exp_f32_e32 v1, v1
	s_nop 0
	v_add_f32_e32 v1, 1.0, v1
	v_rcp_f32_e32 v15, v1
	s_nop 0
	v_pk_mul_f32 v[10:11], v[14:15], v[12:13]
	s_nop 0
	v_pk_mul_f32 v[2:3], v[2:3], v[10:11]
	s_nop 0
	v_cvt_pk_bf16_f32 v1, v2, v3
	global_store_dwordx2 v[94:95], v[0:1], off offset:80
	global_load_dwordx2 v[10:11], v[94:95], off offset:96
	global_load_dwordx2 v[12:13], v[8:9], off offset:96
	s_nop 0
	global_load_dwordx4 v[0:3], v[6:7], off offset:192
	s_waitcnt vmcnt(2)
	v_lshlrev_b32_e32 v18, 16, v10
	s_waitcnt vmcnt(1)
	v_lshlrev_b32_e32 v14, 16, v12
	v_mul_f32_e32 v5, 0xbfb8aa3b, v14
	v_exp_f32_e32 v5, v5
	v_and_b32_e32 v15, 0xffff0000, v12
	v_and_b32_e32 v19, 0xffff0000, v10
	v_lshlrev_b32_e32 v12, 16, v13
	v_add_f32_e32 v5, 1.0, v5
	v_rcp_f32_e32 v16, v5
	v_mul_f32_e32 v5, 0xbfb8aa3b, v15
	v_exp_f32_e32 v5, v5
	v_and_b32_e32 v13, 0xffff0000, v13
	v_lshlrev_b32_e32 v10, 16, v11
	v_and_b32_e32 v11, 0xffff0000, v11
	v_add_f32_e32 v5, 1.0, v5
	v_rcp_f32_e32 v17, v5
	v_pk_mul_f32 v[18:19], v[4:5], v[18:19] op_sel_hi:[0,1]
	s_waitcnt vmcnt(0)
	v_pk_mul_f32 v[0:1], v[0:1], v[18:19]
	v_pk_mul_f32 v[10:11], v[4:5], v[10:11] op_sel_hi:[0,1]
	v_pk_mul_f32 v[14:15], v[16:17], v[14:15]
	v_pk_mul_f32 v[2:3], v[2:3], v[10:11]
	v_pk_mul_f32 v[0:1], v[0:1], v[14:15]
	s_nop 0
	v_cvt_pk_bf16_f32 v0, v0, v1
	v_mul_f32_e32 v1, 0xbfb8aa3b, v12
	v_exp_f32_e32 v1, v1
	s_nop 0
	v_add_f32_e32 v1, 1.0, v1
	v_rcp_f32_e32 v14, v1
	v_mul_f32_e32 v1, 0xbfb8aa3b, v13
	v_exp_f32_e32 v1, v1
	s_nop 0
	v_add_f32_e32 v1, 1.0, v1
	v_rcp_f32_e32 v15, v1
	s_nop 0
	v_pk_mul_f32 v[10:11], v[14:15], v[12:13]
	s_nop 0
	v_pk_mul_f32 v[2:3], v[2:3], v[10:11]
	s_nop 0
	v_cvt_pk_bf16_f32 v1, v2, v3
	global_store_dwordx2 v[94:95], v[0:1], off offset:96
	global_load_dwordx2 v[0:1], v[94:95], off offset:112
	s_nop 0
	global_load_dwordx2 v[2:3], v[8:9], off offset:112
	s_nop 0
	global_load_dwordx4 v[6:9], v[6:7], off offset:224
	s_waitcnt vmcnt(2)
	v_lshlrev_b32_e32 v14, 16, v0
	s_waitcnt vmcnt(1)
	v_lshlrev_b32_e32 v10, 16, v2
	v_mul_f32_e32 v5, 0xbfb8aa3b, v10
	v_exp_f32_e32 v5, v5
	v_and_b32_e32 v11, 0xffff0000, v2
	v_lshlrev_b32_e32 v2, 16, v3
	v_and_b32_e32 v15, 0xffff0000, v0
	v_add_f32_e32 v5, 1.0, v5
	v_rcp_f32_e32 v12, v5
	v_mul_f32_e32 v5, 0xbfb8aa3b, v11
	v_exp_f32_e32 v5, v5
	v_and_b32_e32 v3, 0xffff0000, v3
	v_add_f32_e32 v5, 1.0, v5
	v_rcp_f32_e32 v13, v5
	v_pk_mul_f32 v[14:15], v[4:5], v[14:15] op_sel_hi:[0,1]
	v_mul_f32_e32 v5, 0xbfb8aa3b, v2
	v_exp_f32_e32 v5, v5
	s_waitcnt vmcnt(0)
	v_pk_mul_f32 v[6:7], v[6:7], v[14:15]
	v_pk_mul_f32 v[10:11], v[12:13], v[10:11]
	v_add_f32_e32 v5, 1.0, v5
	v_pk_mul_f32 v[6:7], v[6:7], v[10:11]
	v_lshlrev_b32_e32 v10, 16, v1
	v_cvt_pk_bf16_f32 v0, v6, v7
	v_rcp_f32_e32 v6, v5
	v_mul_f32_e32 v5, 0xbfb8aa3b, v3
	v_exp_f32_e32 v5, v5
	v_and_b32_e32 v11, 0xffff0000, v1
	v_add_f32_e32 v5, 1.0, v5
	v_rcp_f32_e32 v7, v5
	v_pk_mul_f32 v[4:5], v[4:5], v[10:11] op_sel_hi:[0,1]
	v_pk_mul_f32 v[4:5], v[8:9], v[4:5]
	v_pk_mul_f32 v[2:3], v[6:7], v[2:3]
	s_nop 0
	v_pk_mul_f32 v[2:3], v[4:5], v[2:3]
	s_nop 0
	v_cvt_pk_bf16_f32 v1, v2, v3
	global_store_dwordx2 v[94:95], v[0:1], off offset:112
	s_branch .LBB0_338
